# v034 + inverse priority: s_setprio 1 during the fragment-load blocks, 0 during the MFMA blocks
# baseline (speedup 1.0000x reference)
.LBB0_134:
	s_setprio 1
	s_add_u32 s28, s66, 0xfffc0080
	s_addc_u32 s29, s67, -1
	s_add_i32 s88, 0, 0x10000
	v_add_u32_e32 v152, s88, v191
	ds_read_b128 v[128:131], v152
	ds_read_b128 v[132:135], v152 offset:1024
	ds_read_b128 v[148:151], v152 offset:2048
	ds_read_b128 v[152:155], v152 offset:3072
	s_cmp_eq_u32 vcc_lo, 12
	s_cselect_b32 s71, s5, s29
	s_cselect_b32 s70, s7, s28
	s_cselect_b32 s69, s17, s91
	s_cselect_b32 s68, s19, s85
	v_lshl_add_u64 v[172:173], s[66:67], 0, v[144:145]
	s_add_i32 m0, s73, 0xc000
	ds_read_b128 v[156:159], v192
	ds_read_b128 v[164:167], v192 offset:2048
	ds_read_b128 v[194:197], v192 offset:4096
	ds_read_b128 v[202:205], v192 offset:6144
	ds_read_b128 v[160:163], v192 offset:1024
	ds_read_b128 v[168:171], v192 offset:3072
	ds_read_b128 v[198:201], v192 offset:5120
	ds_read_b128 v[206:209], v192 offset:7168
	global_load_lds_dwordx4 v[172:173], off
	v_lshl_add_u64 v[172:173], s[66:67], 0, v[146:147]
	s_add_i32 m0, s73, 0xe000
	s_nop 0
	global_load_lds_dwordx4 v[172:173], off
	s_waitcnt lgkmcnt(8)
	s_barrier
	s_setprio 0
	s_waitcnt lgkmcnt(7)
	v_mfma_f32_16x16x32_bf16 v[124:127], v[128:131], v[156:159], v[124:127]
	v_mfma_f32_16x16x32_bf16 v[120:123], v[148:151], v[156:159], v[120:123]
	s_waitcnt lgkmcnt(6)
	v_mfma_f32_16x16x32_bf16 v[108:111], v[128:131], v[164:167], v[108:111]
	v_mfma_f32_16x16x32_bf16 v[104:107], v[148:151], v[164:167], v[104:107]
	s_waitcnt lgkmcnt(5)
	v_mfma_f32_16x16x32_bf16 v[92:95], v[128:131], v[194:197], v[92:95]
	v_mfma_f32_16x16x32_bf16 v[88:91], v[148:151], v[194:197], v[88:91]
	s_waitcnt lgkmcnt(4)
	v_mfma_f32_16x16x32_bf16 v[76:79], v[128:131], v[202:205], v[76:79]
	v_mfma_f32_16x16x32_bf16 v[72:75], v[148:151], v[202:205], v[72:75]
	s_waitcnt lgkmcnt(3)
	v_mfma_f32_16x16x32_bf16 v[124:127], v[132:135], v[160:163], v[124:127]
	v_mfma_f32_16x16x32_bf16 v[120:123], v[152:155], v[160:163], v[120:123]
	s_waitcnt lgkmcnt(2)
	v_mfma_f32_16x16x32_bf16 v[108:111], v[132:135], v[168:171], v[108:111]
	v_mfma_f32_16x16x32_bf16 v[104:107], v[152:155], v[168:171], v[104:107]
	s_waitcnt lgkmcnt(1)
	v_mfma_f32_16x16x32_bf16 v[92:95], v[132:135], v[198:201], v[92:95]
	v_mfma_f32_16x16x32_bf16 v[88:91], v[152:155], v[198:201], v[88:91]
	s_waitcnt lgkmcnt(0)
	v_mfma_f32_16x16x32_bf16 v[76:79], v[132:135], v[206:209], v[76:79]
	v_mfma_f32_16x16x32_bf16 v[72:75], v[152:155], v[206:209], v[72:75]
	s_barrier
	s_setprio 1
	s_add_i32 s89, 0, 0x14000
	v_add_u32_e32 v172, s89, v191
	s_add_i32 s28, s88, s72
	ds_read_b128 v[210:213], v172
	ds_read_b128 v[214:217], v172 offset:1024
	ds_read_b128 v[232:235], v172 offset:2048
	ds_read_b128 v[236:239], v172 offset:3072
	v_lshl_add_u64 v[172:173], s[68:69], 0, v[138:139]
	s_mov_b32 m0, s28
	v_lshl_add_u64 v[188:189], s[68:69], 0, v[142:143]
	global_load_lds_dwordx4 v[172:173], off
	s_add_i32 m0, s28, 0x2000
	s_nop 0
	global_load_lds_dwordx4 v[188:189], off
	s_barrier
	s_setprio 0
	s_waitcnt lgkmcnt(3)
	v_mfma_f32_16x16x32_bf16 v[116:119], v[210:213], v[156:159], v[116:119]
	s_waitcnt lgkmcnt(1)
	v_mfma_f32_16x16x32_bf16 v[112:115], v[232:235], v[156:159], v[112:115]
	v_mfma_f32_16x16x32_bf16 v[100:103], v[210:213], v[164:167], v[100:103]
	v_mfma_f32_16x16x32_bf16 v[96:99], v[232:235], v[164:167], v[96:99]
	v_mfma_f32_16x16x32_bf16 v[84:87], v[210:213], v[194:197], v[84:87]
	v_mfma_f32_16x16x32_bf16 v[80:83], v[232:235], v[194:197], v[80:83]
	v_mfma_f32_16x16x32_bf16 v[68:71], v[210:213], v[202:205], v[68:71]
	v_mfma_f32_16x16x32_bf16 v[64:67], v[232:235], v[202:205], v[64:67]
	v_mfma_f32_16x16x32_bf16 v[116:119], v[214:217], v[160:163], v[116:119]
	s_waitcnt lgkmcnt(0)
	v_mfma_f32_16x16x32_bf16 v[112:115], v[236:239], v[160:163], v[112:115]
	v_mfma_f32_16x16x32_bf16 v[100:103], v[214:217], v[168:171], v[100:103]
	v_mfma_f32_16x16x32_bf16 v[96:99], v[236:239], v[168:171], v[96:99]
	v_mfma_f32_16x16x32_bf16 v[84:87], v[214:217], v[198:201], v[84:87]
	v_mfma_f32_16x16x32_bf16 v[80:83], v[236:239], v[198:201], v[80:83]
	v_mfma_f32_16x16x32_bf16 v[68:71], v[214:217], v[206:209], v[68:71]
	v_mfma_f32_16x16x32_bf16 v[64:67], v[236:239], v[206:209], v[64:67]
	s_mov_b32 m0, s73
	v_lshl_add_u64 v[240:241], s[70:71], 0, v[136:137]
	s_barrier
	s_setprio 1
	ds_read_b128 v[156:159], v192 offset:16384
	ds_read_b128 v[164:167], v192 offset:18432
	ds_read_b128 v[194:197], v192 offset:20480
	ds_read_b128 v[202:205], v192 offset:22528
	ds_read_b128 v[160:163], v192 offset:17408
	ds_read_b128 v[168:171], v192 offset:19456
	ds_read_b128 v[198:201], v192 offset:21504
	ds_read_b128 v[206:209], v192 offset:23552
	global_load_lds_dwordx4 v[240:241], off
	v_lshl_add_u64 v[242:243], s[70:71], 0, v[140:141]
	s_mov_b32 m0, s74
	s_nop 0
	global_load_lds_dwordx4 v[242:243], off
	s_barrier
	s_setprio 0
	s_waitcnt lgkmcnt(7)
	v_mfma_f32_16x16x32_bf16 v[60:63], v[128:131], v[156:159], v[60:63]
	v_mfma_f32_16x16x32_bf16 v[56:59], v[148:151], v[156:159], v[56:59]
	s_waitcnt lgkmcnt(6)
	v_mfma_f32_16x16x32_bf16 v[44:47], v[128:131], v[164:167], v[44:47]
	v_mfma_f32_16x16x32_bf16 v[40:43], v[148:151], v[164:167], v[40:43]
	s_waitcnt lgkmcnt(5)
	v_mfma_f32_16x16x32_bf16 v[28:31], v[128:131], v[194:197], v[28:31]
	v_mfma_f32_16x16x32_bf16 v[24:27], v[148:151], v[194:197], v[24:27]
	s_waitcnt lgkmcnt(4)
	v_mfma_f32_16x16x32_bf16 v[12:15], v[128:131], v[202:205], v[12:15]
	v_mfma_f32_16x16x32_bf16 v[8:11], v[148:151], v[202:205], v[8:11]
	s_waitcnt lgkmcnt(3)
	v_mfma_f32_16x16x32_bf16 v[60:63], v[132:135], v[160:163], v[60:63]
	v_mfma_f32_16x16x32_bf16 v[56:59], v[152:155], v[160:163], v[56:59]
	s_waitcnt lgkmcnt(2)
	v_mfma_f32_16x16x32_bf16 v[44:47], v[132:135], v[168:171], v[44:47]
	v_mfma_f32_16x16x32_bf16 v[40:43], v[152:155], v[168:171], v[40:43]
	s_waitcnt lgkmcnt(1)
	v_mfma_f32_16x16x32_bf16 v[28:31], v[132:135], v[198:201], v[28:31]
	v_mfma_f32_16x16x32_bf16 v[24:27], v[152:155], v[198:201], v[24:27]
	s_waitcnt lgkmcnt(0)
	v_mfma_f32_16x16x32_bf16 v[12:15], v[132:135], v[206:209], v[12:15]
	v_mfma_f32_16x16x32_bf16 v[8:11], v[152:155], v[206:209], v[8:11]
	s_barrier
	s_setprio 1
	s_add_u32 s28, s68, 0x40000
	s_addc_u32 s29, s69, 0
	s_add_i32 s88, s89, s72
	v_lshl_add_u64 v[128:129], s[28:29], 0, v[138:139]
	s_mov_b32 m0, s88
	s_nop 0
	global_load_lds_dwordx4 v[128:129], off
	v_lshl_add_u64 v[128:129], s[28:29], 0, v[142:143]
	s_add_i32 m0, s88, 0x2000
	s_nop 0
	global_load_lds_dwordx4 v[128:129], off
	s_waitcnt vmcnt(6)
	s_barrier
	s_setprio 0
	v_mfma_f32_16x16x32_bf16 v[52:55], v[210:213], v[156:159], v[52:55]
	v_mfma_f32_16x16x32_bf16 v[48:51], v[232:235], v[156:159], v[48:51]
	v_mfma_f32_16x16x32_bf16 v[36:39], v[210:213], v[164:167], v[36:39]
	v_mfma_f32_16x16x32_bf16 v[32:35], v[232:235], v[164:167], v[32:35]
	v_mfma_f32_16x16x32_bf16 v[20:23], v[210:213], v[194:197], v[20:23]
	v_mfma_f32_16x16x32_bf16 v[16:19], v[232:235], v[194:197], v[16:19]
	v_mfma_f32_16x16x32_bf16 v[4:7], v[210:213], v[202:205], v[4:7]
	v_mfma_f32_16x16x32_bf16 v[0:3], v[232:235], v[202:205], v[0:3]
	v_mfma_f32_16x16x32_bf16 v[52:55], v[214:217], v[160:163], v[52:55]
	v_mfma_f32_16x16x32_bf16 v[48:51], v[236:239], v[160:163], v[48:51]
	v_mfma_f32_16x16x32_bf16 v[36:39], v[214:217], v[168:171], v[36:39]
	v_mfma_f32_16x16x32_bf16 v[32:35], v[236:239], v[168:171], v[32:35]
	v_mfma_f32_16x16x32_bf16 v[20:23], v[214:217], v[198:201], v[20:23]
	v_mfma_f32_16x16x32_bf16 v[16:19], v[236:239], v[198:201], v[16:19]
	v_mfma_f32_16x16x32_bf16 v[4:7], v[214:217], v[206:209], v[4:7]
	v_mfma_f32_16x16x32_bf16 v[0:3], v[236:239], v[206:209], v[0:3]
	s_add_i32 s88, 0, 0x18000
	v_add_u32_e32 v152, s88, v191
	s_barrier
	s_setprio 1
	ds_read_b128 v[128:131], v152
	ds_read_b128 v[132:135], v152 offset:1024
	ds_read_b128 v[148:151], v152 offset:2048
	ds_read_b128 v[152:155], v152 offset:3072
	s_add_u32 s28, s70, 0x40000
	s_addc_u32 s29, s71, 0
	s_mov_b32 m0, s75
	v_lshl_add_u64 v[210:211], s[28:29], 0, v[136:137]
	ds_read_b128 v[156:159], v192 offset:32768
	ds_read_b128 v[164:167], v192 offset:34816
	ds_read_b128 v[194:197], v192 offset:36864
	ds_read_b128 v[202:205], v192 offset:38912
	ds_read_b128 v[160:163], v192 offset:33792
	ds_read_b128 v[168:171], v192 offset:35840
	ds_read_b128 v[198:201], v192 offset:37888
	ds_read_b128 v[206:209], v192 offset:39936
	global_load_lds_dwordx4 v[210:211], off
	v_lshl_add_u64 v[210:211], s[28:29], 0, v[140:141]
	s_mov_b32 m0, s76
	s_nop 0
	global_load_lds_dwordx4 v[210:211], off
	s_waitcnt lgkmcnt(8)
	s_barrier
	s_setprio 0
	s_waitcnt lgkmcnt(7)
	v_mfma_f32_16x16x32_bf16 v[124:127], v[128:131], v[156:159], v[124:127]
	v_mfma_f32_16x16x32_bf16 v[120:123], v[148:151], v[156:159], v[120:123]
	s_waitcnt lgkmcnt(6)
	v_mfma_f32_16x16x32_bf16 v[108:111], v[128:131], v[164:167], v[108:111]
	v_mfma_f32_16x16x32_bf16 v[104:107], v[148:151], v[164:167], v[104:107]
	s_waitcnt lgkmcnt(5)
	v_mfma_f32_16x16x32_bf16 v[92:95], v[128:131], v[194:197], v[92:95]
	v_mfma_f32_16x16x32_bf16 v[88:91], v[148:151], v[194:197], v[88:91]
	s_waitcnt lgkmcnt(4)
	v_mfma_f32_16x16x32_bf16 v[76:79], v[128:131], v[202:205], v[76:79]
	v_mfma_f32_16x16x32_bf16 v[72:75], v[148:151], v[202:205], v[72:75]
	s_waitcnt lgkmcnt(3)
	v_mfma_f32_16x16x32_bf16 v[124:127], v[132:135], v[160:163], v[124:127]
	v_mfma_f32_16x16x32_bf16 v[120:123], v[152:155], v[160:163], v[120:123]
	s_waitcnt lgkmcnt(2)
	v_mfma_f32_16x16x32_bf16 v[108:111], v[132:135], v[168:171], v[108:111]
	v_mfma_f32_16x16x32_bf16 v[104:107], v[152:155], v[168:171], v[104:107]
	s_waitcnt lgkmcnt(1)
	v_mfma_f32_16x16x32_bf16 v[92:95], v[132:135], v[198:201], v[92:95]
	v_mfma_f32_16x16x32_bf16 v[88:91], v[152:155], v[198:201], v[88:91]
	s_waitcnt lgkmcnt(0)
	v_mfma_f32_16x16x32_bf16 v[76:79], v[132:135], v[206:209], v[76:79]
	v_mfma_f32_16x16x32_bf16 v[72:75], v[152:155], v[206:209], v[72:75]
	s_barrier
	s_setprio 1
	s_add_i32 s70, 0, 0x1c000
	s_add_i32 s28, s88, s72
	v_add_u32_e32 v174, s70, v191
	v_lshl_add_u64 v[172:173], v[172:173], 0, s[40:41]
	s_mov_b32 m0, s28
	ds_read_b128 v[210:213], v174
	ds_read_b128 v[214:217], v174 offset:1024
	ds_read_b128 v[232:235], v174 offset:2048
	ds_read_b128 v[236:239], v174 offset:3072
	global_load_lds_dwordx4 v[172:173], off
	v_lshl_add_u64 v[172:173], v[188:189], 0, s[40:41]
	s_add_i32 m0, s28, 0x2000
	s_nop 0
	global_load_lds_dwordx4 v[172:173], off
	s_barrier
	s_setprio 0
	s_waitcnt lgkmcnt(3)
	v_mfma_f32_16x16x32_bf16 v[116:119], v[210:213], v[156:159], v[116:119]
	s_waitcnt lgkmcnt(1)
	v_mfma_f32_16x16x32_bf16 v[112:115], v[232:235], v[156:159], v[112:115]
	v_mfma_f32_16x16x32_bf16 v[100:103], v[210:213], v[164:167], v[100:103]
	v_mfma_f32_16x16x32_bf16 v[96:99], v[232:235], v[164:167], v[96:99]
	v_mfma_f32_16x16x32_bf16 v[84:87], v[210:213], v[194:197], v[84:87]
	v_mfma_f32_16x16x32_bf16 v[80:83], v[232:235], v[194:197], v[80:83]
	v_mfma_f32_16x16x32_bf16 v[68:71], v[210:213], v[202:205], v[68:71]
	v_mfma_f32_16x16x32_bf16 v[64:67], v[232:235], v[202:205], v[64:67]
	v_mfma_f32_16x16x32_bf16 v[116:119], v[214:217], v[160:163], v[116:119]
	s_waitcnt lgkmcnt(0)
	v_mfma_f32_16x16x32_bf16 v[112:115], v[236:239], v[160:163], v[112:115]
	v_mfma_f32_16x16x32_bf16 v[100:103], v[214:217], v[168:171], v[100:103]
	v_mfma_f32_16x16x32_bf16 v[96:99], v[236:239], v[168:171], v[96:99]
	v_mfma_f32_16x16x32_bf16 v[84:87], v[214:217], v[198:201], v[84:87]
	v_mfma_f32_16x16x32_bf16 v[80:83], v[236:239], v[198:201], v[80:83]
	v_mfma_f32_16x16x32_bf16 v[68:71], v[214:217], v[206:209], v[68:71]
	v_mfma_f32_16x16x32_bf16 v[64:67], v[236:239], v[206:209], v[64:67]
	s_mov_b32 m0, s79
	v_lshl_add_u64 v[172:173], v[240:241], 0, s[40:41]
	s_barrier
	s_setprio 1
	ds_read_b128 v[156:159], v192 offset:49152
	ds_read_b128 v[164:167], v192 offset:51200
	ds_read_b128 v[194:197], v192 offset:53248
	ds_read_b128 v[202:205], v192 offset:55296
	ds_read_b128 v[160:163], v192 offset:50176
	ds_read_b128 v[168:171], v192 offset:52224
	ds_read_b128 v[198:201], v192 offset:54272
	ds_read_b128 v[206:209], v192 offset:56320
	global_load_lds_dwordx4 v[172:173], off
	v_lshl_add_u64 v[172:173], v[242:243], 0, s[40:41]
	s_mov_b32 m0, s80
	s_nop 0
	global_load_lds_dwordx4 v[172:173], off
	s_barrier
	s_setprio 0
	s_waitcnt lgkmcnt(7)
	v_mfma_f32_16x16x32_bf16 v[60:63], v[128:131], v[156:159], v[60:63]
	v_mfma_f32_16x16x32_bf16 v[56:59], v[148:151], v[156:159], v[56:59]
	s_waitcnt lgkmcnt(6)
	v_mfma_f32_16x16x32_bf16 v[44:47], v[128:131], v[164:167], v[44:47]
	v_mfma_f32_16x16x32_bf16 v[40:43], v[148:151], v[164:167], v[40:43]
	s_waitcnt lgkmcnt(5)
	v_mfma_f32_16x16x32_bf16 v[28:31], v[128:131], v[194:197], v[28:31]
	v_mfma_f32_16x16x32_bf16 v[24:27], v[148:151], v[194:197], v[24:27]
	s_waitcnt lgkmcnt(4)
	v_mfma_f32_16x16x32_bf16 v[12:15], v[128:131], v[202:205], v[12:15]
	v_mfma_f32_16x16x32_bf16 v[8:11], v[148:151], v[202:205], v[8:11]
	s_waitcnt lgkmcnt(3)
	v_mfma_f32_16x16x32_bf16 v[60:63], v[132:135], v[160:163], v[60:63]
	v_mfma_f32_16x16x32_bf16 v[56:59], v[152:155], v[160:163], v[56:59]
	s_waitcnt lgkmcnt(2)
	v_mfma_f32_16x16x32_bf16 v[44:47], v[132:135], v[168:171], v[44:47]
	v_mfma_f32_16x16x32_bf16 v[40:43], v[152:155], v[168:171], v[40:43]
	s_waitcnt lgkmcnt(1)
	v_mfma_f32_16x16x32_bf16 v[28:31], v[132:135], v[198:201], v[28:31]
	v_mfma_f32_16x16x32_bf16 v[24:27], v[152:155], v[198:201], v[24:27]
	s_waitcnt lgkmcnt(0)
	v_mfma_f32_16x16x32_bf16 v[12:15], v[132:135], v[206:209], v[12:15]
	v_mfma_f32_16x16x32_bf16 v[8:11], v[152:155], v[206:209], v[8:11]
	s_barrier
	s_setprio 1
	s_add_u32 s28, s68, 0x40080
	s_addc_u32 s29, s69, 0
	s_add_i32 s68, s70, s72
	v_lshl_add_u64 v[128:129], s[28:29], 0, v[138:139]
	s_mov_b32 m0, s68
	s_nop 0
	global_load_lds_dwordx4 v[128:129], off
	v_lshl_add_u64 v[128:129], s[28:29], 0, v[142:143]
	s_add_i32 m0, s68, 0x2000
	s_nop 0
	global_load_lds_dwordx4 v[128:129], off
	s_waitcnt vmcnt(6)
	s_barrier
	s_setprio 0
	v_mfma_f32_16x16x32_bf16 v[52:55], v[210:213], v[156:159], v[52:55]
	v_mfma_f32_16x16x32_bf16 v[48:51], v[232:235], v[156:159], v[48:51]
	v_mfma_f32_16x16x32_bf16 v[36:39], v[210:213], v[164:167], v[36:39]
	v_mfma_f32_16x16x32_bf16 v[32:35], v[232:235], v[164:167], v[32:35]
	v_mfma_f32_16x16x32_bf16 v[20:23], v[210:213], v[194:197], v[20:23]
	v_mfma_f32_16x16x32_bf16 v[16:19], v[232:235], v[194:197], v[16:19]
	v_mfma_f32_16x16x32_bf16 v[4:7], v[210:213], v[202:205], v[4:7]
	v_mfma_f32_16x16x32_bf16 v[0:3], v[232:235], v[202:205], v[0:3]
	v_mfma_f32_16x16x32_bf16 v[52:55], v[214:217], v[160:163], v[52:55]
	v_mfma_f32_16x16x32_bf16 v[48:51], v[236:239], v[160:163], v[48:51]
	v_mfma_f32_16x16x32_bf16 v[36:39], v[214:217], v[168:171], v[36:39]
	v_mfma_f32_16x16x32_bf16 v[32:35], v[236:239], v[168:171], v[32:35]
	v_mfma_f32_16x16x32_bf16 v[20:23], v[214:217], v[198:201], v[20:23]
	v_mfma_f32_16x16x32_bf16 v[16:19], v[236:239], v[198:201], v[16:19]
	v_mfma_f32_16x16x32_bf16 v[4:7], v[214:217], v[206:209], v[4:7]
	v_mfma_f32_16x16x32_bf16 v[0:3], v[236:239], v[206:209], v[0:3]
	s_add_i32 vcc_lo, vcc_lo, 2
	s_add_u32 s66, s66, 0x100
	s_addc_u32 s67, s67, 0
	s_add_u32 s85, s85, 0x100
	s_addc_u32 s91, s91, 0
	s_cmp_lt_u32 vcc_lo, 14
	s_barrier
	s_cbranch_scc1 .LBB0_134
	s_lshl_b32 s4, s4, 8
	v_mov_b32_e32 v176, v175
	v_mov_b32_e32 v188, v190
	s_add_i32 s4, s4, s77
	s_cmp_gt_i32 s6, 7
	v_add_u32_e32 v148, s4, v176
	v_lshlrev_b32_e32 v128, 2, v188
	v_ashrrev_i32_e32 v129, 31, v128
	v_ashrrev_i32_e32 v149, 31, v148
	v_lshl_add_u64 v[128:129], v[128:129], 2, s[8:9]
	v_lshlrev_b64 v[130:131], 6, v[148:149]
	v_add_u32_e32 v166, 16, v148
	v_lshl_add_u64 v[130:131], v[128:129], 0, v[130:131]
	v_ashrrev_i32_e32 v167, 31, v166
	global_load_dwordx4 v[160:163], v[130:131], off
	v_lshlrev_b64 v[130:131], 6, v[166:167]
	v_lshl_add_u64 v[130:131], v[128:129], 0, v[130:131]
	global_load_dwordx4 v[168:171], v[130:131], off
	v_add_u32_e32 v164, 32, v148
	v_ashrrev_i32_e32 v165, 31, v164
	v_lshlrev_b64 v[130:131], 6, v[164:165]
	v_add_u32_e32 v158, 48, v148
	v_lshl_add_u64 v[130:131], v[128:129], 0, v[130:131]
	v_ashrrev_i32_e32 v159, 31, v158
	global_load_dwordx4 v[194:197], v[130:131], off
	v_lshlrev_b64 v[130:131], 6, v[158:159]
	v_lshl_add_u64 v[130:131], v[128:129], 0, v[130:131]
	global_load_dwordx4 v[198:201], v[130:131], off
	v_add_u32_e32 v156, 0x80, v148
	v_ashrrev_i32_e32 v157, 31, v156
	v_lshlrev_b64 v[130:131], 6, v[156:157]
	v_add_u32_e32 v154, 0x90, v148
	v_lshl_add_u64 v[130:131], v[128:129], 0, v[130:131]
	v_ashrrev_i32_e32 v155, 31, v154
	global_load_dwordx4 v[202:205], v[130:131], off
	v_lshlrev_b64 v[130:131], 6, v[154:155]
	v_add_u32_e32 v152, 0xa0, v148
	v_lshl_add_u64 v[130:131], v[128:129], 0, v[130:131]
	v_ashrrev_i32_e32 v153, 31, v152
	global_load_dwordx4 v[206:209], v[130:131], off
	v_lshlrev_b64 v[130:131], 6, v[152:153]
	v_add_u32_e32 v150, 0xb0, v148
	v_lshl_add_u64 v[130:131], v[128:129], 0, v[130:131]
	v_ashrrev_i32_e32 v151, 31, v150
	global_load_dwordx4 v[132:135], v[130:131], off
	v_lshlrev_b64 v[130:131], 6, v[150:151]
	v_lshl_add_u64 v[128:129], v[128:129], 0, v[130:131]
	global_load_dwordx4 v[128:131], v[128:129], off
	s_cselect_b64 s[66:67], -1, 0
	s_lshl_b32 s7, s6, 8
	s_add_i32 s7, s81, s7
	s_cmp_lt_i32 s6, 8
	s_mov_b64 s[68:69], -1
	s_waitcnt vmcnt(0)
	v_mov_b32_e32 v172, v161
	v_mov_b32_e32 v173, v162
	v_mov_b32_e32 v161, v163
	v_mov_b32_e32 v162, v169
	v_mov_b32_e32 v163, v170
	v_mov_b32_e32 v169, v171
	v_pk_add_f32 v[160:161], v[172:173], v[160:161]
	v_pk_add_f32 v[162:163], v[162:163], v[168:169]
	v_mov_b32_e32 v169, v160
	v_mov_b32_e32 v168, v162
	v_mov_b32_e32 v160, v163
	v_pk_add_f32 v[160:161], v[168:169], v[160:161]
	ds_bpermute_b32 v163, v219, v161
	ds_bpermute_b32 v162, v219, v160
	s_waitcnt lgkmcnt(0)
	v_pk_add_f32 v[160:161], v[160:161], v[162:163]
	ds_bpermute_b32 v163, v218, v161
	ds_bpermute_b32 v162, v218, v160
	s_waitcnt lgkmcnt(0)
	v_pk_add_f32 v[160:161], v[160:161], v[162:163]
	s_nop 0
	v_pk_fma_f32 v[172:173], v[160:161], s[30:31], v[178:179] op_sel_hi:[1,0,0]
	v_mov_b32_e32 v162, v199
	v_mul_f32_e32 v160, 0x4b800000, v173
	v_cmp_gt_f32_e32 vcc, s86, v173
	v_mov_b32_e32 v163, v200
	v_mov_b32_e32 v199, v201
	v_cndmask_b32_e32 v160, v173, v160, vcc
	v_rsq_f32_e32 v160, v160
	v_pk_add_f32 v[162:163], v[162:163], v[198:199]
	v_cmp_gt_f32_e64 s[4:5], s86, v172
	v_mov_b32_e32 v168, v162
	v_mul_f32_e32 v161, 0x45800000, v160
	v_cndmask_b32_e32 v174, v160, v161, vcc
	v_mov_b32_e32 v160, v195
	v_mov_b32_e32 v161, v196
	v_mov_b32_e32 v195, v197
	v_pk_add_f32 v[160:161], v[160:161], v[194:195]
	s_nop 0
	v_mov_b32_e32 v169, v160
	v_mov_b32_e32 v160, v163
	v_pk_add_f32 v[160:161], v[168:169], v[160:161]
	ds_bpermute_b32 v163, v219, v161
	ds_bpermute_b32 v162, v219, v160
	s_waitcnt lgkmcnt(0)
	v_pk_add_f32 v[168:169], v[160:161], v[162:163]
	v_mov_b32_e32 v160, v203
	v_mov_b32_e32 v161, v204
	v_mov_b32_e32 v203, v205
	v_mov_b32_e32 v162, v207
	v_mov_b32_e32 v163, v208
	v_mov_b32_e32 v207, v209
	v_pk_add_f32 v[160:161], v[160:161], v[202:203]
	v_pk_add_f32 v[162:163], v[162:163], v[206:207]
	v_mov_b32_e32 v195, v160
	v_mov_b32_e32 v194, v162
	v_mov_b32_e32 v160, v163
	v_pk_add_f32 v[160:161], v[194:195], v[160:161]
	v_mov_b32_e32 v194, v133
	v_mov_b32_e32 v195, v134
	v_mov_b32_e32 v133, v135
	v_mov_b32_e32 v134, v129
	v_mov_b32_e32 v135, v130
	v_mov_b32_e32 v129, v131
	v_pk_add_f32 v[132:133], v[194:195], v[132:133]
	v_pk_add_f32 v[128:129], v[134:135], v[128:129]
	v_mov_b32_e32 v131, v132
	v_mov_b32_e32 v130, v128
	v_mov_b32_e32 v132, v129
	v_pk_add_f32 v[128:129], v[130:131], v[132:133]
	ds_bpermute_b32 v163, v219, v161
	ds_bpermute_b32 v162, v219, v160
	ds_bpermute_b32 v131, v219, v129
	ds_bpermute_b32 v130, v219, v128
	ds_bpermute_b32 v171, v218, v169
	ds_bpermute_b32 v170, v218, v168
	s_waitcnt lgkmcnt(4)
	v_pk_add_f32 v[160:161], v[160:161], v[162:163]
	ds_bpermute_b32 v163, v218, v161
	s_waitcnt lgkmcnt(3)
	v_pk_add_f32 v[132:133], v[128:129], v[130:131]
	ds_bpermute_b32 v162, v218, v160
	ds_bpermute_b32 v135, v218, v133
	ds_bpermute_b32 v134, v218, v132
	v_lshlrev_b32_e32 v128, 3, v188
	v_add_u32_e32 v130, s7, v128
	v_lshlrev_b64 v[188:189], 11, v[148:149]
	v_ashrrev_i32_e32 v131, 31, v130
	s_cbranch_scc1 .LBB0_137
	v_mul_f32_e32 v196, v120, v174
	v_mul_f32_e32 v197, v121, v174
	v_mul_f32_e32 v198, v122, v174
	v_mul_f32_e32 v199, v123, v174
	v_mul_f32_e32 v129, v124, v174
	v_mul_f32_e32 v149, v125, v174
	v_mul_f32_e32 v173, v126, v174
	v_mul_f32_e32 v193, v127, v174
	v_cvt_pk_bf16_f32 v194, v129, v149
	v_cvt_pk_bf16_f32 v195, v173, v193
	v_cvt_pk_bf16_f32 v196, v196, v197
	v_cvt_pk_bf16_f32 v197, v198, v199
	v_lshl_add_u64 v[198:199], s[12:13], 0, v[188:189]
	v_lshl_add_u64 v[198:199], v[130:131], 1, v[198:199]
	global_store_dwordx4 v[198:199], v[194:197], off
	s_mov_b64 s[68:69], 0
	v_mul_f32_e32 v129, v116, v174
	v_mul_f32_e32 v196, v112, v174
	v_mul_f32_e32 v197, v113, v174
	v_mul_f32_e32 v149, v117, v174
	v_mul_f32_e32 v173, v118, v174
	v_mul_f32_e32 v193, v119, v174
	v_mul_f32_e32 v200, v114, v174
	v_mul_f32_e32 v201, v115, v174
	v_cvt_pk_bf16_f32 v194, v129, v149
	v_cvt_pk_bf16_f32 v195, v173, v193
	v_cvt_pk_bf16_f32 v196, v196, v197
	v_cvt_pk_bf16_f32 v197, v200, v201
	global_store_dwordx4 v[198:199], v[194:197], off offset:256

.LBB0_413:
	s_setprio 1
	s_add_i32 vcc_lo, s62, 2
	s_add_u32 s4, s18, 0x100
	s_addc_u32 s5, s19, 0
	s_add_i32 s28, 0, 0x10000
	v_add_u32_e32 v140, s28, v164
	ds_read_b128 v[128:131], v140
	ds_read_b128 v[132:135], v140 offset:1024
	ds_read_b128 v[136:139], v140 offset:2048
	ds_read_b128 v[140:143], v140 offset:3072
	s_cmp_eq_u32 s13, s62
	s_cselect_b32 s62, s6, s85
	s_cselect_b32 s65, s17, s5
	s_cselect_b32 s64, s16, s4
	s_cselect_b32 s63, s7, s91
	v_lshl_add_u64 v[174:175], s[18:19], 0, v[150:151]
	s_add_i32 m0, s69, 0xc000
	ds_read_b128 v[154:157], v165
	ds_read_b128 v[166:169], v165 offset:2048
	ds_read_b128 v[188:191], v165 offset:4096
	ds_read_b128 v[196:199], v165 offset:6144
	ds_read_b128 v[158:161], v165 offset:1024
	ds_read_b128 v[170:173], v165 offset:3072
	ds_read_b128 v[192:195], v165 offset:5120
	ds_read_b128 v[200:203], v165 offset:7168
	global_load_lds_dwordx4 v[174:175], off
	v_lshl_add_u64 v[174:175], s[18:19], 0, v[152:153]
	s_add_i32 m0, s69, 0xe000
	s_nop 0
	global_load_lds_dwordx4 v[174:175], off
	s_waitcnt lgkmcnt(8)
	s_barrier
	s_setprio 0
	s_waitcnt lgkmcnt(7)
	v_mfma_f32_16x16x32_bf16 v[124:127], v[128:131], v[154:157], v[124:127]
	v_mfma_f32_16x16x32_bf16 v[120:123], v[136:139], v[154:157], v[120:123]
	s_waitcnt lgkmcnt(6)
	v_mfma_f32_16x16x32_bf16 v[108:111], v[128:131], v[166:169], v[108:111]
	v_mfma_f32_16x16x32_bf16 v[104:107], v[136:139], v[166:169], v[104:107]
	s_waitcnt lgkmcnt(5)
	v_mfma_f32_16x16x32_bf16 v[92:95], v[128:131], v[188:191], v[92:95]
	v_mfma_f32_16x16x32_bf16 v[88:91], v[136:139], v[188:191], v[88:91]
	s_waitcnt lgkmcnt(4)
	v_mfma_f32_16x16x32_bf16 v[76:79], v[128:131], v[196:199], v[76:79]
	v_mfma_f32_16x16x32_bf16 v[72:75], v[136:139], v[196:199], v[72:75]
	s_waitcnt lgkmcnt(3)
	v_mfma_f32_16x16x32_bf16 v[124:127], v[132:135], v[158:161], v[124:127]
	v_mfma_f32_16x16x32_bf16 v[120:123], v[140:143], v[158:161], v[120:123]
	s_waitcnt lgkmcnt(2)
	v_mfma_f32_16x16x32_bf16 v[108:111], v[132:135], v[170:173], v[108:111]
	v_mfma_f32_16x16x32_bf16 v[104:107], v[140:143], v[170:173], v[104:107]
	s_waitcnt lgkmcnt(1)
	v_mfma_f32_16x16x32_bf16 v[92:95], v[132:135], v[192:195], v[92:95]
	v_mfma_f32_16x16x32_bf16 v[88:91], v[140:143], v[192:195], v[88:91]
	s_waitcnt lgkmcnt(0)
	v_mfma_f32_16x16x32_bf16 v[76:79], v[132:135], v[200:203], v[76:79]
	v_mfma_f32_16x16x32_bf16 v[72:75], v[140:143], v[200:203], v[72:75]
	s_barrier
	s_setprio 1
	s_add_i32 s29, 0, 0x14000
	v_add_u32_e32 v174, s29, v164
	s_add_i32 s18, s28, s68
	ds_read_b128 v[204:207], v174
	ds_read_b128 v[208:211], v174 offset:1024
	ds_read_b128 v[212:215], v174 offset:2048
	ds_read_b128 v[232:235], v174 offset:3072
	v_lshl_add_u64 v[174:175], s[62:63], 0, v[176:177]
	s_mov_b32 m0, s18
	v_lshl_add_u64 v[216:217], s[62:63], 0, v[148:149]
	global_load_lds_dwordx4 v[174:175], off
	s_add_i32 m0, s18, 0x2000
	s_nop 0
	global_load_lds_dwordx4 v[216:217], off
	s_barrier
	s_setprio 0
	s_waitcnt lgkmcnt(3)
	v_mfma_f32_16x16x32_bf16 v[116:119], v[204:207], v[154:157], v[116:119]
	s_waitcnt lgkmcnt(1)
	v_mfma_f32_16x16x32_bf16 v[112:115], v[212:215], v[154:157], v[112:115]
	v_mfma_f32_16x16x32_bf16 v[100:103], v[204:207], v[166:169], v[100:103]
	v_mfma_f32_16x16x32_bf16 v[96:99], v[212:215], v[166:169], v[96:99]
	v_mfma_f32_16x16x32_bf16 v[84:87], v[204:207], v[188:191], v[84:87]
	v_mfma_f32_16x16x32_bf16 v[80:83], v[212:215], v[188:191], v[80:83]
	v_mfma_f32_16x16x32_bf16 v[68:71], v[204:207], v[196:199], v[68:71]
	v_mfma_f32_16x16x32_bf16 v[64:67], v[212:215], v[196:199], v[64:67]
	v_mfma_f32_16x16x32_bf16 v[116:119], v[208:211], v[158:161], v[116:119]
	s_waitcnt lgkmcnt(0)
	v_mfma_f32_16x16x32_bf16 v[112:115], v[232:235], v[158:161], v[112:115]
	v_mfma_f32_16x16x32_bf16 v[100:103], v[208:211], v[170:173], v[100:103]
	v_mfma_f32_16x16x32_bf16 v[96:99], v[232:235], v[170:173], v[96:99]
	v_mfma_f32_16x16x32_bf16 v[84:87], v[208:211], v[192:195], v[84:87]
	v_mfma_f32_16x16x32_bf16 v[80:83], v[232:235], v[192:195], v[80:83]
	v_mfma_f32_16x16x32_bf16 v[68:71], v[208:211], v[200:203], v[68:71]
	v_mfma_f32_16x16x32_bf16 v[64:67], v[232:235], v[200:203], v[64:67]
	s_mov_b32 m0, s69
	v_lshl_add_u64 v[236:237], s[64:65], 0, v[144:145]
	s_barrier
	s_setprio 1
	ds_read_b128 v[154:157], v165 offset:16384
	ds_read_b128 v[166:169], v165 offset:18432
	ds_read_b128 v[188:191], v165 offset:20480
	ds_read_b128 v[196:199], v165 offset:22528
	ds_read_b128 v[158:161], v165 offset:17408
	ds_read_b128 v[170:173], v165 offset:19456
	ds_read_b128 v[192:195], v165 offset:21504
	ds_read_b128 v[200:203], v165 offset:23552
	global_load_lds_dwordx4 v[236:237], off
	v_lshl_add_u64 v[238:239], s[64:65], 0, v[146:147]
	s_mov_b32 m0, s70
	s_nop 0
	global_load_lds_dwordx4 v[238:239], off
	s_barrier
	s_setprio 0
	s_waitcnt lgkmcnt(7)
	v_mfma_f32_16x16x32_bf16 v[60:63], v[128:131], v[154:157], v[60:63]
	v_mfma_f32_16x16x32_bf16 v[56:59], v[136:139], v[154:157], v[56:59]
	s_waitcnt lgkmcnt(6)
	v_mfma_f32_16x16x32_bf16 v[44:47], v[128:131], v[166:169], v[44:47]
	v_mfma_f32_16x16x32_bf16 v[40:43], v[136:139], v[166:169], v[40:43]
	s_waitcnt lgkmcnt(5)
	v_mfma_f32_16x16x32_bf16 v[28:31], v[128:131], v[188:191], v[28:31]
	v_mfma_f32_16x16x32_bf16 v[24:27], v[136:139], v[188:191], v[24:27]
	s_waitcnt lgkmcnt(4)
	v_mfma_f32_16x16x32_bf16 v[12:15], v[128:131], v[196:199], v[12:15]
	v_mfma_f32_16x16x32_bf16 v[8:11], v[136:139], v[196:199], v[8:11]
	s_waitcnt lgkmcnt(3)
	v_mfma_f32_16x16x32_bf16 v[60:63], v[132:135], v[158:161], v[60:63]
	v_mfma_f32_16x16x32_bf16 v[56:59], v[140:143], v[158:161], v[56:59]
	s_waitcnt lgkmcnt(2)
	v_mfma_f32_16x16x32_bf16 v[44:47], v[132:135], v[170:173], v[44:47]
	v_mfma_f32_16x16x32_bf16 v[40:43], v[140:143], v[170:173], v[40:43]
	s_waitcnt lgkmcnt(1)
	v_mfma_f32_16x16x32_bf16 v[28:31], v[132:135], v[192:195], v[28:31]
	v_mfma_f32_16x16x32_bf16 v[24:27], v[140:143], v[192:195], v[24:27]
	s_waitcnt lgkmcnt(0)
	v_mfma_f32_16x16x32_bf16 v[12:15], v[132:135], v[200:203], v[12:15]
	v_mfma_f32_16x16x32_bf16 v[8:11], v[140:143], v[200:203], v[8:11]
	s_barrier
	s_setprio 1
	s_add_u32 s18, s62, 0x18000
	s_addc_u32 s19, s63, 0
	s_add_i32 s28, s29, s68
	v_lshl_add_u64 v[128:129], s[18:19], 0, v[176:177]
	s_mov_b32 m0, s28
	s_nop 0
	global_load_lds_dwordx4 v[128:129], off
	v_lshl_add_u64 v[128:129], s[18:19], 0, v[148:149]
	s_add_i32 m0, s28, 0x2000
	s_nop 0
	global_load_lds_dwordx4 v[128:129], off
	s_waitcnt vmcnt(6)
	s_barrier
	s_setprio 0
	v_mfma_f32_16x16x32_bf16 v[52:55], v[204:207], v[154:157], v[52:55]
	v_mfma_f32_16x16x32_bf16 v[48:51], v[212:215], v[154:157], v[48:51]
	v_mfma_f32_16x16x32_bf16 v[36:39], v[204:207], v[166:169], v[36:39]
	v_mfma_f32_16x16x32_bf16 v[32:35], v[212:215], v[166:169], v[32:35]
	v_mfma_f32_16x16x32_bf16 v[20:23], v[204:207], v[188:191], v[20:23]
	v_mfma_f32_16x16x32_bf16 v[16:19], v[212:215], v[188:191], v[16:19]
	v_mfma_f32_16x16x32_bf16 v[4:7], v[204:207], v[196:199], v[4:7]
	v_mfma_f32_16x16x32_bf16 v[0:3], v[212:215], v[196:199], v[0:3]
	v_mfma_f32_16x16x32_bf16 v[52:55], v[208:211], v[158:161], v[52:55]
	v_mfma_f32_16x16x32_bf16 v[48:51], v[232:235], v[158:161], v[48:51]
	v_mfma_f32_16x16x32_bf16 v[36:39], v[208:211], v[170:173], v[36:39]
	v_mfma_f32_16x16x32_bf16 v[32:35], v[232:235], v[170:173], v[32:35]
	v_mfma_f32_16x16x32_bf16 v[20:23], v[208:211], v[192:195], v[20:23]
	v_mfma_f32_16x16x32_bf16 v[16:19], v[232:235], v[192:195], v[16:19]
	v_mfma_f32_16x16x32_bf16 v[4:7], v[208:211], v[200:203], v[4:7]
	v_mfma_f32_16x16x32_bf16 v[0:3], v[232:235], v[200:203], v[0:3]
	s_add_i32 s28, 0, 0x18000
	v_add_u32_e32 v140, s28, v164
	s_barrier
	s_setprio 1
	ds_read_b128 v[128:131], v140
	ds_read_b128 v[132:135], v140 offset:1024
	ds_read_b128 v[136:139], v140 offset:2048
	ds_read_b128 v[140:143], v140 offset:3072
	s_add_u32 s18, s64, 0x18000
	s_addc_u32 s19, s65, 0
	s_mov_b32 m0, s71
	v_lshl_add_u64 v[204:205], s[18:19], 0, v[144:145]
	ds_read_b128 v[154:157], v165 offset:32768
	ds_read_b128 v[166:169], v165 offset:34816
	ds_read_b128 v[188:191], v165 offset:36864
	ds_read_b128 v[196:199], v165 offset:38912
	ds_read_b128 v[158:161], v165 offset:33792
	ds_read_b128 v[170:173], v165 offset:35840
	ds_read_b128 v[192:195], v165 offset:37888
	ds_read_b128 v[200:203], v165 offset:39936
	global_load_lds_dwordx4 v[204:205], off
	v_lshl_add_u64 v[204:205], s[18:19], 0, v[146:147]
	s_mov_b32 m0, s72
	s_nop 0
	global_load_lds_dwordx4 v[204:205], off
	s_waitcnt lgkmcnt(8)
	s_barrier
	s_setprio 0
	s_waitcnt lgkmcnt(7)
	v_mfma_f32_16x16x32_bf16 v[124:127], v[128:131], v[154:157], v[124:127]
	v_mfma_f32_16x16x32_bf16 v[120:123], v[136:139], v[154:157], v[120:123]
	s_waitcnt lgkmcnt(6)
	v_mfma_f32_16x16x32_bf16 v[108:111], v[128:131], v[166:169], v[108:111]
	v_mfma_f32_16x16x32_bf16 v[104:107], v[136:139], v[166:169], v[104:107]
	s_waitcnt lgkmcnt(5)
	v_mfma_f32_16x16x32_bf16 v[92:95], v[128:131], v[188:191], v[92:95]
	v_mfma_f32_16x16x32_bf16 v[88:91], v[136:139], v[188:191], v[88:91]
	s_waitcnt lgkmcnt(4)
	v_mfma_f32_16x16x32_bf16 v[76:79], v[128:131], v[196:199], v[76:79]
	v_mfma_f32_16x16x32_bf16 v[72:75], v[136:139], v[196:199], v[72:75]
	s_waitcnt lgkmcnt(3)
	v_mfma_f32_16x16x32_bf16 v[124:127], v[132:135], v[158:161], v[124:127]
	v_mfma_f32_16x16x32_bf16 v[120:123], v[140:143], v[158:161], v[120:123]
	s_waitcnt lgkmcnt(2)
	v_mfma_f32_16x16x32_bf16 v[108:111], v[132:135], v[170:173], v[108:111]
	v_mfma_f32_16x16x32_bf16 v[104:107], v[140:143], v[170:173], v[104:107]
	s_waitcnt lgkmcnt(1)
	v_mfma_f32_16x16x32_bf16 v[92:95], v[132:135], v[192:195], v[92:95]
	v_mfma_f32_16x16x32_bf16 v[88:91], v[140:143], v[192:195], v[88:91]
	s_waitcnt lgkmcnt(0)
	v_mfma_f32_16x16x32_bf16 v[76:79], v[132:135], v[200:203], v[76:79]
	v_mfma_f32_16x16x32_bf16 v[72:75], v[140:143], v[200:203], v[72:75]
	s_barrier
	s_setprio 1
	s_add_i32 s29, 0, 0x1c000
	s_add_i32 s18, s28, s68
	v_add_u32_e32 v232, s29, v164
	v_lshl_add_u64 v[174:175], v[174:175], 0, s[40:41]
	s_mov_b32 m0, s18
	ds_read_b128 v[204:207], v232
	ds_read_b128 v[208:211], v232 offset:1024
	ds_read_b128 v[212:215], v232 offset:2048
	ds_read_b128 v[232:235], v232 offset:3072
	global_load_lds_dwordx4 v[174:175], off
	v_lshl_add_u64 v[174:175], v[216:217], 0, s[40:41]
	s_add_i32 m0, s18, 0x2000
	s_nop 0
	global_load_lds_dwordx4 v[174:175], off
	s_barrier
	s_setprio 0
	s_waitcnt lgkmcnt(3)
	v_mfma_f32_16x16x32_bf16 v[116:119], v[204:207], v[154:157], v[116:119]
	s_waitcnt lgkmcnt(1)
	v_mfma_f32_16x16x32_bf16 v[112:115], v[212:215], v[154:157], v[112:115]
	v_mfma_f32_16x16x32_bf16 v[100:103], v[204:207], v[166:169], v[100:103]
	v_mfma_f32_16x16x32_bf16 v[96:99], v[212:215], v[166:169], v[96:99]
	v_mfma_f32_16x16x32_bf16 v[84:87], v[204:207], v[188:191], v[84:87]
	v_mfma_f32_16x16x32_bf16 v[80:83], v[212:215], v[188:191], v[80:83]
	v_mfma_f32_16x16x32_bf16 v[68:71], v[204:207], v[196:199], v[68:71]
	v_mfma_f32_16x16x32_bf16 v[64:67], v[212:215], v[196:199], v[64:67]
	v_mfma_f32_16x16x32_bf16 v[116:119], v[208:211], v[158:161], v[116:119]
	s_waitcnt lgkmcnt(0)
	v_mfma_f32_16x16x32_bf16 v[112:115], v[232:235], v[158:161], v[112:115]
	v_mfma_f32_16x16x32_bf16 v[100:103], v[208:211], v[170:173], v[100:103]
	v_mfma_f32_16x16x32_bf16 v[96:99], v[232:235], v[170:173], v[96:99]
	v_mfma_f32_16x16x32_bf16 v[84:87], v[208:211], v[192:195], v[84:87]
	v_mfma_f32_16x16x32_bf16 v[80:83], v[232:235], v[192:195], v[80:83]
	v_mfma_f32_16x16x32_bf16 v[68:71], v[208:211], v[200:203], v[68:71]
	v_mfma_f32_16x16x32_bf16 v[64:67], v[232:235], v[200:203], v[64:67]
	s_mov_b32 m0, s75
	v_lshl_add_u64 v[174:175], v[236:237], 0, s[40:41]
	s_barrier
	s_setprio 1
	ds_read_b128 v[154:157], v165 offset:49152
	ds_read_b128 v[166:169], v165 offset:51200
	ds_read_b128 v[188:191], v165 offset:53248
	ds_read_b128 v[196:199], v165 offset:55296
	ds_read_b128 v[158:161], v165 offset:50176
	ds_read_b128 v[170:173], v165 offset:52224
	ds_read_b128 v[192:195], v165 offset:54272
	ds_read_b128 v[200:203], v165 offset:56320
	global_load_lds_dwordx4 v[174:175], off
	v_lshl_add_u64 v[174:175], v[238:239], 0, s[40:41]
	s_mov_b32 m0, s76
	s_nop 0
	global_load_lds_dwordx4 v[174:175], off
	s_barrier
	s_setprio 0
	s_waitcnt lgkmcnt(7)
	v_mfma_f32_16x16x32_bf16 v[60:63], v[128:131], v[154:157], v[60:63]
	v_mfma_f32_16x16x32_bf16 v[56:59], v[136:139], v[154:157], v[56:59]
	s_waitcnt lgkmcnt(6)
	v_mfma_f32_16x16x32_bf16 v[44:47], v[128:131], v[166:169], v[44:47]
	v_mfma_f32_16x16x32_bf16 v[40:43], v[136:139], v[166:169], v[40:43]
	s_waitcnt lgkmcnt(5)
	v_mfma_f32_16x16x32_bf16 v[28:31], v[128:131], v[188:191], v[28:31]
	v_mfma_f32_16x16x32_bf16 v[24:27], v[136:139], v[188:191], v[24:27]
	s_waitcnt lgkmcnt(4)
	v_mfma_f32_16x16x32_bf16 v[12:15], v[128:131], v[196:199], v[12:15]
	v_mfma_f32_16x16x32_bf16 v[8:11], v[136:139], v[196:199], v[8:11]
	s_waitcnt lgkmcnt(3)
	v_mfma_f32_16x16x32_bf16 v[60:63], v[132:135], v[158:161], v[60:63]
	v_mfma_f32_16x16x32_bf16 v[56:59], v[140:143], v[158:161], v[56:59]
	s_waitcnt lgkmcnt(2)
	v_mfma_f32_16x16x32_bf16 v[44:47], v[132:135], v[170:173], v[44:47]
	v_mfma_f32_16x16x32_bf16 v[40:43], v[140:143], v[170:173], v[40:43]
	s_waitcnt lgkmcnt(1)
	v_mfma_f32_16x16x32_bf16 v[28:31], v[132:135], v[192:195], v[28:31]
	v_mfma_f32_16x16x32_bf16 v[24:27], v[140:143], v[192:195], v[24:27]
	s_waitcnt lgkmcnt(0)
	v_mfma_f32_16x16x32_bf16 v[12:15], v[132:135], v[200:203], v[12:15]
	v_mfma_f32_16x16x32_bf16 v[8:11], v[140:143], v[200:203], v[8:11]
	s_barrier
	s_setprio 1
	s_add_u32 s18, s62, 0x18080
	s_addc_u32 s19, s63, 0
	s_add_i32 s28, s29, s68
	v_lshl_add_u64 v[128:129], s[18:19], 0, v[176:177]
	s_mov_b32 m0, s28
	s_nop 0
	global_load_lds_dwordx4 v[128:129], off
	v_lshl_add_u64 v[128:129], s[18:19], 0, v[148:149]
	s_add_i32 m0, s28, 0x2000
	s_nop 0
	global_load_lds_dwordx4 v[128:129], off
	s_waitcnt vmcnt(6)
	s_barrier
	s_setprio 0
	v_mfma_f32_16x16x32_bf16 v[52:55], v[204:207], v[154:157], v[52:55]
	v_mfma_f32_16x16x32_bf16 v[48:51], v[212:215], v[154:157], v[48:51]
	v_mfma_f32_16x16x32_bf16 v[36:39], v[204:207], v[166:169], v[36:39]
	v_mfma_f32_16x16x32_bf16 v[32:35], v[212:215], v[166:169], v[32:35]
	v_mfma_f32_16x16x32_bf16 v[20:23], v[204:207], v[188:191], v[20:23]
	v_mfma_f32_16x16x32_bf16 v[16:19], v[212:215], v[188:191], v[16:19]
	v_mfma_f32_16x16x32_bf16 v[4:7], v[204:207], v[196:199], v[4:7]
	v_mfma_f32_16x16x32_bf16 v[0:3], v[212:215], v[196:199], v[0:3]
	v_mfma_f32_16x16x32_bf16 v[52:55], v[208:211], v[158:161], v[52:55]
	v_mfma_f32_16x16x32_bf16 v[48:51], v[232:235], v[158:161], v[48:51]
	v_mfma_f32_16x16x32_bf16 v[36:39], v[208:211], v[170:173], v[36:39]
	v_mfma_f32_16x16x32_bf16 v[32:35], v[232:235], v[170:173], v[32:35]
	v_mfma_f32_16x16x32_bf16 v[20:23], v[208:211], v[192:195], v[20:23]
	v_mfma_f32_16x16x32_bf16 v[16:19], v[232:235], v[192:195], v[16:19]
	v_mfma_f32_16x16x32_bf16 v[4:7], v[208:211], v[200:203], v[4:7]
	v_mfma_f32_16x16x32_bf16 v[0:3], v[232:235], v[200:203], v[0:3]
	s_add_u32 s85, s85, 0x100
	s_addc_u32 s91, s91, 0
	s_cmp_lt_i32 vcc_lo, s67
	s_mov_b64 s[18:19], s[4:5]
	s_mov_b32 s62, vcc_lo
	s_barrier
	s_cbranch_scc1 .LBB0_413
	s_ashr_i32 s4, s66, 2
	v_mov_b32_e32 v128, v163
	v_mov_b32_e32 v166, v162
	s_cmp_eq_u32 s4, 2
	s_cbranch_scc1 .LBB0_416
	s_mul_i32 s13, s4, 0x2280000
	s_mul_hi_i32 s5, s4, 0x2280000
	s_add_u32 s18, s13, 0x5858000
	s_addc_u32 s19, s5, 0
	s_mov_b32 s62, 1.0
	s_branch .LBB0_417

.LBB0_505:
	s_setprio 1
	s_add_u32 s6, s4, 0xfff80080
	s_addc_u32 s7, s5, -1
	s_add_i32 s28, 0, 0x10000
	v_add_u32_e32 v154, s28, v144
	ds_read_b128 v[138:141], v154
	ds_read_b128 v[146:149], v154 offset:1024
	ds_read_b128 v[150:153], v154 offset:2048
	ds_read_b128 v[154:157], v154 offset:3072
	s_cmp_eq_u32 s72, 28
	s_cselect_b32 s9, s10, s7
	s_cselect_b32 s8, s11, s6
	s_cselect_b32 s7, s63, s71
	s_cselect_b32 s6, s65, s70
	v_lshl_add_u64 v[174:175], s[4:5], 0, v[134:135]
	s_add_i32 m0, s17, 0xc000
	ds_read_b128 v[158:161], v145
	ds_read_b128 v[166:169], v145 offset:2048
	ds_read_b128 v[188:191], v145 offset:4096
	ds_read_b128 v[196:199], v145 offset:6144
	ds_read_b128 v[162:165], v145 offset:1024
	ds_read_b128 v[170:173], v145 offset:3072
	ds_read_b128 v[192:195], v145 offset:5120
	ds_read_b128 v[200:203], v145 offset:7168
	global_load_lds_dwordx4 v[174:175], off
	v_lshl_add_u64 v[174:175], s[4:5], 0, v[136:137]
	s_add_i32 m0, s17, 0xe000
	s_nop 0
	global_load_lds_dwordx4 v[174:175], off
	s_waitcnt lgkmcnt(8)
	s_barrier
	s_setprio 0
	s_waitcnt lgkmcnt(7)
	v_mfma_f32_16x16x32_bf16 v[124:127], v[138:141], v[158:161], v[124:127]
	v_mfma_f32_16x16x32_bf16 v[120:123], v[150:153], v[158:161], v[120:123]
	s_waitcnt lgkmcnt(6)
	v_mfma_f32_16x16x32_bf16 v[116:119], v[138:141], v[166:169], v[116:119]
	v_mfma_f32_16x16x32_bf16 v[108:111], v[150:153], v[166:169], v[108:111]
	s_waitcnt lgkmcnt(5)
	v_mfma_f32_16x16x32_bf16 v[100:103], v[138:141], v[188:191], v[100:103]
	v_mfma_f32_16x16x32_bf16 v[92:95], v[150:153], v[188:191], v[92:95]
	s_waitcnt lgkmcnt(4)
	v_mfma_f32_16x16x32_bf16 v[84:87], v[138:141], v[196:199], v[84:87]
	v_mfma_f32_16x16x32_bf16 v[76:79], v[150:153], v[196:199], v[76:79]
	s_waitcnt lgkmcnt(3)
	v_mfma_f32_16x16x32_bf16 v[124:127], v[146:149], v[162:165], v[124:127]
	v_mfma_f32_16x16x32_bf16 v[120:123], v[154:157], v[162:165], v[120:123]
	s_waitcnt lgkmcnt(2)
	v_mfma_f32_16x16x32_bf16 v[116:119], v[146:149], v[170:173], v[116:119]
	v_mfma_f32_16x16x32_bf16 v[108:111], v[154:157], v[170:173], v[108:111]
	s_waitcnt lgkmcnt(1)
	v_mfma_f32_16x16x32_bf16 v[100:103], v[146:149], v[192:195], v[100:103]
	v_mfma_f32_16x16x32_bf16 v[92:95], v[154:157], v[192:195], v[92:95]
	s_waitcnt lgkmcnt(0)
	v_mfma_f32_16x16x32_bf16 v[84:87], v[146:149], v[200:203], v[84:87]
	v_mfma_f32_16x16x32_bf16 v[76:79], v[154:157], v[200:203], v[76:79]
	s_barrier
	s_setprio 1
	s_add_i32 s29, 0, 0x14000
	v_add_u32_e32 v174, s29, v144
	s_add_i32 s28, s28, s77
	ds_read_b128 v[204:207], v174
	ds_read_b128 v[208:211], v174 offset:1024
	ds_read_b128 v[212:215], v174 offset:2048
	ds_read_b128 v[232:235], v174 offset:3072
	v_lshl_add_u64 v[174:175], s[6:7], 0, v[176:177]
	s_mov_b32 m0, s28
	v_lshl_add_u64 v[216:217], s[6:7], 0, v[132:133]
	global_load_lds_dwordx4 v[174:175], off
	s_add_i32 m0, s28, 0x2000
	s_nop 0
	global_load_lds_dwordx4 v[216:217], off
	s_barrier
	s_setprio 0
	s_waitcnt lgkmcnt(3)
	v_mfma_f32_16x16x32_bf16 v[112:115], v[204:207], v[158:161], v[112:115]
	s_waitcnt lgkmcnt(1)
	v_mfma_f32_16x16x32_bf16 v[104:107], v[212:215], v[158:161], v[104:107]
	v_mfma_f32_16x16x32_bf16 v[96:99], v[204:207], v[166:169], v[96:99]
	v_mfma_f32_16x16x32_bf16 v[88:91], v[212:215], v[166:169], v[88:91]
	v_mfma_f32_16x16x32_bf16 v[80:83], v[204:207], v[188:191], v[80:83]
	v_mfma_f32_16x16x32_bf16 v[72:75], v[212:215], v[188:191], v[72:75]
	v_mfma_f32_16x16x32_bf16 v[68:71], v[204:207], v[196:199], v[68:71]
	v_mfma_f32_16x16x32_bf16 v[64:67], v[212:215], v[196:199], v[64:67]
	v_mfma_f32_16x16x32_bf16 v[112:115], v[208:211], v[162:165], v[112:115]
	s_waitcnt lgkmcnt(0)
	v_mfma_f32_16x16x32_bf16 v[104:107], v[232:235], v[162:165], v[104:107]
	v_mfma_f32_16x16x32_bf16 v[96:99], v[208:211], v[170:173], v[96:99]
	v_mfma_f32_16x16x32_bf16 v[88:91], v[232:235], v[170:173], v[88:91]
	v_mfma_f32_16x16x32_bf16 v[80:83], v[208:211], v[192:195], v[80:83]
	v_mfma_f32_16x16x32_bf16 v[72:75], v[232:235], v[192:195], v[72:75]
	v_mfma_f32_16x16x32_bf16 v[68:71], v[208:211], v[200:203], v[68:71]
	v_mfma_f32_16x16x32_bf16 v[64:67], v[232:235], v[200:203], v[64:67]
	s_mov_b32 m0, s17
	v_lshl_add_u64 v[236:237], s[8:9], 0, v[128:129]
	s_barrier
	s_setprio 1
	ds_read_b128 v[158:161], v145 offset:16384
	ds_read_b128 v[166:169], v145 offset:18432
	ds_read_b128 v[188:191], v145 offset:20480
	ds_read_b128 v[196:199], v145 offset:22528
	ds_read_b128 v[162:165], v145 offset:17408
	ds_read_b128 v[170:173], v145 offset:19456
	ds_read_b128 v[192:195], v145 offset:21504
	ds_read_b128 v[200:203], v145 offset:23552
	global_load_lds_dwordx4 v[236:237], off
	v_lshl_add_u64 v[238:239], s[8:9], 0, v[130:131]
	s_mov_b32 m0, s19
	s_nop 0
	global_load_lds_dwordx4 v[238:239], off
	s_barrier
	s_setprio 0
	s_waitcnt lgkmcnt(7)
	v_mfma_f32_16x16x32_bf16 v[60:63], v[138:141], v[158:161], v[60:63]
	v_mfma_f32_16x16x32_bf16 v[56:59], v[150:153], v[158:161], v[56:59]
	s_waitcnt lgkmcnt(6)
	v_mfma_f32_16x16x32_bf16 v[52:55], v[138:141], v[166:169], v[52:55]
	v_mfma_f32_16x16x32_bf16 v[44:47], v[150:153], v[166:169], v[44:47]
	s_waitcnt lgkmcnt(5)
	v_mfma_f32_16x16x32_bf16 v[36:39], v[138:141], v[188:191], v[36:39]
	v_mfma_f32_16x16x32_bf16 v[28:31], v[150:153], v[188:191], v[28:31]
	s_waitcnt lgkmcnt(4)
	v_mfma_f32_16x16x32_bf16 v[20:23], v[138:141], v[196:199], v[20:23]
	v_mfma_f32_16x16x32_bf16 v[12:15], v[150:153], v[196:199], v[12:15]
	s_waitcnt lgkmcnt(3)
	v_mfma_f32_16x16x32_bf16 v[60:63], v[146:149], v[162:165], v[60:63]
	v_mfma_f32_16x16x32_bf16 v[56:59], v[154:157], v[162:165], v[56:59]
	s_waitcnt lgkmcnt(2)
	v_mfma_f32_16x16x32_bf16 v[52:55], v[146:149], v[170:173], v[52:55]
	v_mfma_f32_16x16x32_bf16 v[44:47], v[154:157], v[170:173], v[44:47]
	s_waitcnt lgkmcnt(1)
	v_mfma_f32_16x16x32_bf16 v[36:39], v[146:149], v[192:195], v[36:39]
	v_mfma_f32_16x16x32_bf16 v[28:31], v[154:157], v[192:195], v[28:31]
	s_waitcnt lgkmcnt(0)
	v_mfma_f32_16x16x32_bf16 v[20:23], v[146:149], v[200:203], v[20:23]
	v_mfma_f32_16x16x32_bf16 v[12:15], v[154:157], v[200:203], v[12:15]
	s_barrier
	s_setprio 1
	s_add_u32 vcc_lo, s6, 0x80000
	s_addc_u32 vcc_hi, s7, 0
	s_add_i32 s28, s29, s77
	v_lshl_add_u64 v[138:139], vcc, 0, v[176:177]
	s_mov_b32 m0, s28
	s_nop 0
	global_load_lds_dwordx4 v[138:139], off
	v_lshl_add_u64 v[138:139], vcc, 0, v[132:133]
	s_add_i32 m0, s28, 0x2000
	s_nop 0
	global_load_lds_dwordx4 v[138:139], off
	s_waitcnt vmcnt(6)
	s_barrier
	s_setprio 0
	v_mfma_f32_16x16x32_bf16 v[48:51], v[204:207], v[158:161], v[48:51]
	v_mfma_f32_16x16x32_bf16 v[40:43], v[212:215], v[158:161], v[40:43]
	v_mfma_f32_16x16x32_bf16 v[32:35], v[204:207], v[166:169], v[32:35]
	v_mfma_f32_16x16x32_bf16 v[24:27], v[212:215], v[166:169], v[24:27]
	v_mfma_f32_16x16x32_bf16 v[16:19], v[204:207], v[188:191], v[16:19]
	v_mfma_f32_16x16x32_bf16 v[8:11], v[212:215], v[188:191], v[8:11]
	v_mfma_f32_16x16x32_bf16 v[4:7], v[204:207], v[196:199], v[4:7]
	v_mfma_f32_16x16x32_bf16 v[0:3], v[212:215], v[196:199], v[0:3]
	v_mfma_f32_16x16x32_bf16 v[48:51], v[208:211], v[162:165], v[48:51]
	v_mfma_f32_16x16x32_bf16 v[40:43], v[232:235], v[162:165], v[40:43]
	v_mfma_f32_16x16x32_bf16 v[32:35], v[208:211], v[170:173], v[32:35]
	v_mfma_f32_16x16x32_bf16 v[24:27], v[232:235], v[170:173], v[24:27]
	v_mfma_f32_16x16x32_bf16 v[16:19], v[208:211], v[192:195], v[16:19]
	v_mfma_f32_16x16x32_bf16 v[8:11], v[232:235], v[192:195], v[8:11]
	v_mfma_f32_16x16x32_bf16 v[4:7], v[208:211], v[200:203], v[4:7]
	v_mfma_f32_16x16x32_bf16 v[0:3], v[232:235], v[200:203], v[0:3]
	s_add_i32 s28, 0, 0x18000
	v_add_u32_e32 v154, s28, v144
	s_barrier
	s_setprio 1
	ds_read_b128 v[138:141], v154
	ds_read_b128 v[146:149], v154 offset:1024
	ds_read_b128 v[150:153], v154 offset:2048
	ds_read_b128 v[154:157], v154 offset:3072
	s_add_u32 s8, s8, 0x80000
	s_addc_u32 s9, s9, 0
	s_mov_b32 m0, s78
	v_lshl_add_u64 v[204:205], s[8:9], 0, v[128:129]
	ds_read_b128 v[158:161], v145 offset:32768
	ds_read_b128 v[166:169], v145 offset:34816
	ds_read_b128 v[188:191], v145 offset:36864
	ds_read_b128 v[196:199], v145 offset:38912
	ds_read_b128 v[162:165], v145 offset:33792
	ds_read_b128 v[170:173], v145 offset:35840
	ds_read_b128 v[192:195], v145 offset:37888
	ds_read_b128 v[200:203], v145 offset:39936
	global_load_lds_dwordx4 v[204:205], off
	v_lshl_add_u64 v[204:205], s[8:9], 0, v[130:131]
	s_mov_b32 m0, s79
	s_nop 0
	global_load_lds_dwordx4 v[204:205], off
	s_waitcnt lgkmcnt(8)
	s_barrier
	s_setprio 0
	s_waitcnt lgkmcnt(7)
	v_mfma_f32_16x16x32_bf16 v[124:127], v[138:141], v[158:161], v[124:127]
	v_mfma_f32_16x16x32_bf16 v[120:123], v[150:153], v[158:161], v[120:123]
	s_waitcnt lgkmcnt(6)
	v_mfma_f32_16x16x32_bf16 v[116:119], v[138:141], v[166:169], v[116:119]
	v_mfma_f32_16x16x32_bf16 v[108:111], v[150:153], v[166:169], v[108:111]
	s_waitcnt lgkmcnt(5)
	v_mfma_f32_16x16x32_bf16 v[100:103], v[138:141], v[188:191], v[100:103]
	v_mfma_f32_16x16x32_bf16 v[92:95], v[150:153], v[188:191], v[92:95]
	s_waitcnt lgkmcnt(4)
	v_mfma_f32_16x16x32_bf16 v[84:87], v[138:141], v[196:199], v[84:87]
	v_mfma_f32_16x16x32_bf16 v[76:79], v[150:153], v[196:199], v[76:79]
	s_waitcnt lgkmcnt(3)
	v_mfma_f32_16x16x32_bf16 v[124:127], v[146:149], v[162:165], v[124:127]
	v_mfma_f32_16x16x32_bf16 v[120:123], v[154:157], v[162:165], v[120:123]
	s_waitcnt lgkmcnt(2)
	v_mfma_f32_16x16x32_bf16 v[116:119], v[146:149], v[170:173], v[116:119]
	v_mfma_f32_16x16x32_bf16 v[108:111], v[154:157], v[170:173], v[108:111]
	s_waitcnt lgkmcnt(1)
	v_mfma_f32_16x16x32_bf16 v[100:103], v[146:149], v[192:195], v[100:103]
	v_mfma_f32_16x16x32_bf16 v[92:95], v[154:157], v[192:195], v[92:95]
	s_waitcnt lgkmcnt(0)
	v_mfma_f32_16x16x32_bf16 v[84:87], v[146:149], v[200:203], v[84:87]
	v_mfma_f32_16x16x32_bf16 v[76:79], v[154:157], v[200:203], v[76:79]
	s_barrier
	s_setprio 1
	s_add_i32 s8, 0, 0x1c000
	s_add_i32 s9, s28, s77
	v_add_u32_e32 v232, s8, v144
	v_lshl_add_u64 v[174:175], v[174:175], 0, s[40:41]
	s_mov_b32 m0, s9
	ds_read_b128 v[204:207], v232
	ds_read_b128 v[208:211], v232 offset:1024
	ds_read_b128 v[212:215], v232 offset:2048
	ds_read_b128 v[232:235], v232 offset:3072
	global_load_lds_dwordx4 v[174:175], off
	v_lshl_add_u64 v[174:175], v[216:217], 0, s[40:41]
	s_add_i32 m0, s9, 0x2000
	s_nop 0
	global_load_lds_dwordx4 v[174:175], off
	s_barrier
	s_setprio 0
	s_waitcnt lgkmcnt(3)
	v_mfma_f32_16x16x32_bf16 v[112:115], v[204:207], v[158:161], v[112:115]
	s_waitcnt lgkmcnt(1)
	v_mfma_f32_16x16x32_bf16 v[104:107], v[212:215], v[158:161], v[104:107]
	v_mfma_f32_16x16x32_bf16 v[96:99], v[204:207], v[166:169], v[96:99]
	v_mfma_f32_16x16x32_bf16 v[88:91], v[212:215], v[166:169], v[88:91]
	v_mfma_f32_16x16x32_bf16 v[80:83], v[204:207], v[188:191], v[80:83]
	v_mfma_f32_16x16x32_bf16 v[72:75], v[212:215], v[188:191], v[72:75]
	v_mfma_f32_16x16x32_bf16 v[68:71], v[204:207], v[196:199], v[68:71]
	v_mfma_f32_16x16x32_bf16 v[64:67], v[212:215], v[196:199], v[64:67]
	v_mfma_f32_16x16x32_bf16 v[112:115], v[208:211], v[162:165], v[112:115]
	s_waitcnt lgkmcnt(0)
	v_mfma_f32_16x16x32_bf16 v[104:107], v[232:235], v[162:165], v[104:107]
	v_mfma_f32_16x16x32_bf16 v[96:99], v[208:211], v[170:173], v[96:99]
	v_mfma_f32_16x16x32_bf16 v[88:91], v[232:235], v[170:173], v[88:91]
	v_mfma_f32_16x16x32_bf16 v[80:83], v[208:211], v[192:195], v[80:83]
	v_mfma_f32_16x16x32_bf16 v[72:75], v[232:235], v[192:195], v[72:75]
	v_mfma_f32_16x16x32_bf16 v[68:71], v[208:211], v[200:203], v[68:71]
	v_mfma_f32_16x16x32_bf16 v[64:67], v[232:235], v[200:203], v[64:67]
	s_mov_b32 m0, s82
	v_lshl_add_u64 v[174:175], v[236:237], 0, s[40:41]
	s_barrier
	s_setprio 1
	ds_read_b128 v[158:161], v145 offset:49152
	ds_read_b128 v[166:169], v145 offset:51200
	ds_read_b128 v[188:191], v145 offset:53248
	ds_read_b128 v[196:199], v145 offset:55296
	ds_read_b128 v[162:165], v145 offset:50176
	ds_read_b128 v[170:173], v145 offset:52224
	ds_read_b128 v[192:195], v145 offset:54272
	ds_read_b128 v[200:203], v145 offset:56320
	global_load_lds_dwordx4 v[174:175], off
	v_lshl_add_u64 v[174:175], v[238:239], 0, s[40:41]
	s_mov_b32 m0, s83
	s_nop 0
	global_load_lds_dwordx4 v[174:175], off
	s_barrier
	s_setprio 0
	s_waitcnt lgkmcnt(7)
	v_mfma_f32_16x16x32_bf16 v[60:63], v[138:141], v[158:161], v[60:63]
	v_mfma_f32_16x16x32_bf16 v[56:59], v[150:153], v[158:161], v[56:59]
	s_waitcnt lgkmcnt(6)
	v_mfma_f32_16x16x32_bf16 v[52:55], v[138:141], v[166:169], v[52:55]
	v_mfma_f32_16x16x32_bf16 v[44:47], v[150:153], v[166:169], v[44:47]
	s_waitcnt lgkmcnt(5)
	v_mfma_f32_16x16x32_bf16 v[36:39], v[138:141], v[188:191], v[36:39]
	v_mfma_f32_16x16x32_bf16 v[28:31], v[150:153], v[188:191], v[28:31]
	s_waitcnt lgkmcnt(4)
	v_mfma_f32_16x16x32_bf16 v[20:23], v[138:141], v[196:199], v[20:23]
	v_mfma_f32_16x16x32_bf16 v[12:15], v[150:153], v[196:199], v[12:15]
	s_waitcnt lgkmcnt(3)
	v_mfma_f32_16x16x32_bf16 v[60:63], v[146:149], v[162:165], v[60:63]
	v_mfma_f32_16x16x32_bf16 v[56:59], v[154:157], v[162:165], v[56:59]
	s_waitcnt lgkmcnt(2)
	v_mfma_f32_16x16x32_bf16 v[52:55], v[146:149], v[170:173], v[52:55]
	v_mfma_f32_16x16x32_bf16 v[44:47], v[154:157], v[170:173], v[44:47]
	s_waitcnt lgkmcnt(1)
	v_mfma_f32_16x16x32_bf16 v[36:39], v[146:149], v[192:195], v[36:39]
	v_mfma_f32_16x16x32_bf16 v[28:31], v[154:157], v[192:195], v[28:31]
	s_waitcnt lgkmcnt(0)
	v_mfma_f32_16x16x32_bf16 v[20:23], v[146:149], v[200:203], v[20:23]
	v_mfma_f32_16x16x32_bf16 v[12:15], v[154:157], v[200:203], v[12:15]
	s_barrier
	s_setprio 1
	s_add_u32 s6, s6, 0x80080
	s_addc_u32 s7, s7, 0
	s_add_i32 s8, s8, s77
	v_lshl_add_u64 v[138:139], s[6:7], 0, v[176:177]
	s_mov_b32 m0, s8
	s_nop 0
	global_load_lds_dwordx4 v[138:139], off
	v_lshl_add_u64 v[138:139], s[6:7], 0, v[132:133]
	s_add_i32 m0, s8, 0x2000
	s_nop 0
	global_load_lds_dwordx4 v[138:139], off
	s_waitcnt vmcnt(6)
	s_barrier
	s_setprio 0
	v_mfma_f32_16x16x32_bf16 v[48:51], v[204:207], v[158:161], v[48:51]
	v_mfma_f32_16x16x32_bf16 v[40:43], v[212:215], v[158:161], v[40:43]
	v_mfma_f32_16x16x32_bf16 v[32:35], v[204:207], v[166:169], v[32:35]
	v_mfma_f32_16x16x32_bf16 v[24:27], v[212:215], v[166:169], v[24:27]
	v_mfma_f32_16x16x32_bf16 v[16:19], v[204:207], v[188:191], v[16:19]
	v_mfma_f32_16x16x32_bf16 v[8:11], v[212:215], v[188:191], v[8:11]
	v_mfma_f32_16x16x32_bf16 v[4:7], v[204:207], v[196:199], v[4:7]
	v_mfma_f32_16x16x32_bf16 v[0:3], v[212:215], v[196:199], v[0:3]
	v_mfma_f32_16x16x32_bf16 v[48:51], v[208:211], v[162:165], v[48:51]
	v_mfma_f32_16x16x32_bf16 v[40:43], v[232:235], v[162:165], v[40:43]
	v_mfma_f32_16x16x32_bf16 v[32:35], v[208:211], v[170:173], v[32:35]
	v_mfma_f32_16x16x32_bf16 v[24:27], v[232:235], v[170:173], v[24:27]
	v_mfma_f32_16x16x32_bf16 v[16:19], v[208:211], v[192:195], v[16:19]
	v_mfma_f32_16x16x32_bf16 v[8:11], v[232:235], v[192:195], v[8:11]
	v_mfma_f32_16x16x32_bf16 v[4:7], v[208:211], v[200:203], v[4:7]
	v_mfma_f32_16x16x32_bf16 v[0:3], v[232:235], v[200:203], v[0:3]
	s_add_i32 s72, s72, 2
	s_add_u32 s4, s4, 0x100
	s_addc_u32 s5, s5, 0
	s_add_u32 s70, s70, 0x100
	s_addc_u32 s71, s71, 0
	s_cmp_lt_u32 s72, 30
	s_barrier
	s_cbranch_scc1 .LBB0_505
	v_mov_b32_e32 v147, v142
	v_mov_b32_e32 v146, v143
	s_cmp_lt_i32 s16, 12
	s_mov_b64 s[4:5], -1
	s_cbranch_scc1 .LBB0_1052
	s_lshl_b32 s4, s18, 8
	s_add_i32 s4, s4, s80
	v_add_u32_e32 v149, s4, v147
	s_lshl_b32 s4, s16, 8
	s_add_i32 s4, s84, s4
	v_lshl_add_u32 v138, v146, 3, s4
	v_mad_i64_i32 v[140:141], s[4:5], v149, s97, 0
	v_cmp_gt_i32_e32 vcc, s34, v138
	s_and_saveexec_b64 s[10:11], vcc
	s_cbranch_execz .LBB0_541
	v_cmp_lt_i32_e64 s[8:9], 63, v138
	v_cmp_gt_u32_e64 s[4:5], s93, v138
	v_cmp_gt_u32_e64 s[6:7], s96, v138
	s_and_saveexec_b64 s[70:71], s[8:9]
	s_xor_b64 s[70:71], exec, s[70:71]
	s_cbranch_execz .LBB0_510
	v_mul_f32_e32 v139, 0xbfb8aa3b, v124
	v_exp_f32_e32 v139, v139
	s_nop 0
	v_add_f32_e32 v139, 1.0, v139
	v_rcp_f32_e32 v139, v139
	s_nop 0
	v_cndmask_b32_e64 v139, 0, v139, s[6:7]
	v_cndmask_b32_e64 v139, v139, v124, s[4:5]
	s_andn2_saveexec_b64 s[70:71], s[70:71]
	s_cbranch_execz .LBB0_512
	s_branch .LBB0_511

.LBB0_1114:
	s_setprio 1
	s_add_i32 vcc_hi, s66, 2
	s_add_u32 s28, s64, 0x80
	s_addc_u32 s29, s65, 0
	s_add_i32 s88, 0, 0x10000
	v_add_u32_e32 v140, s88, v194
	ds_read_b128 v[128:131], v140
	ds_read_b128 v[132:135], v140 offset:1024
	ds_read_b128 v[136:139], v140 offset:2048
	ds_read_b128 v[140:143], v140 offset:3072
	s_cmp_eq_u32 s85, s66
	s_cselect_b32 s66, s4, s28
	s_cselect_b32 s67, s5, s29
	s_cselect_b32 s69, s7, vcc_lo
	s_cselect_b32 s68, s6, s91
	v_lshl_add_u64 v[174:175], s[64:65], 0, v[158:159]
	s_add_i32 m0, s70, 0xc000
	ds_read_b128 v[144:147], v195
	ds_read_b128 v[162:165], v195 offset:2048
	ds_read_b128 v[170:173], v195 offset:4096
	ds_read_b128 v[196:199], v195 offset:6144
	ds_read_b128 v[148:151], v195 offset:1024
	ds_read_b128 v[166:169], v195 offset:3072
	ds_read_b128 v[188:191], v195 offset:5120
	ds_read_b128 v[200:203], v195 offset:7168
	global_load_lds_dwordx4 v[174:175], off
	v_lshl_add_u64 v[174:175], s[64:65], 0, v[160:161]
	s_add_i32 m0, s70, 0xe000
	s_nop 0
	global_load_lds_dwordx4 v[174:175], off
	s_waitcnt lgkmcnt(8)
	s_barrier
	s_setprio 0
	s_waitcnt lgkmcnt(7)
	v_mfma_f32_16x16x32_bf16 v[124:127], v[128:131], v[144:147], v[124:127]
	v_mfma_f32_16x16x32_bf16 v[120:123], v[136:139], v[144:147], v[120:123]
	s_waitcnt lgkmcnt(6)
	v_mfma_f32_16x16x32_bf16 v[108:111], v[128:131], v[162:165], v[108:111]
	v_mfma_f32_16x16x32_bf16 v[104:107], v[136:139], v[162:165], v[104:107]
	s_waitcnt lgkmcnt(5)
	v_mfma_f32_16x16x32_bf16 v[92:95], v[128:131], v[170:173], v[92:95]
	v_mfma_f32_16x16x32_bf16 v[88:91], v[136:139], v[170:173], v[88:91]
	s_waitcnt lgkmcnt(4)
	v_mfma_f32_16x16x32_bf16 v[76:79], v[128:131], v[196:199], v[76:79]
	v_mfma_f32_16x16x32_bf16 v[72:75], v[136:139], v[196:199], v[72:75]
	s_waitcnt lgkmcnt(3)
	v_mfma_f32_16x16x32_bf16 v[124:127], v[132:135], v[148:151], v[124:127]
	v_mfma_f32_16x16x32_bf16 v[120:123], v[140:143], v[148:151], v[120:123]
	s_waitcnt lgkmcnt(2)
	v_mfma_f32_16x16x32_bf16 v[108:111], v[132:135], v[166:169], v[108:111]
	v_mfma_f32_16x16x32_bf16 v[104:107], v[140:143], v[166:169], v[104:107]
	s_waitcnt lgkmcnt(1)
	v_mfma_f32_16x16x32_bf16 v[92:95], v[132:135], v[188:191], v[92:95]
	v_mfma_f32_16x16x32_bf16 v[88:91], v[140:143], v[188:191], v[88:91]
	s_waitcnt lgkmcnt(0)
	v_mfma_f32_16x16x32_bf16 v[76:79], v[132:135], v[200:203], v[76:79]
	v_mfma_f32_16x16x32_bf16 v[72:75], v[140:143], v[200:203], v[72:75]
	s_barrier
	s_setprio 1
	s_add_i32 s28, 0, 0x14000
	v_add_u32_e32 v174, s28, v194
	s_add_i32 s29, s88, s47
	ds_read_b128 v[204:207], v174
	ds_read_b128 v[208:211], v174 offset:1024
	ds_read_b128 v[212:215], v174 offset:2048
	ds_read_b128 v[232:235], v174 offset:3072
	v_lshl_add_u64 v[174:175], s[68:69], 0, v[176:177]
	s_mov_b32 m0, s29
	v_lshl_add_u64 v[216:217], s[68:69], 0, v[156:157]
	global_load_lds_dwordx4 v[174:175], off
	s_add_i32 m0, s29, 0x2000
	s_nop 0
	global_load_lds_dwordx4 v[216:217], off
	s_barrier
	s_setprio 0
	s_waitcnt lgkmcnt(3)
	v_mfma_f32_16x16x32_bf16 v[116:119], v[204:207], v[144:147], v[116:119]
	s_waitcnt lgkmcnt(1)
	v_mfma_f32_16x16x32_bf16 v[112:115], v[212:215], v[144:147], v[112:115]
	v_mfma_f32_16x16x32_bf16 v[100:103], v[204:207], v[162:165], v[100:103]
	v_mfma_f32_16x16x32_bf16 v[96:99], v[212:215], v[162:165], v[96:99]
	v_mfma_f32_16x16x32_bf16 v[84:87], v[204:207], v[170:173], v[84:87]
	v_mfma_f32_16x16x32_bf16 v[80:83], v[212:215], v[170:173], v[80:83]
	v_mfma_f32_16x16x32_bf16 v[68:71], v[204:207], v[196:199], v[68:71]
	v_mfma_f32_16x16x32_bf16 v[64:67], v[212:215], v[196:199], v[64:67]
	v_mfma_f32_16x16x32_bf16 v[116:119], v[208:211], v[148:151], v[116:119]
	s_waitcnt lgkmcnt(0)
	v_mfma_f32_16x16x32_bf16 v[112:115], v[232:235], v[148:151], v[112:115]
	v_mfma_f32_16x16x32_bf16 v[100:103], v[208:211], v[166:169], v[100:103]
	v_mfma_f32_16x16x32_bf16 v[96:99], v[232:235], v[166:169], v[96:99]
	v_mfma_f32_16x16x32_bf16 v[84:87], v[208:211], v[188:191], v[84:87]
	v_mfma_f32_16x16x32_bf16 v[80:83], v[232:235], v[188:191], v[80:83]
	v_mfma_f32_16x16x32_bf16 v[68:71], v[208:211], v[200:203], v[68:71]
	v_mfma_f32_16x16x32_bf16 v[64:67], v[232:235], v[200:203], v[64:67]
	s_mov_b32 m0, s70
	v_lshl_add_u64 v[236:237], s[66:67], 0, v[152:153]
	s_barrier
	s_setprio 1
	ds_read_b128 v[144:147], v195 offset:16384
	ds_read_b128 v[162:165], v195 offset:18432
	ds_read_b128 v[170:173], v195 offset:20480
	ds_read_b128 v[196:199], v195 offset:22528
	ds_read_b128 v[148:151], v195 offset:17408
	ds_read_b128 v[166:169], v195 offset:19456
	ds_read_b128 v[188:191], v195 offset:21504
	ds_read_b128 v[200:203], v195 offset:23552
	global_load_lds_dwordx4 v[236:237], off
	v_lshl_add_u64 v[238:239], s[66:67], 0, v[154:155]
	s_mov_b32 m0, s71
	s_nop 0
	global_load_lds_dwordx4 v[238:239], off
	s_barrier
	s_setprio 0
	s_waitcnt lgkmcnt(7)
	v_mfma_f32_16x16x32_bf16 v[60:63], v[128:131], v[144:147], v[60:63]
	v_mfma_f32_16x16x32_bf16 v[56:59], v[136:139], v[144:147], v[56:59]
	s_waitcnt lgkmcnt(6)
	v_mfma_f32_16x16x32_bf16 v[44:47], v[128:131], v[162:165], v[44:47]
	v_mfma_f32_16x16x32_bf16 v[40:43], v[136:139], v[162:165], v[40:43]
	s_waitcnt lgkmcnt(5)
	v_mfma_f32_16x16x32_bf16 v[28:31], v[128:131], v[170:173], v[28:31]
	v_mfma_f32_16x16x32_bf16 v[24:27], v[136:139], v[170:173], v[24:27]
	s_waitcnt lgkmcnt(4)
	v_mfma_f32_16x16x32_bf16 v[12:15], v[128:131], v[196:199], v[12:15]
	v_mfma_f32_16x16x32_bf16 v[8:11], v[136:139], v[196:199], v[8:11]
	s_waitcnt lgkmcnt(3)
	v_mfma_f32_16x16x32_bf16 v[60:63], v[132:135], v[148:151], v[60:63]
	v_mfma_f32_16x16x32_bf16 v[56:59], v[140:143], v[148:151], v[56:59]
	s_waitcnt lgkmcnt(2)
	v_mfma_f32_16x16x32_bf16 v[44:47], v[132:135], v[166:169], v[44:47]
	v_mfma_f32_16x16x32_bf16 v[40:43], v[140:143], v[166:169], v[40:43]
	s_waitcnt lgkmcnt(1)
	v_mfma_f32_16x16x32_bf16 v[28:31], v[132:135], v[188:191], v[28:31]
	v_mfma_f32_16x16x32_bf16 v[24:27], v[140:143], v[188:191], v[24:27]
	s_waitcnt lgkmcnt(0)
	v_mfma_f32_16x16x32_bf16 v[12:15], v[132:135], v[200:203], v[12:15]
	v_mfma_f32_16x16x32_bf16 v[8:11], v[140:143], v[200:203], v[8:11]
	s_barrier
	s_setprio 1
	s_add_u32 s68, s68, s58
	s_addc_u32 s69, s69, 0
	s_add_i32 s28, s28, s47
	v_lshl_add_u64 v[240:241], s[68:69], 0, v[176:177]
	s_mov_b32 m0, s28
	v_lshl_add_u64 v[242:243], s[68:69], 0, v[156:157]
	global_load_lds_dwordx4 v[240:241], off
	s_add_i32 m0, s28, 0x2000
	s_nop 0
	global_load_lds_dwordx4 v[242:243], off
	s_waitcnt vmcnt(6)
	s_barrier
	s_setprio 0
	v_mfma_f32_16x16x32_bf16 v[52:55], v[204:207], v[144:147], v[52:55]
	v_mfma_f32_16x16x32_bf16 v[48:51], v[212:215], v[144:147], v[48:51]
	v_mfma_f32_16x16x32_bf16 v[36:39], v[204:207], v[162:165], v[36:39]
	v_mfma_f32_16x16x32_bf16 v[32:35], v[212:215], v[162:165], v[32:35]
	v_mfma_f32_16x16x32_bf16 v[20:23], v[204:207], v[170:173], v[20:23]
	v_mfma_f32_16x16x32_bf16 v[16:19], v[212:215], v[170:173], v[16:19]
	v_mfma_f32_16x16x32_bf16 v[4:7], v[204:207], v[196:199], v[4:7]
	v_mfma_f32_16x16x32_bf16 v[0:3], v[212:215], v[196:199], v[0:3]
	v_mfma_f32_16x16x32_bf16 v[52:55], v[208:211], v[148:151], v[52:55]
	v_mfma_f32_16x16x32_bf16 v[48:51], v[232:235], v[148:151], v[48:51]
	v_mfma_f32_16x16x32_bf16 v[36:39], v[208:211], v[166:169], v[36:39]
	v_mfma_f32_16x16x32_bf16 v[32:35], v[232:235], v[166:169], v[32:35]
	v_mfma_f32_16x16x32_bf16 v[20:23], v[208:211], v[188:191], v[20:23]
	v_mfma_f32_16x16x32_bf16 v[16:19], v[232:235], v[188:191], v[16:19]
	v_mfma_f32_16x16x32_bf16 v[4:7], v[208:211], v[200:203], v[4:7]
	v_mfma_f32_16x16x32_bf16 v[0:3], v[232:235], v[200:203], v[0:3]
	s_add_i32 s28, 0, 0x18000
	v_add_u32_e32 v140, s28, v194
	s_barrier
	s_setprio 1
	ds_read_b128 v[128:131], v140
	ds_read_b128 v[132:135], v140 offset:1024
	ds_read_b128 v[136:139], v140 offset:2048
	ds_read_b128 v[140:143], v140 offset:3072
	s_add_u32 s66, s66, s58
	s_addc_u32 s67, s67, 0
	s_mov_b32 m0, s72
	v_lshl_add_u64 v[204:205], s[66:67], 0, v[152:153]
	ds_read_b128 v[144:147], v195 offset:32768
	ds_read_b128 v[162:165], v195 offset:34816
	ds_read_b128 v[170:173], v195 offset:36864
	ds_read_b128 v[196:199], v195 offset:38912
	ds_read_b128 v[148:151], v195 offset:33792
	ds_read_b128 v[166:169], v195 offset:35840
	ds_read_b128 v[188:191], v195 offset:37888
	ds_read_b128 v[200:203], v195 offset:39936
	global_load_lds_dwordx4 v[204:205], off
	v_lshl_add_u64 v[204:205], s[66:67], 0, v[154:155]
	s_mov_b32 m0, s73
	s_nop 0
	global_load_lds_dwordx4 v[204:205], off
	s_waitcnt lgkmcnt(8)
	s_barrier
	s_setprio 0
	s_waitcnt lgkmcnt(7)
	v_mfma_f32_16x16x32_bf16 v[124:127], v[128:131], v[144:147], v[124:127]
	v_mfma_f32_16x16x32_bf16 v[120:123], v[136:139], v[144:147], v[120:123]
	s_waitcnt lgkmcnt(6)
	v_mfma_f32_16x16x32_bf16 v[108:111], v[128:131], v[162:165], v[108:111]
	v_mfma_f32_16x16x32_bf16 v[104:107], v[136:139], v[162:165], v[104:107]
	s_waitcnt lgkmcnt(5)
	v_mfma_f32_16x16x32_bf16 v[92:95], v[128:131], v[170:173], v[92:95]
	v_mfma_f32_16x16x32_bf16 v[88:91], v[136:139], v[170:173], v[88:91]
	s_waitcnt lgkmcnt(4)
	v_mfma_f32_16x16x32_bf16 v[76:79], v[128:131], v[196:199], v[76:79]
	v_mfma_f32_16x16x32_bf16 v[72:75], v[136:139], v[196:199], v[72:75]
	s_waitcnt lgkmcnt(3)
	v_mfma_f32_16x16x32_bf16 v[124:127], v[132:135], v[148:151], v[124:127]
	v_mfma_f32_16x16x32_bf16 v[120:123], v[140:143], v[148:151], v[120:123]
	s_waitcnt lgkmcnt(2)
	v_mfma_f32_16x16x32_bf16 v[108:111], v[132:135], v[166:169], v[108:111]
	v_mfma_f32_16x16x32_bf16 v[104:107], v[140:143], v[166:169], v[104:107]
	s_waitcnt lgkmcnt(1)
	v_mfma_f32_16x16x32_bf16 v[92:95], v[132:135], v[188:191], v[92:95]
	v_mfma_f32_16x16x32_bf16 v[88:91], v[140:143], v[188:191], v[88:91]
	s_waitcnt lgkmcnt(0)
	v_mfma_f32_16x16x32_bf16 v[76:79], v[132:135], v[200:203], v[76:79]
	v_mfma_f32_16x16x32_bf16 v[72:75], v[140:143], v[200:203], v[72:75]
	s_barrier
	s_setprio 1
	s_add_i32 s29, 0, 0x1c000
	s_add_i32 s28, s28, s47
	v_add_u32_e32 v232, s29, v194
	v_lshl_add_u64 v[174:175], v[174:175], 0, s[40:41]
	s_mov_b32 m0, s28
	ds_read_b128 v[204:207], v232
	ds_read_b128 v[208:211], v232 offset:1024
	ds_read_b128 v[212:215], v232 offset:2048
	ds_read_b128 v[232:235], v232 offset:3072
	global_load_lds_dwordx4 v[174:175], off
	v_lshl_add_u64 v[174:175], v[216:217], 0, s[40:41]
	s_add_i32 m0, s28, 0x2000
	s_nop 0
	global_load_lds_dwordx4 v[174:175], off
	s_barrier
	s_setprio 0
	s_waitcnt lgkmcnt(3)
	v_mfma_f32_16x16x32_bf16 v[116:119], v[204:207], v[144:147], v[116:119]
	s_waitcnt lgkmcnt(1)
	v_mfma_f32_16x16x32_bf16 v[112:115], v[212:215], v[144:147], v[112:115]
	v_mfma_f32_16x16x32_bf16 v[100:103], v[204:207], v[162:165], v[100:103]
	v_mfma_f32_16x16x32_bf16 v[96:99], v[212:215], v[162:165], v[96:99]
	v_mfma_f32_16x16x32_bf16 v[84:87], v[204:207], v[170:173], v[84:87]
	v_mfma_f32_16x16x32_bf16 v[80:83], v[212:215], v[170:173], v[80:83]
	v_mfma_f32_16x16x32_bf16 v[68:71], v[204:207], v[196:199], v[68:71]
	v_mfma_f32_16x16x32_bf16 v[64:67], v[212:215], v[196:199], v[64:67]
	v_mfma_f32_16x16x32_bf16 v[116:119], v[208:211], v[148:151], v[116:119]
	s_waitcnt lgkmcnt(0)
	v_mfma_f32_16x16x32_bf16 v[112:115], v[232:235], v[148:151], v[112:115]
	v_mfma_f32_16x16x32_bf16 v[100:103], v[208:211], v[166:169], v[100:103]
	v_mfma_f32_16x16x32_bf16 v[96:99], v[232:235], v[166:169], v[96:99]
	v_mfma_f32_16x16x32_bf16 v[84:87], v[208:211], v[188:191], v[84:87]
	v_mfma_f32_16x16x32_bf16 v[80:83], v[232:235], v[188:191], v[80:83]
	v_mfma_f32_16x16x32_bf16 v[68:71], v[208:211], v[200:203], v[68:71]
	v_mfma_f32_16x16x32_bf16 v[64:67], v[232:235], v[200:203], v[64:67]
	s_mov_b32 m0, s74
	v_lshl_add_u64 v[174:175], v[236:237], 0, s[40:41]
	s_barrier
	s_setprio 1
	ds_read_b128 v[144:147], v195 offset:49152
	ds_read_b128 v[162:165], v195 offset:51200
	ds_read_b128 v[170:173], v195 offset:53248
	ds_read_b128 v[196:199], v195 offset:55296
	ds_read_b128 v[148:151], v195 offset:50176
	ds_read_b128 v[166:169], v195 offset:52224
	ds_read_b128 v[188:191], v195 offset:54272
	ds_read_b128 v[200:203], v195 offset:56320
	global_load_lds_dwordx4 v[174:175], off
	v_lshl_add_u64 v[174:175], v[238:239], 0, s[40:41]
	s_mov_b32 m0, s75
	s_nop 0
	global_load_lds_dwordx4 v[174:175], off
	s_barrier
	s_setprio 0
	s_waitcnt lgkmcnt(7)
	v_mfma_f32_16x16x32_bf16 v[60:63], v[128:131], v[144:147], v[60:63]
	v_mfma_f32_16x16x32_bf16 v[56:59], v[136:139], v[144:147], v[56:59]
	s_waitcnt lgkmcnt(6)
	v_mfma_f32_16x16x32_bf16 v[44:47], v[128:131], v[162:165], v[44:47]
	v_mfma_f32_16x16x32_bf16 v[40:43], v[136:139], v[162:165], v[40:43]
	s_waitcnt lgkmcnt(5)
	v_mfma_f32_16x16x32_bf16 v[28:31], v[128:131], v[170:173], v[28:31]
	v_mfma_f32_16x16x32_bf16 v[24:27], v[136:139], v[170:173], v[24:27]
	s_waitcnt lgkmcnt(4)
	v_mfma_f32_16x16x32_bf16 v[12:15], v[128:131], v[196:199], v[12:15]
	v_mfma_f32_16x16x32_bf16 v[8:11], v[136:139], v[196:199], v[8:11]
	s_waitcnt lgkmcnt(3)
	v_mfma_f32_16x16x32_bf16 v[60:63], v[132:135], v[148:151], v[60:63]
	v_mfma_f32_16x16x32_bf16 v[56:59], v[140:143], v[148:151], v[56:59]
	s_waitcnt lgkmcnt(2)
	v_mfma_f32_16x16x32_bf16 v[44:47], v[132:135], v[166:169], v[44:47]
	v_mfma_f32_16x16x32_bf16 v[40:43], v[140:143], v[166:169], v[40:43]
	s_waitcnt lgkmcnt(1)
	v_mfma_f32_16x16x32_bf16 v[28:31], v[132:135], v[188:191], v[28:31]
	v_mfma_f32_16x16x32_bf16 v[24:27], v[140:143], v[188:191], v[24:27]
	s_waitcnt lgkmcnt(0)
	v_mfma_f32_16x16x32_bf16 v[12:15], v[132:135], v[200:203], v[12:15]
	v_mfma_f32_16x16x32_bf16 v[8:11], v[140:143], v[200:203], v[8:11]
	s_barrier
	s_setprio 1
	s_add_i32 s28, s29, s47
	v_lshl_add_u64 v[128:129], v[240:241], 0, s[40:41]
	s_mov_b32 m0, s28
	s_nop 0
	global_load_lds_dwordx4 v[128:129], off
	v_lshl_add_u64 v[128:129], v[242:243], 0, s[40:41]
	s_add_i32 m0, s28, 0x2000
	s_nop 0
	global_load_lds_dwordx4 v[128:129], off
	s_waitcnt vmcnt(6)
	s_barrier
	s_setprio 0
	v_mfma_f32_16x16x32_bf16 v[52:55], v[204:207], v[144:147], v[52:55]
	v_mfma_f32_16x16x32_bf16 v[48:51], v[212:215], v[144:147], v[48:51]
	v_mfma_f32_16x16x32_bf16 v[36:39], v[204:207], v[162:165], v[36:39]
	v_mfma_f32_16x16x32_bf16 v[32:35], v[212:215], v[162:165], v[32:35]
	v_mfma_f32_16x16x32_bf16 v[20:23], v[204:207], v[170:173], v[20:23]
	v_mfma_f32_16x16x32_bf16 v[16:19], v[212:215], v[170:173], v[16:19]
	v_mfma_f32_16x16x32_bf16 v[4:7], v[204:207], v[196:199], v[4:7]
	v_mfma_f32_16x16x32_bf16 v[0:3], v[212:215], v[196:199], v[0:3]
	v_mfma_f32_16x16x32_bf16 v[52:55], v[208:211], v[148:151], v[52:55]
	v_mfma_f32_16x16x32_bf16 v[48:51], v[232:235], v[148:151], v[48:51]
	v_mfma_f32_16x16x32_bf16 v[36:39], v[208:211], v[166:169], v[36:39]
	v_mfma_f32_16x16x32_bf16 v[32:35], v[232:235], v[166:169], v[32:35]
	v_mfma_f32_16x16x32_bf16 v[20:23], v[208:211], v[188:191], v[20:23]
	v_mfma_f32_16x16x32_bf16 v[16:19], v[232:235], v[188:191], v[16:19]
	v_mfma_f32_16x16x32_bf16 v[4:7], v[208:211], v[200:203], v[4:7]
	v_mfma_f32_16x16x32_bf16 v[0:3], v[232:235], v[200:203], v[0:3]
	s_add_u32 s64, s64, 0x100
	s_addc_u32 s65, s65, 0
	s_add_u32 s91, s91, 0x100
	s_addc_u32 vcc_lo, vcc_lo, 0
	s_cmp_lt_i32 vcc_hi, s76
	s_mov_b32 s66, vcc_hi
	s_barrier
	s_cbranch_scc1 .LBB0_1114
	s_lshl_b32 s28, s84, 8
	v_mov_b32_e32 v128, v193
	v_mov_b32_e32 v129, v192
	s_add_i32 s28, s28, s78
	s_lshl_b32 s64, s24, 2
	v_add_u32_e32 v166, s28, v129
	s_lshl_b32 s28, s24, 8
	s_or_b32 s28, s28, s79
	v_lshl_add_u32 v162, v128, 3, s28
	v_ashrrev_i32_e32 v163, 31, v162
	v_lshlrev_b64 v[204:205], 1, v[162:163]
	v_ashrrev_i32_e32 v167, 31, v166
	v_lshl_add_u64 v[164:165], s[12:13], 0, v[204:205]
	v_lshlrev_b64 v[206:207], 11, v[166:167]
	v_cmp_eq_u32_e32 vcc, 0, v128
	v_lshl_add_u64 v[128:129], v[164:165], 0, v[206:207]
	global_load_dwordx4 v[196:199], v[128:129], off
	global_load_dwordx4 v[200:203], v[128:129], off offset:256
	v_add_u32_e32 v188, 16, v166
	v_ashrrev_i32_e32 v189, 31, v188
	v_add_u32_e32 v172, 32, v166
	v_lshlrev_b64 v[190:191], 11, v[188:189]
	v_ashrrev_i32_e32 v173, 31, v172
	v_add_u32_e32 v168, 48, v166
	v_lshl_add_u64 v[128:129], v[164:165], 0, v[190:191]
	v_lshlrev_b64 v[174:175], 11, v[172:173]
	v_ashrrev_i32_e32 v169, 31, v168
	global_load_dwordx4 v[148:151], v[128:129], off
	global_load_dwordx4 v[144:147], v[128:129], off offset:256
	v_lshl_add_u64 v[128:129], v[164:165], 0, v[174:175]
	v_lshlrev_b64 v[170:171], 11, v[168:169]
	global_load_dwordx4 v[140:143], v[128:129], off
	global_load_dwordx4 v[136:139], v[128:129], off offset:256
	v_lshl_add_u64 v[128:129], v[164:165], 0, v[170:171]
	global_load_dwordx4 v[132:135], v[128:129], off
	s_nop 0
	global_load_dwordx4 v[128:131], v[128:129], off offset:256
	v_lshl_add_u64 v[206:207], s[12:13], 0, v[206:207]
	v_lshl_add_u64 v[204:205], v[206:207], 0, v[204:205]
	s_ashr_i32 s65, s64, 31
	s_waitcnt vmcnt(0)
	v_lshlrev_b32_e32 v208, 16, v196
	v_and_b32_e32 v209, 0xffff0000, v196
	v_lshlrev_b32_e32 v196, 16, v197
	v_and_b32_e32 v197, 0xffff0000, v197
	v_lshlrev_b32_e32 v210, 16, v198
	v_and_b32_e32 v211, 0xffff0000, v198
	v_lshlrev_b32_e32 v198, 16, v199
	v_and_b32_e32 v199, 0xffff0000, v199
	v_pk_fma_f32 v[126:127], s[62:63], v[126:127], v[196:197]
	v_pk_fma_f32 v[124:125], s[10:11], v[124:125], v[208:209]
	v_pk_fma_f32 v[196:197], s[62:63], v[122:123], v[198:199]
	v_pk_fma_f32 v[198:199], s[10:11], v[120:121], v[210:211]
	v_cvt_pk_bf16_f32 v120, v124, v125
	v_cvt_pk_bf16_f32 v121, v126, v127
	s_nop 0
	v_cvt_pk_bf16_f32 v122, v198, v199
	v_cvt_pk_bf16_f32 v123, v196, v197
	global_store_dwordx4 v[204:205], v[120:123], off
	s_nop 1
	v_pk_mul_f32 v[120:121], v[198:199], v[198:199]
	v_pk_mul_f32 v[122:123], v[196:197], v[196:197]
	v_pk_fma_f32 v[120:121], v[124:125], v[124:125], v[120:121]
	v_pk_fma_f32 v[122:123], v[126:127], v[126:127], v[122:123]
	v_add_f32_e32 v120, v120, v121
	v_add_f32_e32 v121, v122, v123
	v_add_f32_e32 v196, v120, v121
	v_lshlrev_b32_e32 v120, 16, v200
	v_and_b32_e32 v121, 0xffff0000, v200
	v_lshlrev_b32_e32 v122, 16, v201
	v_and_b32_e32 v123, 0xffff0000, v201
	v_lshlrev_b32_e32 v124, 16, v202
	v_and_b32_e32 v125, 0xffff0000, v202
	v_lshlrev_b32_e32 v126, 16, v203
	v_and_b32_e32 v127, 0xffff0000, v203
	v_pk_fma_f32 v[118:119], s[62:63], v[118:119], v[122:123]
	v_pk_fma_f32 v[116:117], s[10:11], v[116:117], v[120:121]
	v_pk_fma_f32 v[120:121], s[62:63], v[114:115], v[126:127]
	v_pk_fma_f32 v[122:123], s[10:11], v[112:113], v[124:125]
	v_cvt_pk_bf16_f32 v112, v116, v117
	v_cvt_pk_bf16_f32 v113, v118, v119
	s_nop 0
	v_cvt_pk_bf16_f32 v114, v122, v123
	v_cvt_pk_bf16_f32 v115, v120, v121
	global_store_dwordx4 v[204:205], v[112:115], off offset:256
	s_nop 1
	v_pk_mul_f32 v[112:113], v[122:123], v[122:123]
	v_pk_mul_f32 v[114:115], v[120:121], v[120:121]
	v_pk_fma_f32 v[112:113], v[116:117], v[116:117], v[112:113]
	v_pk_fma_f32 v[114:115], v[118:119], v[118:119], v[114:115]
	v_add_f32_e32 v112, v112, v113
	v_add_f32_e32 v113, v114, v115
	v_add_f32_e32 v112, v112, v113
	v_add_f32_e32 v112, v196, v112
	ds_bpermute_b32 v113, v219, v112
	s_waitcnt lgkmcnt(0)
	v_add_f32_e32 v112, v112, v113
	ds_bpermute_b32 v113, v218, v112
	s_and_saveexec_b64 s[66:67], vcc
	s_cbranch_execz .LBB0_1117
	v_lshlrev_b64 v[114:115], 6, v[166:167]
	v_lshl_add_u64 v[114:115], s[8:9], 0, v[114:115]
	v_lshl_add_u64 v[114:115], s[64:65], 2, v[114:115]
	s_lshl_b32 s24, s77, 2
	v_lshl_add_u64 v[114:115], v[114:115], 0, s[24:25]
	s_waitcnt lgkmcnt(0)
	v_add_f32_e32 v112, v112, v113
	global_store_dword v[114:115], v112, off

.LBB0_1282:
	s_setprio 1
	s_add_i32 s81, s60, 2
	s_add_u32 s28, s58, 0x80
	s_addc_u32 s29, s59, 0
	s_add_i32 s82, 0, 0x10000
	v_add_u32_e32 v140, s82, v195
	ds_read_b128 v[128:131], v140
	ds_read_b128 v[132:135], v140 offset:1024
	ds_read_b128 v[136:139], v140 offset:2048
	ds_read_b128 v[140:143], v140 offset:3072
	s_cmp_eq_u32 s5, s60
	s_cselect_b32 s60, s56, s28
	s_cselect_b32 s61, s57, s29
	s_cselect_b32 s63, s3, s80
	s_cselect_b32 s62, s2, s21
	v_lshl_add_u64 v[174:175], s[58:59], 0, v[158:159]
	s_add_i32 m0, s66, 0xc000
	ds_read_b128 v[144:147], v196
	ds_read_b128 v[162:165], v196 offset:2048
	ds_read_b128 v[170:173], v196 offset:4096
	ds_read_b128 v[198:201], v196 offset:6144
	ds_read_b128 v[148:151], v196 offset:1024
	ds_read_b128 v[166:169], v196 offset:3072
	ds_read_b128 v[188:191], v196 offset:5120
	ds_read_b128 v[202:205], v196 offset:7168
	global_load_lds_dwordx4 v[174:175], off
	v_lshl_add_u64 v[174:175], s[58:59], 0, v[160:161]
	s_add_i32 m0, s66, 0xe000
	s_nop 0
	global_load_lds_dwordx4 v[174:175], off
	s_waitcnt lgkmcnt(8)
	s_barrier
	s_setprio 0
	s_waitcnt lgkmcnt(7)
	v_mfma_f32_16x16x32_bf16 v[124:127], v[128:131], v[144:147], v[124:127]
	v_mfma_f32_16x16x32_bf16 v[120:123], v[136:139], v[144:147], v[120:123]
	s_waitcnt lgkmcnt(6)
	v_mfma_f32_16x16x32_bf16 v[108:111], v[128:131], v[162:165], v[108:111]
	v_mfma_f32_16x16x32_bf16 v[104:107], v[136:139], v[162:165], v[104:107]
	s_waitcnt lgkmcnt(5)
	v_mfma_f32_16x16x32_bf16 v[92:95], v[128:131], v[170:173], v[92:95]
	v_mfma_f32_16x16x32_bf16 v[88:91], v[136:139], v[170:173], v[88:91]
	s_waitcnt lgkmcnt(4)
	v_mfma_f32_16x16x32_bf16 v[76:79], v[128:131], v[198:201], v[76:79]
	v_mfma_f32_16x16x32_bf16 v[72:75], v[136:139], v[198:201], v[72:75]
	s_waitcnt lgkmcnt(3)
	v_mfma_f32_16x16x32_bf16 v[124:127], v[132:135], v[148:151], v[124:127]
	v_mfma_f32_16x16x32_bf16 v[120:123], v[140:143], v[148:151], v[120:123]
	s_waitcnt lgkmcnt(2)
	v_mfma_f32_16x16x32_bf16 v[108:111], v[132:135], v[166:169], v[108:111]
	v_mfma_f32_16x16x32_bf16 v[104:107], v[140:143], v[166:169], v[104:107]
	s_waitcnt lgkmcnt(1)
	v_mfma_f32_16x16x32_bf16 v[92:95], v[132:135], v[188:191], v[92:95]
	v_mfma_f32_16x16x32_bf16 v[88:91], v[140:143], v[188:191], v[88:91]
	s_waitcnt lgkmcnt(0)
	v_mfma_f32_16x16x32_bf16 v[76:79], v[132:135], v[202:205], v[76:79]
	v_mfma_f32_16x16x32_bf16 v[72:75], v[140:143], v[202:205], v[72:75]
	s_barrier
	s_setprio 1
	s_add_i32 s28, 0, 0x14000
	v_add_u32_e32 v174, s28, v195
	s_add_i32 s29, s82, s65
	ds_read_b128 v[206:209], v174
	ds_read_b128 v[210:213], v174 offset:1024
	ds_read_b128 v[214:217], v174 offset:2048
	ds_read_b128 v[232:235], v174 offset:3072
	v_lshl_add_u64 v[174:175], s[62:63], 0, v[176:177]
	s_mov_b32 m0, s29
	v_lshl_add_u64 v[236:237], s[62:63], 0, v[156:157]
	global_load_lds_dwordx4 v[174:175], off
	s_add_i32 m0, s29, 0x2000
	s_nop 0
	global_load_lds_dwordx4 v[236:237], off
	s_barrier
	s_setprio 0
	s_waitcnt lgkmcnt(3)
	v_mfma_f32_16x16x32_bf16 v[116:119], v[206:209], v[144:147], v[116:119]
	s_waitcnt lgkmcnt(1)
	v_mfma_f32_16x16x32_bf16 v[112:115], v[214:217], v[144:147], v[112:115]
	v_mfma_f32_16x16x32_bf16 v[100:103], v[206:209], v[162:165], v[100:103]
	v_mfma_f32_16x16x32_bf16 v[96:99], v[214:217], v[162:165], v[96:99]
	v_mfma_f32_16x16x32_bf16 v[84:87], v[206:209], v[170:173], v[84:87]
	v_mfma_f32_16x16x32_bf16 v[80:83], v[214:217], v[170:173], v[80:83]
	v_mfma_f32_16x16x32_bf16 v[68:71], v[206:209], v[198:201], v[68:71]
	v_mfma_f32_16x16x32_bf16 v[64:67], v[214:217], v[198:201], v[64:67]
	v_mfma_f32_16x16x32_bf16 v[116:119], v[210:213], v[148:151], v[116:119]
	s_waitcnt lgkmcnt(0)
	v_mfma_f32_16x16x32_bf16 v[112:115], v[232:235], v[148:151], v[112:115]
	v_mfma_f32_16x16x32_bf16 v[100:103], v[210:213], v[166:169], v[100:103]
	v_mfma_f32_16x16x32_bf16 v[96:99], v[232:235], v[166:169], v[96:99]
	v_mfma_f32_16x16x32_bf16 v[84:87], v[210:213], v[188:191], v[84:87]
	v_mfma_f32_16x16x32_bf16 v[80:83], v[232:235], v[188:191], v[80:83]
	v_mfma_f32_16x16x32_bf16 v[68:71], v[210:213], v[202:205], v[68:71]
	v_mfma_f32_16x16x32_bf16 v[64:67], v[232:235], v[202:205], v[64:67]
	s_mov_b32 m0, s66
	v_lshl_add_u64 v[238:239], s[60:61], 0, v[152:153]
	s_barrier
	s_setprio 1
	ds_read_b128 v[144:147], v196 offset:16384
	ds_read_b128 v[162:165], v196 offset:18432
	ds_read_b128 v[170:173], v196 offset:20480
	ds_read_b128 v[198:201], v196 offset:22528
	ds_read_b128 v[148:151], v196 offset:17408
	ds_read_b128 v[166:169], v196 offset:19456
	ds_read_b128 v[188:191], v196 offset:21504
	ds_read_b128 v[202:205], v196 offset:23552
	global_load_lds_dwordx4 v[238:239], off
	v_lshl_add_u64 v[240:241], s[60:61], 0, v[154:155]
	s_mov_b32 m0, s67
	s_nop 0
	global_load_lds_dwordx4 v[240:241], off
	s_barrier
	s_setprio 0
	s_waitcnt lgkmcnt(7)
	v_mfma_f32_16x16x32_bf16 v[60:63], v[128:131], v[144:147], v[60:63]
	v_mfma_f32_16x16x32_bf16 v[56:59], v[136:139], v[144:147], v[56:59]
	s_waitcnt lgkmcnt(6)
	v_mfma_f32_16x16x32_bf16 v[44:47], v[128:131], v[162:165], v[44:47]
	v_mfma_f32_16x16x32_bf16 v[40:43], v[136:139], v[162:165], v[40:43]
	s_waitcnt lgkmcnt(5)
	v_mfma_f32_16x16x32_bf16 v[28:31], v[128:131], v[170:173], v[28:31]
	v_mfma_f32_16x16x32_bf16 v[24:27], v[136:139], v[170:173], v[24:27]
	s_waitcnt lgkmcnt(4)
	v_mfma_f32_16x16x32_bf16 v[12:15], v[128:131], v[198:201], v[12:15]
	v_mfma_f32_16x16x32_bf16 v[8:11], v[136:139], v[198:201], v[8:11]
	s_waitcnt lgkmcnt(3)
	v_mfma_f32_16x16x32_bf16 v[60:63], v[132:135], v[148:151], v[60:63]
	v_mfma_f32_16x16x32_bf16 v[56:59], v[140:143], v[148:151], v[56:59]
	s_waitcnt lgkmcnt(2)
	v_mfma_f32_16x16x32_bf16 v[44:47], v[132:135], v[166:169], v[44:47]
	v_mfma_f32_16x16x32_bf16 v[40:43], v[140:143], v[166:169], v[40:43]
	s_waitcnt lgkmcnt(1)
	v_mfma_f32_16x16x32_bf16 v[28:31], v[132:135], v[188:191], v[28:31]
	v_mfma_f32_16x16x32_bf16 v[24:27], v[140:143], v[188:191], v[24:27]
	s_waitcnt lgkmcnt(0)
	v_mfma_f32_16x16x32_bf16 v[12:15], v[132:135], v[202:205], v[12:15]
	v_mfma_f32_16x16x32_bf16 v[8:11], v[140:143], v[202:205], v[8:11]
	s_barrier
	s_setprio 1
	s_add_u32 s62, s62, s4
	s_addc_u32 s63, s63, 0
	s_add_i32 s28, s28, s65
	v_lshl_add_u64 v[242:243], s[62:63], 0, v[176:177]
	s_mov_b32 m0, s28
	v_lshl_add_u64 v[244:245], s[62:63], 0, v[156:157]
	global_load_lds_dwordx4 v[242:243], off
	s_add_i32 m0, s28, 0x2000
	s_nop 0
	global_load_lds_dwordx4 v[244:245], off
	s_waitcnt vmcnt(6)
	s_barrier
	s_setprio 0
	v_mfma_f32_16x16x32_bf16 v[52:55], v[206:209], v[144:147], v[52:55]
	v_mfma_f32_16x16x32_bf16 v[48:51], v[214:217], v[144:147], v[48:51]
	v_mfma_f32_16x16x32_bf16 v[36:39], v[206:209], v[162:165], v[36:39]
	v_mfma_f32_16x16x32_bf16 v[32:35], v[214:217], v[162:165], v[32:35]
	v_mfma_f32_16x16x32_bf16 v[20:23], v[206:209], v[170:173], v[20:23]
	v_mfma_f32_16x16x32_bf16 v[16:19], v[214:217], v[170:173], v[16:19]
	v_mfma_f32_16x16x32_bf16 v[4:7], v[206:209], v[198:201], v[4:7]
	v_mfma_f32_16x16x32_bf16 v[0:3], v[214:217], v[198:201], v[0:3]
	v_mfma_f32_16x16x32_bf16 v[52:55], v[210:213], v[148:151], v[52:55]
	v_mfma_f32_16x16x32_bf16 v[48:51], v[232:235], v[148:151], v[48:51]
	v_mfma_f32_16x16x32_bf16 v[36:39], v[210:213], v[166:169], v[36:39]
	v_mfma_f32_16x16x32_bf16 v[32:35], v[232:235], v[166:169], v[32:35]
	v_mfma_f32_16x16x32_bf16 v[20:23], v[210:213], v[188:191], v[20:23]
	v_mfma_f32_16x16x32_bf16 v[16:19], v[232:235], v[188:191], v[16:19]
	v_mfma_f32_16x16x32_bf16 v[4:7], v[210:213], v[202:205], v[4:7]
	v_mfma_f32_16x16x32_bf16 v[0:3], v[232:235], v[202:205], v[0:3]
	s_add_i32 s28, 0, 0x18000
	v_add_u32_e32 v140, s28, v195
	s_barrier
	s_setprio 1
	ds_read_b128 v[128:131], v140
	ds_read_b128 v[132:135], v140 offset:1024
	ds_read_b128 v[136:139], v140 offset:2048
	ds_read_b128 v[140:143], v140 offset:3072
	s_add_u32 s60, s60, s4
	s_addc_u32 s61, s61, 0
	s_mov_b32 m0, s68
	v_lshl_add_u64 v[206:207], s[60:61], 0, v[152:153]
	ds_read_b128 v[144:147], v196 offset:32768
	ds_read_b128 v[162:165], v196 offset:34816
	ds_read_b128 v[170:173], v196 offset:36864
	ds_read_b128 v[198:201], v196 offset:38912
	ds_read_b128 v[148:151], v196 offset:33792
	ds_read_b128 v[166:169], v196 offset:35840
	ds_read_b128 v[188:191], v196 offset:37888
	ds_read_b128 v[202:205], v196 offset:39936
	global_load_lds_dwordx4 v[206:207], off
	v_lshl_add_u64 v[206:207], s[60:61], 0, v[154:155]
	s_mov_b32 m0, s69
	s_nop 0
	global_load_lds_dwordx4 v[206:207], off
	s_waitcnt lgkmcnt(8)
	s_barrier
	s_setprio 0
	s_waitcnt lgkmcnt(7)
	v_mfma_f32_16x16x32_bf16 v[124:127], v[128:131], v[144:147], v[124:127]
	v_mfma_f32_16x16x32_bf16 v[120:123], v[136:139], v[144:147], v[120:123]
	s_waitcnt lgkmcnt(6)
	v_mfma_f32_16x16x32_bf16 v[108:111], v[128:131], v[162:165], v[108:111]
	v_mfma_f32_16x16x32_bf16 v[104:107], v[136:139], v[162:165], v[104:107]
	s_waitcnt lgkmcnt(5)
	v_mfma_f32_16x16x32_bf16 v[92:95], v[128:131], v[170:173], v[92:95]
	v_mfma_f32_16x16x32_bf16 v[88:91], v[136:139], v[170:173], v[88:91]
	s_waitcnt lgkmcnt(4)
	v_mfma_f32_16x16x32_bf16 v[76:79], v[128:131], v[198:201], v[76:79]
	v_mfma_f32_16x16x32_bf16 v[72:75], v[136:139], v[198:201], v[72:75]
	s_waitcnt lgkmcnt(3)
	v_mfma_f32_16x16x32_bf16 v[124:127], v[132:135], v[148:151], v[124:127]
	v_mfma_f32_16x16x32_bf16 v[120:123], v[140:143], v[148:151], v[120:123]
	s_waitcnt lgkmcnt(2)
	v_mfma_f32_16x16x32_bf16 v[108:111], v[132:135], v[166:169], v[108:111]
	v_mfma_f32_16x16x32_bf16 v[104:107], v[140:143], v[166:169], v[104:107]
	s_waitcnt lgkmcnt(1)
	v_mfma_f32_16x16x32_bf16 v[92:95], v[132:135], v[188:191], v[92:95]
	v_mfma_f32_16x16x32_bf16 v[88:91], v[140:143], v[188:191], v[88:91]
	s_waitcnt lgkmcnt(0)
	v_mfma_f32_16x16x32_bf16 v[76:79], v[132:135], v[202:205], v[76:79]
	v_mfma_f32_16x16x32_bf16 v[72:75], v[140:143], v[202:205], v[72:75]
	s_barrier
	s_setprio 1
	s_add_i32 s29, 0, 0x1c000
	s_add_i32 s28, s28, s65
	v_add_u32_e32 v197, s29, v195
	v_lshl_add_u64 v[174:175], v[174:175], 0, s[40:41]
	s_mov_b32 m0, s28
	ds_read_b128 v[206:209], v197
	ds_read_b128 v[210:213], v197 offset:1024
	ds_read_b128 v[214:217], v197 offset:2048
	ds_read_b128 v[232:235], v197 offset:3072
	global_load_lds_dwordx4 v[174:175], off
	v_lshl_add_u64 v[174:175], v[236:237], 0, s[40:41]
	s_add_i32 m0, s28, 0x2000
	s_nop 0
	global_load_lds_dwordx4 v[174:175], off
	s_barrier
	s_setprio 0
	s_waitcnt lgkmcnt(3)
	v_mfma_f32_16x16x32_bf16 v[116:119], v[206:209], v[144:147], v[116:119]
	s_waitcnt lgkmcnt(1)
	v_mfma_f32_16x16x32_bf16 v[112:115], v[214:217], v[144:147], v[112:115]
	v_mfma_f32_16x16x32_bf16 v[100:103], v[206:209], v[162:165], v[100:103]
	v_mfma_f32_16x16x32_bf16 v[96:99], v[214:217], v[162:165], v[96:99]
	v_mfma_f32_16x16x32_bf16 v[84:87], v[206:209], v[170:173], v[84:87]
	v_mfma_f32_16x16x32_bf16 v[80:83], v[214:217], v[170:173], v[80:83]
	v_mfma_f32_16x16x32_bf16 v[68:71], v[206:209], v[198:201], v[68:71]
	v_mfma_f32_16x16x32_bf16 v[64:67], v[214:217], v[198:201], v[64:67]
	v_mfma_f32_16x16x32_bf16 v[116:119], v[210:213], v[148:151], v[116:119]
	s_waitcnt lgkmcnt(0)
	v_mfma_f32_16x16x32_bf16 v[112:115], v[232:235], v[148:151], v[112:115]
	v_mfma_f32_16x16x32_bf16 v[100:103], v[210:213], v[166:169], v[100:103]
	v_mfma_f32_16x16x32_bf16 v[96:99], v[232:235], v[166:169], v[96:99]
	v_mfma_f32_16x16x32_bf16 v[84:87], v[210:213], v[188:191], v[84:87]
	v_mfma_f32_16x16x32_bf16 v[80:83], v[232:235], v[188:191], v[80:83]
	v_mfma_f32_16x16x32_bf16 v[68:71], v[210:213], v[202:205], v[68:71]
	v_mfma_f32_16x16x32_bf16 v[64:67], v[232:235], v[202:205], v[64:67]
	s_mov_b32 m0, s71
	v_lshl_add_u64 v[174:175], v[238:239], 0, s[40:41]
	s_barrier
	s_setprio 1
	ds_read_b128 v[144:147], v196 offset:49152
	ds_read_b128 v[162:165], v196 offset:51200
	ds_read_b128 v[170:173], v196 offset:53248
	ds_read_b128 v[198:201], v196 offset:55296
	ds_read_b128 v[148:151], v196 offset:50176
	ds_read_b128 v[166:169], v196 offset:52224
	ds_read_b128 v[188:191], v196 offset:54272
	ds_read_b128 v[202:205], v196 offset:56320
	global_load_lds_dwordx4 v[174:175], off
	v_lshl_add_u64 v[174:175], v[240:241], 0, s[40:41]
	s_mov_b32 m0, s72
	s_nop 0
	global_load_lds_dwordx4 v[174:175], off
	s_barrier
	s_setprio 0
	s_waitcnt lgkmcnt(7)
	v_mfma_f32_16x16x32_bf16 v[60:63], v[128:131], v[144:147], v[60:63]
	v_mfma_f32_16x16x32_bf16 v[56:59], v[136:139], v[144:147], v[56:59]
	s_waitcnt lgkmcnt(6)
	v_mfma_f32_16x16x32_bf16 v[44:47], v[128:131], v[162:165], v[44:47]
	v_mfma_f32_16x16x32_bf16 v[40:43], v[136:139], v[162:165], v[40:43]
	s_waitcnt lgkmcnt(5)
	v_mfma_f32_16x16x32_bf16 v[28:31], v[128:131], v[170:173], v[28:31]
	v_mfma_f32_16x16x32_bf16 v[24:27], v[136:139], v[170:173], v[24:27]
	s_waitcnt lgkmcnt(4)
	v_mfma_f32_16x16x32_bf16 v[12:15], v[128:131], v[198:201], v[12:15]
	v_mfma_f32_16x16x32_bf16 v[8:11], v[136:139], v[198:201], v[8:11]
	s_waitcnt lgkmcnt(3)
	v_mfma_f32_16x16x32_bf16 v[60:63], v[132:135], v[148:151], v[60:63]
	v_mfma_f32_16x16x32_bf16 v[56:59], v[140:143], v[148:151], v[56:59]
	s_waitcnt lgkmcnt(2)
	v_mfma_f32_16x16x32_bf16 v[44:47], v[132:135], v[166:169], v[44:47]
	v_mfma_f32_16x16x32_bf16 v[40:43], v[140:143], v[166:169], v[40:43]
	s_waitcnt lgkmcnt(1)
	v_mfma_f32_16x16x32_bf16 v[28:31], v[132:135], v[188:191], v[28:31]
	v_mfma_f32_16x16x32_bf16 v[24:27], v[140:143], v[188:191], v[24:27]
	s_waitcnt lgkmcnt(0)
	v_mfma_f32_16x16x32_bf16 v[12:15], v[132:135], v[202:205], v[12:15]
	v_mfma_f32_16x16x32_bf16 v[8:11], v[140:143], v[202:205], v[8:11]
	s_barrier
	s_setprio 1
	s_add_i32 s28, s29, s65
	v_lshl_add_u64 v[128:129], v[242:243], 0, s[40:41]
	s_mov_b32 m0, s28
	s_nop 0
	global_load_lds_dwordx4 v[128:129], off
	v_lshl_add_u64 v[128:129], v[244:245], 0, s[40:41]
	s_add_i32 m0, s28, 0x2000
	s_nop 0
	global_load_lds_dwordx4 v[128:129], off
	s_waitcnt vmcnt(6)
	s_barrier
	s_setprio 0
	v_mfma_f32_16x16x32_bf16 v[52:55], v[206:209], v[144:147], v[52:55]
	v_mfma_f32_16x16x32_bf16 v[48:51], v[214:217], v[144:147], v[48:51]
	v_mfma_f32_16x16x32_bf16 v[36:39], v[206:209], v[162:165], v[36:39]
	v_mfma_f32_16x16x32_bf16 v[32:35], v[214:217], v[162:165], v[32:35]
	v_mfma_f32_16x16x32_bf16 v[20:23], v[206:209], v[170:173], v[20:23]
	v_mfma_f32_16x16x32_bf16 v[16:19], v[214:217], v[170:173], v[16:19]
	v_mfma_f32_16x16x32_bf16 v[4:7], v[206:209], v[198:201], v[4:7]
	v_mfma_f32_16x16x32_bf16 v[0:3], v[214:217], v[198:201], v[0:3]
	v_mfma_f32_16x16x32_bf16 v[52:55], v[210:213], v[148:151], v[52:55]
	v_mfma_f32_16x16x32_bf16 v[48:51], v[232:235], v[148:151], v[48:51]
	v_mfma_f32_16x16x32_bf16 v[36:39], v[210:213], v[166:169], v[36:39]
	v_mfma_f32_16x16x32_bf16 v[32:35], v[232:235], v[166:169], v[32:35]
	v_mfma_f32_16x16x32_bf16 v[20:23], v[210:213], v[188:191], v[20:23]
	v_mfma_f32_16x16x32_bf16 v[16:19], v[232:235], v[188:191], v[16:19]
	v_mfma_f32_16x16x32_bf16 v[4:7], v[210:213], v[202:205], v[4:7]
	v_mfma_f32_16x16x32_bf16 v[0:3], v[232:235], v[202:205], v[0:3]
	s_add_u32 s58, s58, 0x100
	s_addc_u32 s59, s59, 0
	s_add_u32 s21, s21, 0x100
	s_addc_u32 s80, s80, 0
	s_cmp_ge_i32 s81, s79
	s_mov_b32 s60, s81
	s_barrier
	s_cbranch_scc0 .LBB0_1282
	s_cmp_gt_i32 s24, -1
	s_mov_b64 s[58:59], -1
	s_cbranch_scc0 .LBB0_1285
	s_lshl_b64 s[58:59], s[24:25], 17
	v_mov_b32_e32 v128, v231
	s_add_u32 s58, s37, s58
	s_addc_u32 s59, s46, s59
	v_ashrrev_i32_e32 v129, 31, v128
	v_lshl_add_u64 v[128:129], v[128:129], 4, s[58:59]
	v_add_co_u32_e32 v134, vcc, s36, v128
	v_cvt_pk_bf16_f32 v130, v124, v125
	v_cvt_pk_bf16_f32 v131, v126, v127
	v_cvt_pk_bf16_f32 v132, v120, v121
	v_cvt_pk_bf16_f32 v133, v122, v123
	s_nop 1
	v_addc_co_u32_e32 v135, vcc, 0, v129, vcc
	s_movk_i32 s5, 0x4000
	global_store_dwordx4 v[128:129], v[130:133], off
	s_mov_b64 s[58:59], 0
	s_nop 0
	v_cvt_pk_bf16_f32 v130, v108, v109
	v_cvt_pk_bf16_f32 v131, v110, v111
	v_cvt_pk_bf16_f32 v132, v104, v105
	v_cvt_pk_bf16_f32 v133, v106, v107
	global_store_dwordx4 v[134:135], v[130:133], off
	v_add_co_u32_e32 v134, vcc, s5, v128
	s_movk_i32 s5, 0x6000
	s_nop 0
	v_addc_co_u32_e32 v135, vcc, 0, v129, vcc
	v_cvt_pk_bf16_f32 v130, v92, v93
	v_cvt_pk_bf16_f32 v131, v94, v95
	v_cvt_pk_bf16_f32 v132, v88, v89
	v_cvt_pk_bf16_f32 v133, v90, v91
	global_store_dwordx4 v[134:135], v[130:133], off
	v_add_co_u32_e32 v134, vcc, s5, v128
	s_nop 0
	v_cvt_pk_bf16_f32 v130, v76, v77
	v_cvt_pk_bf16_f32 v131, v78, v79
	v_cvt_pk_bf16_f32 v132, v72, v73
	v_cvt_pk_bf16_f32 v133, v74, v75
	s_nop 0
	v_addc_co_u32_e32 v135, vcc, 0, v129, vcc
	global_store_dwordx4 v[134:135], v[130:133], off
	v_add_co_u32_e32 v134, vcc, s92, v128
	s_mov_b32 s5, 0xa000
	s_nop 0
	v_addc_co_u32_e32 v135, vcc, 0, v129, vcc
	v_cvt_pk_bf16_f32 v130, v116, v117
	v_cvt_pk_bf16_f32 v131, v118, v119
	v_cvt_pk_bf16_f32 v132, v112, v113
	v_cvt_pk_bf16_f32 v133, v114, v115
	global_store_dwordx4 v[134:135], v[130:133], off
	v_add_co_u32_e32 v134, vcc, s5, v128
	s_mov_b32 s5, 0xc000
	s_nop 0
	v_addc_co_u32_e32 v135, vcc, 0, v129, vcc
	v_cvt_pk_bf16_f32 v130, v100, v101
	v_cvt_pk_bf16_f32 v131, v102, v103
	v_cvt_pk_bf16_f32 v132, v96, v97
	v_cvt_pk_bf16_f32 v133, v98, v99
	global_store_dwordx4 v[134:135], v[130:133], off
	v_add_co_u32_e32 v134, vcc, s5, v128
	s_mov_b32 s5, 0xe000
	s_nop 0
	v_addc_co_u32_e32 v135, vcc, 0, v129, vcc
	v_cvt_pk_bf16_f32 v130, v84, v85
	v_cvt_pk_bf16_f32 v131, v86, v87
	v_cvt_pk_bf16_f32 v132, v80, v81
	v_cvt_pk_bf16_f32 v133, v82, v83
	global_store_dwordx4 v[134:135], v[130:133], off
	v_add_co_u32_e32 v134, vcc, s5, v128
	s_mov_b32 s5, 0x10000
	s_nop 0
	v_addc_co_u32_e32 v135, vcc, 0, v129, vcc
	v_cvt_pk_bf16_f32 v130, v68, v69
	v_cvt_pk_bf16_f32 v131, v70, v71
	v_cvt_pk_bf16_f32 v132, v64, v65
	v_cvt_pk_bf16_f32 v133, v66, v67
	global_store_dwordx4 v[134:135], v[130:133], off
	v_add_co_u32_e32 v134, vcc, s5, v128
	s_mov_b32 s5, 0x12000
	s_nop 0
	v_addc_co_u32_e32 v135, vcc, 0, v129, vcc
	v_cvt_pk_bf16_f32 v130, v60, v61
	v_cvt_pk_bf16_f32 v131, v62, v63
	v_cvt_pk_bf16_f32 v132, v56, v57
	v_cvt_pk_bf16_f32 v133, v58, v59
	global_store_dwordx4 v[134:135], v[130:133], off
	v_add_co_u32_e32 v134, vcc, s5, v128
	s_mov_b32 s5, 0x14000
	s_nop 0
	v_addc_co_u32_e32 v135, vcc, 0, v129, vcc
	v_cvt_pk_bf16_f32 v130, v44, v45
	v_cvt_pk_bf16_f32 v131, v46, v47
	v_cvt_pk_bf16_f32 v132, v40, v41
	v_cvt_pk_bf16_f32 v133, v42, v43
	global_store_dwordx4 v[134:135], v[130:133], off
	v_add_co_u32_e32 v134, vcc, s5, v128
	s_mov_b32 s5, 0x16000
	s_nop 0
	v_addc_co_u32_e32 v135, vcc, 0, v129, vcc
	v_cvt_pk_bf16_f32 v130, v28, v29
	v_cvt_pk_bf16_f32 v131, v30, v31
	v_cvt_pk_bf16_f32 v132, v24, v25
	v_cvt_pk_bf16_f32 v133, v26, v27
	global_store_dwordx4 v[134:135], v[130:133], off
	v_add_co_u32_e32 v134, vcc, s5, v128
	s_mov_b32 s5, 0x18000
	s_nop 0
	v_addc_co_u32_e32 v135, vcc, 0, v129, vcc
	v_cvt_pk_bf16_f32 v130, v12, v13
	v_cvt_pk_bf16_f32 v131, v14, v15
	v_cvt_pk_bf16_f32 v132, v8, v9
	v_cvt_pk_bf16_f32 v133, v10, v11
	global_store_dwordx4 v[134:135], v[130:133], off
	v_add_co_u32_e32 v134, vcc, s5, v128
	s_mov_b32 s5, 0x1a000
	s_nop 0
	v_addc_co_u32_e32 v135, vcc, 0, v129, vcc
	v_cvt_pk_bf16_f32 v130, v52, v53
	v_cvt_pk_bf16_f32 v131, v54, v55
	v_cvt_pk_bf16_f32 v132, v48, v49
	v_cvt_pk_bf16_f32 v133, v50, v51
	global_store_dwordx4 v[134:135], v[130:133], off
	v_add_co_u32_e32 v134, vcc, s5, v128
	s_mov_b32 s5, 0x1c000
	s_nop 0
	v_addc_co_u32_e32 v135, vcc, 0, v129, vcc
	v_cvt_pk_bf16_f32 v130, v36, v37
	v_cvt_pk_bf16_f32 v131, v38, v39
	v_cvt_pk_bf16_f32 v132, v32, v33
	v_cvt_pk_bf16_f32 v133, v34, v35
	global_store_dwordx4 v[134:135], v[130:133], off
	v_add_co_u32_e32 v134, vcc, s5, v128
	s_nop 0
	v_cvt_pk_bf16_f32 v130, v20, v21
	v_cvt_pk_bf16_f32 v131, v22, v23
	v_cvt_pk_bf16_f32 v132, v16, v17
	v_cvt_pk_bf16_f32 v133, v18, v19
	s_nop 0
	v_addc_co_u32_e32 v135, vcc, 0, v129, vcc
	v_add_co_u32_e32 v128, vcc, 0x1e000, v128
	global_store_dwordx4 v[134:135], v[130:133], off
	s_nop 0
	v_addc_co_u32_e32 v129, vcc, 0, v129, vcc
	v_cvt_pk_bf16_f32 v130, v4, v5
	v_cvt_pk_bf16_f32 v131, v6, v7
	v_cvt_pk_bf16_f32 v132, v0, v1
	v_cvt_pk_bf16_f32 v133, v2, v3
	global_store_dwordx4 v[128:129], v[130:133], off

.LBB0_1436:
	s_setprio 1
	s_add_u32 s28, s6, 0xfffc0080
	s_addc_u32 s29, s7, -1
	s_add_i32 s71, 0, 0x10000
	v_add_u32_e32 v140, s71, v200
	ds_read_b128 v[128:131], v140
	ds_read_b128 v[132:135], v140 offset:1024
	ds_read_b128 v[136:139], v140 offset:2048
	ds_read_b128 v[140:143], v140 offset:3072
	s_cmp_eq_u32 s70, 12
	s_cselect_b32 s53, s17, s29
	s_cselect_b32 s52, s66, s28
	s_cselect_b32 s51, s13, s69
	s_cselect_b32 s50, s67, s68
	v_lshl_add_u64 v[174:175], s[6:7], 0, v[162:163]
	s_add_i32 m0, s56, 0xc000
	ds_read_b128 v[144:147], v201
	ds_read_b128 v[152:155], v201 offset:2048
	ds_read_b128 v[170:173], v201 offset:4096
	ds_read_b128 v[192:195], v201 offset:6144
	ds_read_b128 v[148:151], v201 offset:1024
	ds_read_b128 v[166:169], v201 offset:3072
	ds_read_b128 v[188:191], v201 offset:5120
	ds_read_b128 v[202:205], v201 offset:7168
	global_load_lds_dwordx4 v[174:175], off
	v_lshl_add_u64 v[174:175], s[6:7], 0, v[164:165]
	s_add_i32 m0, s56, 0xe000
	s_nop 0
	global_load_lds_dwordx4 v[174:175], off
	s_waitcnt lgkmcnt(8)
	s_barrier
	s_setprio 0
	s_waitcnt lgkmcnt(7)
	v_mfma_f32_16x16x32_bf16 v[124:127], v[128:131], v[144:147], v[124:127]
	v_mfma_f32_16x16x32_bf16 v[116:119], v[136:139], v[144:147], v[116:119]
	s_waitcnt lgkmcnt(6)
	v_mfma_f32_16x16x32_bf16 v[108:111], v[128:131], v[152:155], v[108:111]
	v_mfma_f32_16x16x32_bf16 v[100:103], v[136:139], v[152:155], v[100:103]
	s_waitcnt lgkmcnt(5)
	v_mfma_f32_16x16x32_bf16 v[92:95], v[128:131], v[170:173], v[92:95]
	v_mfma_f32_16x16x32_bf16 v[84:87], v[136:139], v[170:173], v[84:87]
	s_waitcnt lgkmcnt(4)
	v_mfma_f32_16x16x32_bf16 v[76:79], v[128:131], v[192:195], v[76:79]
	v_mfma_f32_16x16x32_bf16 v[68:71], v[136:139], v[192:195], v[68:71]
	s_waitcnt lgkmcnt(3)
	v_mfma_f32_16x16x32_bf16 v[124:127], v[132:135], v[148:151], v[124:127]
	v_mfma_f32_16x16x32_bf16 v[116:119], v[140:143], v[148:151], v[116:119]
	s_waitcnt lgkmcnt(2)
	v_mfma_f32_16x16x32_bf16 v[108:111], v[132:135], v[166:169], v[108:111]
	v_mfma_f32_16x16x32_bf16 v[100:103], v[140:143], v[166:169], v[100:103]
	s_waitcnt lgkmcnt(1)
	v_mfma_f32_16x16x32_bf16 v[92:95], v[132:135], v[188:191], v[92:95]
	v_mfma_f32_16x16x32_bf16 v[84:87], v[140:143], v[188:191], v[84:87]
	s_waitcnt lgkmcnt(0)
	v_mfma_f32_16x16x32_bf16 v[76:79], v[132:135], v[202:205], v[76:79]
	v_mfma_f32_16x16x32_bf16 v[68:71], v[140:143], v[202:205], v[68:71]
	s_barrier
	s_setprio 1
	s_add_i32 s28, 0, 0x14000
	v_add_u32_e32 v174, s28, v200
	s_add_i32 s29, s71, s55
	ds_read_b128 v[206:209], v174
	ds_read_b128 v[210:213], v174 offset:1024
	ds_read_b128 v[214:217], v174 offset:2048
	ds_read_b128 v[232:235], v174 offset:3072
	v_lshl_add_u64 v[174:175], s[50:51], 0, v[176:177]
	s_mov_b32 m0, s29
	v_lshl_add_u64 v[196:197], s[50:51], 0, v[160:161]
	global_load_lds_dwordx4 v[174:175], off
	s_add_i32 m0, s29, 0x2000
	s_nop 0
	global_load_lds_dwordx4 v[196:197], off
	s_barrier
	s_setprio 0
	s_waitcnt lgkmcnt(3)
	v_mfma_f32_16x16x32_bf16 v[120:123], v[206:209], v[144:147], v[120:123]
	s_waitcnt lgkmcnt(1)
	v_mfma_f32_16x16x32_bf16 v[112:115], v[214:217], v[144:147], v[112:115]
	v_mfma_f32_16x16x32_bf16 v[104:107], v[206:209], v[152:155], v[104:107]
	v_mfma_f32_16x16x32_bf16 v[96:99], v[214:217], v[152:155], v[96:99]
	v_mfma_f32_16x16x32_bf16 v[88:91], v[206:209], v[170:173], v[88:91]
	v_mfma_f32_16x16x32_bf16 v[80:83], v[214:217], v[170:173], v[80:83]
	v_mfma_f32_16x16x32_bf16 v[72:75], v[206:209], v[192:195], v[72:75]
	v_mfma_f32_16x16x32_bf16 v[64:67], v[214:217], v[192:195], v[64:67]
	v_mfma_f32_16x16x32_bf16 v[120:123], v[210:213], v[148:151], v[120:123]
	s_waitcnt lgkmcnt(0)
	v_mfma_f32_16x16x32_bf16 v[112:115], v[232:235], v[148:151], v[112:115]
	v_mfma_f32_16x16x32_bf16 v[104:107], v[210:213], v[166:169], v[104:107]
	v_mfma_f32_16x16x32_bf16 v[96:99], v[232:235], v[166:169], v[96:99]
	v_mfma_f32_16x16x32_bf16 v[88:91], v[210:213], v[188:191], v[88:91]
	v_mfma_f32_16x16x32_bf16 v[80:83], v[232:235], v[188:191], v[80:83]
	v_mfma_f32_16x16x32_bf16 v[72:75], v[210:213], v[202:205], v[72:75]
	v_mfma_f32_16x16x32_bf16 v[64:67], v[232:235], v[202:205], v[64:67]
	s_mov_b32 m0, s56
	v_lshl_add_u64 v[236:237], s[52:53], 0, v[156:157]
	s_barrier
	s_setprio 1
	ds_read_b128 v[144:147], v201 offset:16384
	ds_read_b128 v[152:155], v201 offset:18432
	ds_read_b128 v[170:173], v201 offset:20480
	ds_read_b128 v[192:195], v201 offset:22528
	ds_read_b128 v[148:151], v201 offset:17408
	ds_read_b128 v[166:169], v201 offset:19456
	ds_read_b128 v[188:191], v201 offset:21504
	ds_read_b128 v[202:205], v201 offset:23552
	global_load_lds_dwordx4 v[236:237], off
	v_lshl_add_u64 v[238:239], s[52:53], 0, v[158:159]
	s_mov_b32 m0, s57
	s_nop 0
	global_load_lds_dwordx4 v[238:239], off
	s_barrier
	s_setprio 0
	s_waitcnt lgkmcnt(7)
	v_mfma_f32_16x16x32_bf16 v[60:63], v[128:131], v[144:147], v[60:63]
	v_mfma_f32_16x16x32_bf16 v[52:55], v[136:139], v[144:147], v[52:55]
	s_waitcnt lgkmcnt(6)
	v_mfma_f32_16x16x32_bf16 v[44:47], v[128:131], v[152:155], v[44:47]
	v_mfma_f32_16x16x32_bf16 v[36:39], v[136:139], v[152:155], v[36:39]
	s_waitcnt lgkmcnt(5)
	v_mfma_f32_16x16x32_bf16 v[28:31], v[128:131], v[170:173], v[28:31]
	v_mfma_f32_16x16x32_bf16 v[20:23], v[136:139], v[170:173], v[20:23]
	s_waitcnt lgkmcnt(4)
	v_mfma_f32_16x16x32_bf16 v[12:15], v[128:131], v[192:195], v[12:15]
	v_mfma_f32_16x16x32_bf16 v[4:7], v[136:139], v[192:195], v[4:7]
	s_waitcnt lgkmcnt(3)
	v_mfma_f32_16x16x32_bf16 v[60:63], v[132:135], v[148:151], v[60:63]
	v_mfma_f32_16x16x32_bf16 v[52:55], v[140:143], v[148:151], v[52:55]
	s_waitcnt lgkmcnt(2)
	v_mfma_f32_16x16x32_bf16 v[44:47], v[132:135], v[166:169], v[44:47]
	v_mfma_f32_16x16x32_bf16 v[36:39], v[140:143], v[166:169], v[36:39]
	s_waitcnt lgkmcnt(1)
	v_mfma_f32_16x16x32_bf16 v[28:31], v[132:135], v[188:191], v[28:31]
	v_mfma_f32_16x16x32_bf16 v[20:23], v[140:143], v[188:191], v[20:23]
	s_waitcnt lgkmcnt(0)
	v_mfma_f32_16x16x32_bf16 v[12:15], v[132:135], v[202:205], v[12:15]
	v_mfma_f32_16x16x32_bf16 v[4:7], v[140:143], v[202:205], v[4:7]
	s_barrier
	s_setprio 1
	s_add_u32 s72, s50, 0x40000
	s_addc_u32 s73, s51, 0
	s_add_i32 s28, s28, s55
	v_lshl_add_u64 v[128:129], s[72:73], 0, v[176:177]
	s_mov_b32 m0, s28
	s_nop 0
	global_load_lds_dwordx4 v[128:129], off
	v_lshl_add_u64 v[128:129], s[72:73], 0, v[160:161]
	s_add_i32 m0, s28, 0x2000
	s_nop 0
	global_load_lds_dwordx4 v[128:129], off
	s_waitcnt vmcnt(6)
	s_barrier
	s_setprio 0
	v_mfma_f32_16x16x32_bf16 v[56:59], v[206:209], v[144:147], v[56:59]
	v_mfma_f32_16x16x32_bf16 v[48:51], v[214:217], v[144:147], v[48:51]
	v_mfma_f32_16x16x32_bf16 v[40:43], v[206:209], v[152:155], v[40:43]
	v_mfma_f32_16x16x32_bf16 v[32:35], v[214:217], v[152:155], v[32:35]
	v_mfma_f32_16x16x32_bf16 v[24:27], v[206:209], v[170:173], v[24:27]
	v_mfma_f32_16x16x32_bf16 v[16:19], v[214:217], v[170:173], v[16:19]
	v_mfma_f32_16x16x32_bf16 v[8:11], v[206:209], v[192:195], v[8:11]
	v_mfma_f32_16x16x32_bf16 v[0:3], v[214:217], v[192:195], v[0:3]
	v_mfma_f32_16x16x32_bf16 v[56:59], v[210:213], v[148:151], v[56:59]
	v_mfma_f32_16x16x32_bf16 v[48:51], v[232:235], v[148:151], v[48:51]
	v_mfma_f32_16x16x32_bf16 v[40:43], v[210:213], v[166:169], v[40:43]
	v_mfma_f32_16x16x32_bf16 v[32:35], v[232:235], v[166:169], v[32:35]
	v_mfma_f32_16x16x32_bf16 v[24:27], v[210:213], v[188:191], v[24:27]
	v_mfma_f32_16x16x32_bf16 v[16:19], v[232:235], v[188:191], v[16:19]
	v_mfma_f32_16x16x32_bf16 v[8:11], v[210:213], v[202:205], v[8:11]
	v_mfma_f32_16x16x32_bf16 v[0:3], v[232:235], v[202:205], v[0:3]
	s_add_i32 s28, 0, 0x18000
	v_add_u32_e32 v140, s28, v200
	s_barrier
	s_setprio 1
	ds_read_b128 v[128:131], v140
	ds_read_b128 v[132:135], v140 offset:1024
	ds_read_b128 v[136:139], v140 offset:2048
	ds_read_b128 v[140:143], v140 offset:3072
	s_add_u32 s52, s52, 0x40000
	s_addc_u32 s53, s53, 0
	s_mov_b32 m0, s58
	v_lshl_add_u64 v[206:207], s[52:53], 0, v[156:157]
	ds_read_b128 v[144:147], v201 offset:32768
	ds_read_b128 v[152:155], v201 offset:34816
	ds_read_b128 v[170:173], v201 offset:36864
	ds_read_b128 v[192:195], v201 offset:38912
	ds_read_b128 v[148:151], v201 offset:33792
	ds_read_b128 v[166:169], v201 offset:35840
	ds_read_b128 v[188:191], v201 offset:37888
	ds_read_b128 v[202:205], v201 offset:39936
	global_load_lds_dwordx4 v[206:207], off
	v_lshl_add_u64 v[206:207], s[52:53], 0, v[158:159]
	s_mov_b32 m0, s59
	s_nop 0
	global_load_lds_dwordx4 v[206:207], off
	s_waitcnt lgkmcnt(8)
	s_barrier
	s_setprio 0
	s_waitcnt lgkmcnt(7)
	v_mfma_f32_16x16x32_bf16 v[124:127], v[128:131], v[144:147], v[124:127]
	v_mfma_f32_16x16x32_bf16 v[116:119], v[136:139], v[144:147], v[116:119]
	s_waitcnt lgkmcnt(6)
	v_mfma_f32_16x16x32_bf16 v[108:111], v[128:131], v[152:155], v[108:111]
	v_mfma_f32_16x16x32_bf16 v[100:103], v[136:139], v[152:155], v[100:103]
	s_waitcnt lgkmcnt(5)
	v_mfma_f32_16x16x32_bf16 v[92:95], v[128:131], v[170:173], v[92:95]
	v_mfma_f32_16x16x32_bf16 v[84:87], v[136:139], v[170:173], v[84:87]
	s_waitcnt lgkmcnt(4)
	v_mfma_f32_16x16x32_bf16 v[76:79], v[128:131], v[192:195], v[76:79]
	v_mfma_f32_16x16x32_bf16 v[68:71], v[136:139], v[192:195], v[68:71]
	s_waitcnt lgkmcnt(3)
	v_mfma_f32_16x16x32_bf16 v[124:127], v[132:135], v[148:151], v[124:127]
	v_mfma_f32_16x16x32_bf16 v[116:119], v[140:143], v[148:151], v[116:119]
	s_waitcnt lgkmcnt(2)
	v_mfma_f32_16x16x32_bf16 v[108:111], v[132:135], v[166:169], v[108:111]
	v_mfma_f32_16x16x32_bf16 v[100:103], v[140:143], v[166:169], v[100:103]
	s_waitcnt lgkmcnt(1)
	v_mfma_f32_16x16x32_bf16 v[92:95], v[132:135], v[188:191], v[92:95]
	v_mfma_f32_16x16x32_bf16 v[84:87], v[140:143], v[188:191], v[84:87]
	s_waitcnt lgkmcnt(0)
	v_mfma_f32_16x16x32_bf16 v[76:79], v[132:135], v[202:205], v[76:79]
	v_mfma_f32_16x16x32_bf16 v[68:71], v[140:143], v[202:205], v[68:71]
	s_barrier
	s_setprio 1
	s_add_i32 s29, 0, 0x1c000
	s_add_i32 s28, s28, s55
	v_add_u32_e32 v232, s29, v200
	v_lshl_add_u64 v[174:175], v[174:175], 0, s[40:41]
	s_mov_b32 m0, s28
	ds_read_b128 v[206:209], v232
	ds_read_b128 v[210:213], v232 offset:1024
	ds_read_b128 v[214:217], v232 offset:2048
	ds_read_b128 v[232:235], v232 offset:3072
	global_load_lds_dwordx4 v[174:175], off
	v_lshl_add_u64 v[174:175], v[196:197], 0, s[40:41]
	s_add_i32 m0, s28, 0x2000
	s_nop 0
	global_load_lds_dwordx4 v[174:175], off
	s_barrier
	s_setprio 0
	s_waitcnt lgkmcnt(3)
	v_mfma_f32_16x16x32_bf16 v[120:123], v[206:209], v[144:147], v[120:123]
	s_waitcnt lgkmcnt(1)
	v_mfma_f32_16x16x32_bf16 v[112:115], v[214:217], v[144:147], v[112:115]
	v_mfma_f32_16x16x32_bf16 v[104:107], v[206:209], v[152:155], v[104:107]
	v_mfma_f32_16x16x32_bf16 v[96:99], v[214:217], v[152:155], v[96:99]
	v_mfma_f32_16x16x32_bf16 v[88:91], v[206:209], v[170:173], v[88:91]
	v_mfma_f32_16x16x32_bf16 v[80:83], v[214:217], v[170:173], v[80:83]
	v_mfma_f32_16x16x32_bf16 v[72:75], v[206:209], v[192:195], v[72:75]
	v_mfma_f32_16x16x32_bf16 v[64:67], v[214:217], v[192:195], v[64:67]
	v_mfma_f32_16x16x32_bf16 v[120:123], v[210:213], v[148:151], v[120:123]
	s_waitcnt lgkmcnt(0)
	v_mfma_f32_16x16x32_bf16 v[112:115], v[232:235], v[148:151], v[112:115]
	v_mfma_f32_16x16x32_bf16 v[104:107], v[210:213], v[166:169], v[104:107]
	v_mfma_f32_16x16x32_bf16 v[96:99], v[232:235], v[166:169], v[96:99]
	v_mfma_f32_16x16x32_bf16 v[88:91], v[210:213], v[188:191], v[88:91]
	v_mfma_f32_16x16x32_bf16 v[80:83], v[232:235], v[188:191], v[80:83]
	v_mfma_f32_16x16x32_bf16 v[72:75], v[210:213], v[202:205], v[72:75]
	v_mfma_f32_16x16x32_bf16 v[64:67], v[232:235], v[202:205], v[64:67]
	s_mov_b32 m0, s62
	v_lshl_add_u64 v[174:175], v[236:237], 0, s[40:41]
	s_barrier
	s_setprio 1
	ds_read_b128 v[144:147], v201 offset:49152
	ds_read_b128 v[152:155], v201 offset:51200
	ds_read_b128 v[170:173], v201 offset:53248
	ds_read_b128 v[192:195], v201 offset:55296
	ds_read_b128 v[148:151], v201 offset:50176
	ds_read_b128 v[166:169], v201 offset:52224
	ds_read_b128 v[188:191], v201 offset:54272
	ds_read_b128 v[202:205], v201 offset:56320
	global_load_lds_dwordx4 v[174:175], off
	v_lshl_add_u64 v[174:175], v[238:239], 0, s[40:41]
	s_mov_b32 m0, s63
	s_nop 0
	global_load_lds_dwordx4 v[174:175], off
	s_barrier
	s_setprio 0
	s_waitcnt lgkmcnt(7)
	v_mfma_f32_16x16x32_bf16 v[60:63], v[128:131], v[144:147], v[60:63]
	v_mfma_f32_16x16x32_bf16 v[52:55], v[136:139], v[144:147], v[52:55]
	s_waitcnt lgkmcnt(6)
	v_mfma_f32_16x16x32_bf16 v[44:47], v[128:131], v[152:155], v[44:47]
	v_mfma_f32_16x16x32_bf16 v[36:39], v[136:139], v[152:155], v[36:39]
	s_waitcnt lgkmcnt(5)
	v_mfma_f32_16x16x32_bf16 v[28:31], v[128:131], v[170:173], v[28:31]
	v_mfma_f32_16x16x32_bf16 v[20:23], v[136:139], v[170:173], v[20:23]
	s_waitcnt lgkmcnt(4)
	v_mfma_f32_16x16x32_bf16 v[12:15], v[128:131], v[192:195], v[12:15]
	v_mfma_f32_16x16x32_bf16 v[4:7], v[136:139], v[192:195], v[4:7]
	s_waitcnt lgkmcnt(3)
	v_mfma_f32_16x16x32_bf16 v[60:63], v[132:135], v[148:151], v[60:63]
	v_mfma_f32_16x16x32_bf16 v[52:55], v[140:143], v[148:151], v[52:55]
	s_waitcnt lgkmcnt(2)
	v_mfma_f32_16x16x32_bf16 v[44:47], v[132:135], v[166:169], v[44:47]
	v_mfma_f32_16x16x32_bf16 v[36:39], v[140:143], v[166:169], v[36:39]
	s_waitcnt lgkmcnt(1)
	v_mfma_f32_16x16x32_bf16 v[28:31], v[132:135], v[188:191], v[28:31]
	v_mfma_f32_16x16x32_bf16 v[20:23], v[140:143], v[188:191], v[20:23]
	s_waitcnt lgkmcnt(0)
	v_mfma_f32_16x16x32_bf16 v[12:15], v[132:135], v[202:205], v[12:15]
	v_mfma_f32_16x16x32_bf16 v[4:7], v[140:143], v[202:205], v[4:7]
	s_barrier
	s_setprio 1
	s_add_u32 s50, s50, 0x40080
	s_addc_u32 s51, s51, 0
	s_add_i32 s28, s29, s55
	v_lshl_add_u64 v[128:129], s[50:51], 0, v[176:177]
	s_mov_b32 m0, s28
	s_nop 0
	global_load_lds_dwordx4 v[128:129], off
	v_lshl_add_u64 v[128:129], s[50:51], 0, v[160:161]
	s_add_i32 m0, s28, 0x2000
	s_nop 0
	global_load_lds_dwordx4 v[128:129], off
	s_waitcnt vmcnt(6)
	s_barrier
	s_setprio 0
	v_mfma_f32_16x16x32_bf16 v[56:59], v[206:209], v[144:147], v[56:59]
	v_mfma_f32_16x16x32_bf16 v[48:51], v[214:217], v[144:147], v[48:51]
	v_mfma_f32_16x16x32_bf16 v[40:43], v[206:209], v[152:155], v[40:43]
	v_mfma_f32_16x16x32_bf16 v[32:35], v[214:217], v[152:155], v[32:35]
	v_mfma_f32_16x16x32_bf16 v[24:27], v[206:209], v[170:173], v[24:27]
	v_mfma_f32_16x16x32_bf16 v[16:19], v[214:217], v[170:173], v[16:19]
	v_mfma_f32_16x16x32_bf16 v[8:11], v[206:209], v[192:195], v[8:11]
	v_mfma_f32_16x16x32_bf16 v[0:3], v[214:217], v[192:195], v[0:3]
	v_mfma_f32_16x16x32_bf16 v[56:59], v[210:213], v[148:151], v[56:59]
	v_mfma_f32_16x16x32_bf16 v[48:51], v[232:235], v[148:151], v[48:51]
	v_mfma_f32_16x16x32_bf16 v[40:43], v[210:213], v[166:169], v[40:43]
	v_mfma_f32_16x16x32_bf16 v[32:35], v[232:235], v[166:169], v[32:35]
	v_mfma_f32_16x16x32_bf16 v[24:27], v[210:213], v[188:191], v[24:27]
	v_mfma_f32_16x16x32_bf16 v[16:19], v[232:235], v[188:191], v[16:19]
	v_mfma_f32_16x16x32_bf16 v[8:11], v[210:213], v[202:205], v[8:11]
	v_mfma_f32_16x16x32_bf16 v[0:3], v[232:235], v[202:205], v[0:3]
	s_add_i32 s70, s70, 2
	s_add_u32 s6, s6, 0x100
	s_addc_u32 s7, s7, 0
	s_add_u32 s68, s68, 0x100
	s_addc_u32 s69, s69, 0
	s_cmp_lt_u32 s70, 14
	s_barrier
	s_cbranch_scc1 .LBB0_1436
	v_mov_b32_e32 v134, v199
	v_mov_b32_e32 v128, v198
	s_lshl_b32 s4, s4, 8
	s_add_i32 s4, s4, s60
	v_add_u32_e32 v192, s4, v128
	v_lshlrev_b32_e32 v128, 2, v134
	v_ashrrev_i32_e32 v129, 31, v128
	v_ashrrev_i32_e32 v193, 31, v192
	v_add_u32_e32 v190, 16, v192
	v_lshl_add_u64 v[132:133], v[128:129], 2, s[8:9]
	v_lshlrev_b64 v[128:129], 6, v[192:193]
	v_ashrrev_i32_e32 v191, 31, v190
	v_add_u32_e32 v188, 32, v192
	v_lshl_add_u64 v[128:129], v[132:133], 0, v[128:129]
	v_lshlrev_b64 v[130:131], 6, v[190:191]
	v_ashrrev_i32_e32 v189, 31, v188
	v_lshl_add_u64 v[130:131], v[132:133], 0, v[130:131]
	global_load_dwordx4 v[202:205], v[128:129], off
	global_load_dwordx4 v[144:147], v[130:131], off
	v_lshlrev_b64 v[128:129], 6, v[188:189]
	v_add_u32_e32 v174, 48, v192
	v_lshl_add_u64 v[128:129], v[132:133], 0, v[128:129]
	v_ashrrev_i32_e32 v175, 31, v174
	global_load_dwordx4 v[148:151], v[128:129], off
	v_lshlrev_b64 v[128:129], 6, v[174:175]
	v_lshl_add_u64 v[128:129], v[132:133], 0, v[128:129]
	global_load_dwordx4 v[152:155], v[128:129], off
	v_add_u32_e32 v172, 0x80, v192
	v_ashrrev_i32_e32 v173, 31, v172
	v_lshlrev_b64 v[128:129], 6, v[172:173]
	v_lshl_add_u64 v[128:129], v[132:133], 0, v[128:129]
	global_load_dwordx4 v[140:143], v[128:129], off
	v_add_u32_e32 v170, 0x90, v192
	v_ashrrev_i32_e32 v171, 31, v170
	v_lshlrev_b64 v[128:129], 6, v[170:171]
	v_lshl_add_u64 v[128:129], v[132:133], 0, v[128:129]
	global_load_dwordx4 v[128:131], v[128:129], off
	s_lshl_b32 s5, s5, 7
	v_add_u32_e32 v168, 0xa0, v192
	v_add_u32_e32 v166, 0xb0, v192
	s_or_b32 s5, s5, s61
	v_ashrrev_i32_e32 v169, 31, v168
	v_ashrrev_i32_e32 v167, 31, v166
	v_lshl_add_u32 v194, v134, 3, s5
	v_lshlrev_b64 v[134:135], 6, v[168:169]
	v_lshlrev_b64 v[136:137], 6, v[166:167]
	v_lshl_add_u64 v[134:135], v[132:133], 0, v[134:135]
	v_lshl_add_u64 v[132:133], v[132:133], 0, v[136:137]
	global_load_dwordx4 v[136:139], v[134:135], off
	s_nop 0
	global_load_dwordx4 v[132:135], v[132:133], off
	s_mov_b32 s4, 0x358637bd
	v_mov_b64_e32 v[196:197], s[4:5]
	v_ashrrev_i32_e32 v195, 31, v194
	s_mov_b64 s[50:51], s[20:21]
	s_waitcnt vmcnt(0)
	v_mov_b32_e32 v206, v203
	v_mov_b32_e32 v207, v204
	v_mov_b32_e32 v203, v205
	v_mov_b32_e32 v204, v145
	v_mov_b32_e32 v205, v146
	v_mov_b32_e32 v145, v147
	v_pk_add_f32 v[202:203], v[206:207], v[202:203]
	v_mov_b32_e32 v146, v149
	v_mov_b32_e32 v147, v150
	v_mov_b32_e32 v149, v151
	v_mov_b32_e32 v150, v153
	v_mov_b32_e32 v151, v154
	v_mov_b32_e32 v153, v155
	v_pk_add_f32 v[144:145], v[204:205], v[144:145]
	v_mov_b32_e32 v155, v202
	v_pk_add_f32 v[146:147], v[146:147], v[148:149]
	v_pk_add_f32 v[148:149], v[150:151], v[152:153]
	v_mov_b32_e32 v154, v144
	v_mov_b32_e32 v202, v145
	v_mov_b32_e32 v144, v148
	v_mov_b32_e32 v145, v146
	v_mov_b32_e32 v146, v149
	v_pk_add_f32 v[148:149], v[154:155], v[202:203]
	v_pk_add_f32 v[144:145], v[144:145], v[146:147]
	ds_bpermute_b32 v147, v219, v149
	ds_bpermute_b32 v146, v219, v148
	ds_bpermute_b32 v151, v219, v145
	ds_bpermute_b32 v150, v219, v144
	v_mov_b32_e32 v152, v141
	v_mov_b32_e32 v153, v142
	v_mov_b32_e32 v141, v143
	s_waitcnt lgkmcnt(0)
	v_pk_add_f32 v[142:143], v[148:149], v[146:147]
	ds_bpermute_b32 v147, v218, v143
	ds_bpermute_b32 v146, v218, v142
	v_pk_add_f32 v[144:145], v[144:145], v[150:151]
	ds_bpermute_b32 v149, v218, v145
	ds_bpermute_b32 v148, v218, v144
	v_mov_b32_e32 v150, v129
	s_waitcnt lgkmcnt(2)
	v_pk_add_f32 v[142:143], v[142:143], v[146:147]
	v_mov_b32_e32 v151, v130
	v_pk_fma_f32 v[142:143], v[142:143], s[30:31], v[196:197] op_sel_hi:[1,0,0]
	s_waitcnt lgkmcnt(0)
	v_pk_add_f32 v[144:145], v[144:145], v[148:149]
	v_mul_f32_e32 v129, 0x4b800000, v143
	v_cmp_gt_f32_e32 vcc, s86, v143
	v_pk_fma_f32 v[146:147], v[144:145], s[30:31], v[196:197] op_sel_hi:[1,0,0]
	v_mul_f32_e32 v130, 0x4b800000, v142
	v_cndmask_b32_e32 v129, v143, v129, vcc
	v_rsq_f32_e32 v129, v129
	v_cmp_gt_f32_e64 s[4:5], s86, v142
	v_mul_f32_e32 v144, 0x4b800000, v147
	v_cmp_gt_f32_e64 s[6:7], s86, v147
	v_cndmask_b32_e64 v130, v142, v130, s[4:5]
	v_rsq_f32_e32 v142, v130
	v_cndmask_b32_e64 v130, v147, v144, s[6:7]
	v_rsq_f32_e32 v143, v130
	v_mul_f32_e32 v130, 0x45800000, v129
	v_cndmask_b32_e32 v144, v129, v130, vcc
	v_mov_b32_e32 v129, v131
	v_pk_add_f32 v[140:141], v[152:153], v[140:141]
	v_pk_add_f32 v[128:129], v[150:151], v[128:129]
	v_mov_b32_e32 v131, v140
	v_mov_b32_e32 v130, v128
	v_mov_b32_e32 v140, v129
	v_pk_add_f32 v[128:129], v[130:131], v[140:141]
	ds_bpermute_b32 v131, v219, v129
	ds_bpermute_b32 v130, v219, v128
	v_mul_f32_e32 v145, 0x45800000, v142
	v_cndmask_b32_e64 v142, v142, v145, s[4:5]
	v_mul_f32_e32 v140, 0x4b800000, v146
	v_cmp_gt_f32_e32 vcc, s86, v146
	s_waitcnt lgkmcnt(0)
	v_pk_add_f32 v[128:129], v[128:129], v[130:131]
	ds_bpermute_b32 v131, v218, v129
	ds_bpermute_b32 v130, v218, v128
	v_cndmask_b32_e32 v140, v146, v140, vcc
	v_rsq_f32_e32 v141, v140
	v_mul_f32_e32 v140, 0x45800000, v143
	v_cndmask_b32_e64 v140, v143, v140, s[6:7]
	s_waitcnt lgkmcnt(0)
	v_pk_add_f32 v[128:129], v[128:129], v[130:131]
	v_mov_b32_e32 v131, v138
	v_pk_fma_f32 v[128:129], v[128:129], s[30:31], v[196:197] op_sel_hi:[1,0,0]
	v_mul_f32_e32 v143, 0x45800000, v141
	v_mul_f32_e32 v130, 0x4b800000, v129
	v_cmp_gt_f32_e64 s[4:5], s86, v129
	v_cmp_gt_f32_e64 s[6:7], s86, v128
	v_pk_mul_f32 v[110:111], v[110:111], v[142:143] op_sel_hi:[1,0]
	v_cndmask_b32_e64 v129, v129, v130, s[4:5]
	v_mov_b32_e32 v130, v137
	v_mov_b32_e32 v137, v139
	v_pk_add_f32 v[130:131], v[130:131], v[136:137]
	v_mov_b32_e32 v136, v133
	v_mov_b32_e32 v137, v134
	v_mov_b32_e32 v133, v135
	v_pk_add_f32 v[132:133], v[136:137], v[132:133]
	v_mov_b32_e32 v135, v130
	v_mov_b32_e32 v134, v132
	v_mov_b32_e32 v130, v133
	v_pk_add_f32 v[130:131], v[134:135], v[130:131]
	ds_bpermute_b32 v133, v219, v131
	ds_bpermute_b32 v132, v219, v130
	v_rsq_f32_e32 v145, v129
	v_mul_f32_e32 v129, 0x4b800000, v128
	v_cndmask_b32_e64 v128, v128, v129, s[6:7]
	v_rsq_f32_e32 v135, v128
	s_waitcnt lgkmcnt(0)
	v_pk_add_f32 v[128:129], v[130:131], v[132:133]
	ds_bpermute_b32 v131, v218, v129
	ds_bpermute_b32 v130, v218, v128
	v_pk_mul_f32 v[126:127], v[126:127], v[144:145] op_sel_hi:[1,0]
	v_pk_mul_f32 v[122:123], v[122:123], v[144:145] op_sel_hi:[1,0]
	v_pk_mul_f32 v[116:117], v[116:117], v[144:145] op_sel_hi:[1,0]
	v_pk_mul_f32 v[124:125], v[124:125], v[144:145] op_sel_hi:[1,0]
	v_pk_mul_f32 v[138:139], v[126:127], s[44:45] op_sel_hi:[1,0]
	v_pk_mul_f32 v[120:121], v[120:121], v[144:145] op_sel_hi:[1,0]
	v_pk_mul_f32 v[122:123], v[126:127], v[122:123]
	v_pk_mul_f32 v[118:119], v[118:119], v[144:145] op_sel_hi:[1,0]
	v_pk_mul_f32 v[126:127], v[116:117], s[44:45] op_sel_hi:[1,0]
	v_pk_mul_f32 v[146:147], v[124:125], s[44:45] op_sel_hi:[1,0]
	v_pk_mul_f32 v[120:121], v[124:125], v[120:121]
	v_pk_mul_f32 v[124:125], v[118:119], s[44:45] op_sel_hi:[1,0]
	v_exp_f32_e32 v126, v126
	v_exp_f32_e32 v127, v127
	s_waitcnt lgkmcnt(0)
	v_pk_add_f32 v[128:129], v[128:129], v[130:131]
	v_exp_f32_e32 v146, v146
	v_exp_f32_e32 v138, v138
	v_exp_f32_e32 v139, v139
	v_exp_f32_e32 v147, v147
	v_exp_f32_e32 v124, v124
	v_exp_f32_e32 v125, v125
	v_pk_fma_f32 v[128:129], v[128:129], s[30:31], v[196:197] op_sel_hi:[1,0,0]
	v_cndmask_b32_e32 v136, v141, v143, vcc
	v_mul_f32_e32 v132, 0x45800000, v145
	v_mul_f32_e32 v130, 0x4b800000, v129
	v_cmp_gt_f32_e32 vcc, s86, v129
	v_cndmask_b32_e64 v134, v145, v132, s[4:5]
	v_cmp_gt_f32_e64 s[4:5], s86, v128
	v_cndmask_b32_e32 v129, v129, v130, vcc
	v_mul_f32_e32 v130, 0x4b800000, v128
	v_pk_add_f32 v[126:127], v[126:127], 1.0 op_sel_hi:[1,0]
	v_rsq_f32_e32 v129, v129
	v_cndmask_b32_e64 v128, v128, v130, s[4:5]
	v_pk_add_f32 v[138:139], v[138:139], 1.0 op_sel_hi:[1,0]
	v_pk_add_f32 v[146:147], v[146:147], 1.0 op_sel_hi:[1,0]
	v_pk_add_f32 v[124:125], v[124:125], 1.0 op_sel_hi:[1,0]
	v_rcp_f32_e32 v126, v126
	v_rcp_f32_e32 v127, v127
	v_rsq_f32_e32 v128, v128
	v_rcp_f32_e32 v146, v146
	v_rcp_f32_e32 v138, v138
	v_rcp_f32_e32 v139, v139
	v_rcp_f32_e32 v147, v147
	v_rcp_f32_e32 v124, v124
	v_rcp_f32_e32 v125, v125
	v_pk_mul_f32 v[112:113], v[112:113], v[144:145] op_sel_hi:[1,0]
	v_pk_mul_f32 v[114:115], v[114:115], v[144:145] op_sel_hi:[1,0]
	v_pk_mul_f32 v[112:113], v[116:117], v[112:113]
	v_mul_f32_e32 v130, 0x45800000, v129
	v_pk_mul_f32 v[114:115], v[118:119], v[114:115]
	v_pk_mul_f32 v[112:113], v[112:113], v[126:127]
	v_cndmask_b32_e32 v130, v129, v130, vcc
	v_mul_f32_e32 v129, 0x45800000, v128
	v_pk_mul_f32 v[122:123], v[122:123], v[138:139]
	v_pk_mul_f32 v[120:121], v[120:121], v[146:147]
	v_pk_mul_f32 v[114:115], v[114:115], v[124:125]
	v_cvt_pk_bf16_f32 v116, v120, v121
	v_cvt_pk_bf16_f32 v117, v122, v123
	v_cvt_pk_bf16_f32 v118, v112, v113
	v_mov_b64_e32 v[112:113], s[10:11]
	v_cndmask_b32_e64 v128, v128, v129, s[4:5]
	v_cvt_pk_bf16_f32 v119, v114, v115
	v_mad_i64_i32 v[120:121], s[4:5], v192, s35, v[112:113]
	v_lshlrev_b64 v[114:115], 1, v[194:195]
	v_lshl_add_u64 v[120:121], v[120:121], 0, v[114:115]
	v_pk_mul_f32 v[108:109], v[108:109], v[142:143] op_sel_hi:[1,0]
	v_pk_mul_f32 v[106:107], v[106:107], v[142:143] op_sel_hi:[1,0]
	v_pk_mul_f32 v[104:105], v[104:105], v[142:143] op_sel_hi:[1,0]
	v_pk_mul_f32 v[102:103], v[102:103], v[142:143] op_sel_hi:[1,0]
	v_pk_mul_f32 v[100:101], v[100:101], v[142:143] op_sel_hi:[1,0]
	global_store_dwordx4 v[120:121], v[116:119], off
	v_pk_mul_f32 v[104:105], v[108:109], v[104:105]
	v_pk_mul_f32 v[106:107], v[110:111], v[106:107]
	v_pk_mul_f32 v[116:117], v[110:111], s[44:45] op_sel_hi:[1,0]
	v_pk_mul_f32 v[118:119], v[108:109], s[44:45] op_sel_hi:[1,0]
	v_pk_mul_f32 v[108:109], v[102:103], s[44:45] op_sel_hi:[1,0]
	v_pk_mul_f32 v[110:111], v[100:101], s[44:45] op_sel_hi:[1,0]
	v_exp_f32_e32 v108, v108
	v_exp_f32_e32 v110, v110
	v_exp_f32_e32 v109, v109
	v_exp_f32_e32 v111, v111
	v_exp_f32_e32 v118, v118
	v_exp_f32_e32 v116, v116
	v_exp_f32_e32 v117, v117
	v_exp_f32_e32 v119, v119
	v_pk_add_f32 v[108:109], v[108:109], 1.0 op_sel_hi:[1,0]
	v_pk_add_f32 v[110:111], v[110:111], 1.0 op_sel_hi:[1,0]
	v_pk_add_f32 v[116:117], v[116:117], 1.0 op_sel_hi:[1,0]
	v_pk_add_f32 v[118:119], v[118:119], 1.0 op_sel_hi:[1,0]
	v_rcp_f32_e32 v110, v110
	v_rcp_f32_e32 v108, v108
	v_rcp_f32_e32 v109, v109
	v_rcp_f32_e32 v111, v111
	v_rcp_f32_e32 v118, v118
	v_rcp_f32_e32 v116, v116
	v_rcp_f32_e32 v117, v117
	v_rcp_f32_e32 v119, v119
	v_pk_mul_f32 v[98:99], v[98:99], v[142:143] op_sel_hi:[1,0]
	v_pk_mul_f32 v[96:97], v[96:97], v[142:143] op_sel_hi:[1,0]
	v_pk_mul_f32 v[98:99], v[102:103], v[98:99]
	v_pk_mul_f32 v[96:97], v[100:101], v[96:97]
	v_pk_mul_f32 v[100:101], v[98:99], v[108:109]
	v_pk_mul_f32 v[98:99], v[96:97], v[110:111]
	v_pk_mul_f32 v[106:107], v[106:107], v[116:117]
	v_pk_mul_f32 v[104:105], v[104:105], v[118:119]
	v_pk_mul_f32 v[94:95], v[94:95], v[140:141] op_sel_hi:[1,0]
	v_cvt_pk_bf16_f32 v96, v104, v105
	v_cvt_pk_bf16_f32 v97, v106, v107
	v_cvt_pk_bf16_f32 v98, v98, v99
	v_cvt_pk_bf16_f32 v99, v100, v101
	v_mad_i64_i32 v[100:101], s[4:5], v190, s35, v[112:113]
	v_lshl_add_u64 v[100:101], v[100:101], 0, v[114:115]
	v_pk_mul_f32 v[92:93], v[92:93], v[140:141] op_sel_hi:[1,0]
	v_pk_mul_f32 v[90:91], v[90:91], v[140:141] op_sel_hi:[1,0]
	v_pk_mul_f32 v[88:89], v[88:89], v[140:141] op_sel_hi:[1,0]
	v_pk_mul_f32 v[86:87], v[86:87], v[140:141] op_sel_hi:[1,0]
	v_pk_mul_f32 v[84:85], v[84:85], v[140:141] op_sel_hi:[1,0]
	global_store_dwordx4 v[100:101], v[96:99], off
	v_pk_mul_f32 v[88:89], v[92:93], v[88:89]
	v_pk_mul_f32 v[90:91], v[94:95], v[90:91]
	v_pk_mul_f32 v[96:97], v[94:95], s[44:45] op_sel_hi:[1,0]
	v_pk_mul_f32 v[98:99], v[92:93], s[44:45] op_sel_hi:[1,0]
	v_pk_mul_f32 v[92:93], v[86:87], s[44:45] op_sel_hi:[1,0]
	v_pk_mul_f32 v[94:95], v[84:85], s[44:45] op_sel_hi:[1,0]
	v_exp_f32_e32 v92, v92
	v_exp_f32_e32 v94, v94
	v_exp_f32_e32 v93, v93
	v_exp_f32_e32 v95, v95
	v_exp_f32_e32 v98, v98
	v_exp_f32_e32 v96, v96
	v_exp_f32_e32 v97, v97
	v_exp_f32_e32 v99, v99
	v_pk_add_f32 v[92:93], v[92:93], 1.0 op_sel_hi:[1,0]
	v_pk_add_f32 v[94:95], v[94:95], 1.0 op_sel_hi:[1,0]
	v_pk_add_f32 v[96:97], v[96:97], 1.0 op_sel_hi:[1,0]
	v_pk_add_f32 v[98:99], v[98:99], 1.0 op_sel_hi:[1,0]
	v_rcp_f32_e32 v94, v94
	v_rcp_f32_e32 v92, v92
	v_rcp_f32_e32 v93, v93
	v_rcp_f32_e32 v95, v95
	v_rcp_f32_e32 v98, v98
	v_rcp_f32_e32 v96, v96
	v_rcp_f32_e32 v97, v97
	v_rcp_f32_e32 v99, v99
	v_pk_mul_f32 v[82:83], v[82:83], v[140:141] op_sel_hi:[1,0]
	v_pk_mul_f32 v[80:81], v[80:81], v[140:141] op_sel_hi:[1,0]
	v_pk_mul_f32 v[82:83], v[86:87], v[82:83]
	v_pk_mul_f32 v[80:81], v[84:85], v[80:81]
	v_pk_mul_f32 v[84:85], v[82:83], v[92:93]
	v_pk_mul_f32 v[82:83], v[80:81], v[94:95]
	v_pk_mul_f32 v[90:91], v[90:91], v[96:97]
	v_pk_mul_f32 v[88:89], v[88:89], v[98:99]
	v_pk_mul_f32 v[78:79], v[78:79], v[136:137] op_sel_hi:[1,0]
	v_cvt_pk_bf16_f32 v80, v88, v89
	v_cvt_pk_bf16_f32 v81, v90, v91
	v_cvt_pk_bf16_f32 v82, v82, v83
	v_cvt_pk_bf16_f32 v83, v84, v85
	v_mad_i64_i32 v[84:85], s[4:5], v188, s35, v[112:113]
	v_lshl_add_u64 v[84:85], v[84:85], 0, v[114:115]
	v_pk_mul_f32 v[76:77], v[76:77], v[136:137] op_sel_hi:[1,0]
	v_pk_mul_f32 v[74:75], v[74:75], v[136:137] op_sel_hi:[1,0]
	v_pk_mul_f32 v[72:73], v[72:73], v[136:137] op_sel_hi:[1,0]
	v_pk_mul_f32 v[70:71], v[70:71], v[136:137] op_sel_hi:[1,0]
	v_pk_mul_f32 v[68:69], v[68:69], v[136:137] op_sel_hi:[1,0]
	global_store_dwordx4 v[84:85], v[80:83], off
	v_pk_mul_f32 v[72:73], v[76:77], v[72:73]
	v_pk_mul_f32 v[74:75], v[78:79], v[74:75]
	v_pk_mul_f32 v[80:81], v[78:79], s[44:45] op_sel_hi:[1,0]
	v_pk_mul_f32 v[82:83], v[76:77], s[44:45] op_sel_hi:[1,0]
	v_pk_mul_f32 v[76:77], v[70:71], s[44:45] op_sel_hi:[1,0]
	v_pk_mul_f32 v[78:79], v[68:69], s[44:45] op_sel_hi:[1,0]
	v_exp_f32_e32 v76, v76
	v_exp_f32_e32 v78, v78
	v_exp_f32_e32 v77, v77
	v_exp_f32_e32 v79, v79
	v_exp_f32_e32 v82, v82
	v_exp_f32_e32 v80, v80
	v_exp_f32_e32 v81, v81
	v_exp_f32_e32 v83, v83
	v_pk_add_f32 v[76:77], v[76:77], 1.0 op_sel_hi:[1,0]
	v_pk_add_f32 v[78:79], v[78:79], 1.0 op_sel_hi:[1,0]
	v_pk_add_f32 v[80:81], v[80:81], 1.0 op_sel_hi:[1,0]
	v_pk_add_f32 v[82:83], v[82:83], 1.0 op_sel_hi:[1,0]
	v_rcp_f32_e32 v78, v78
	v_rcp_f32_e32 v76, v76
	v_rcp_f32_e32 v77, v77
	v_rcp_f32_e32 v79, v79
	v_rcp_f32_e32 v82, v82
	v_rcp_f32_e32 v80, v80
	v_rcp_f32_e32 v81, v81
	v_rcp_f32_e32 v83, v83
	v_pk_mul_f32 v[66:67], v[66:67], v[136:137] op_sel_hi:[1,0]
	v_pk_mul_f32 v[64:65], v[64:65], v[136:137] op_sel_hi:[1,0]
	v_pk_mul_f32 v[66:67], v[70:71], v[66:67]
	v_pk_mul_f32 v[64:65], v[68:69], v[64:65]
	v_pk_mul_f32 v[68:69], v[66:67], v[76:77]
	v_pk_mul_f32 v[66:67], v[64:65], v[78:79]
	v_pk_mul_f32 v[74:75], v[74:75], v[80:81]
	v_pk_mul_f32 v[72:73], v[72:73], v[82:83]
	v_pk_mul_f32 v[62:63], v[62:63], v[134:135] op_sel_hi:[1,0]
	v_cvt_pk_bf16_f32 v64, v72, v73
	v_cvt_pk_bf16_f32 v65, v74, v75
	v_cvt_pk_bf16_f32 v66, v66, v67
	v_cvt_pk_bf16_f32 v67, v68, v69
	v_mad_i64_i32 v[68:69], s[4:5], v174, s35, v[112:113]
	v_lshl_add_u64 v[68:69], v[68:69], 0, v[114:115]
	v_pk_mul_f32 v[60:61], v[60:61], v[134:135] op_sel_hi:[1,0]
	v_pk_mul_f32 v[58:59], v[58:59], v[134:135] op_sel_hi:[1,0]
	v_pk_mul_f32 v[56:57], v[56:57], v[134:135] op_sel_hi:[1,0]
	v_pk_mul_f32 v[54:55], v[54:55], v[134:135] op_sel_hi:[1,0]
	v_pk_mul_f32 v[52:53], v[52:53], v[134:135] op_sel_hi:[1,0]
	global_store_dwordx4 v[68:69], v[64:67], off
	v_pk_mul_f32 v[56:57], v[60:61], v[56:57]
	v_pk_mul_f32 v[58:59], v[62:63], v[58:59]
	v_pk_mul_f32 v[64:65], v[62:63], s[44:45] op_sel_hi:[1,0]
	v_pk_mul_f32 v[66:67], v[60:61], s[44:45] op_sel_hi:[1,0]
	v_pk_mul_f32 v[60:61], v[54:55], s[44:45] op_sel_hi:[1,0]
	v_pk_mul_f32 v[62:63], v[52:53], s[44:45] op_sel_hi:[1,0]
	v_exp_f32_e32 v60, v60
	v_exp_f32_e32 v62, v62
	v_exp_f32_e32 v61, v61
	v_exp_f32_e32 v63, v63
	v_exp_f32_e32 v66, v66
	v_exp_f32_e32 v64, v64
	v_exp_f32_e32 v65, v65
	v_exp_f32_e32 v67, v67
	v_pk_add_f32 v[60:61], v[60:61], 1.0 op_sel_hi:[1,0]
	v_pk_add_f32 v[62:63], v[62:63], 1.0 op_sel_hi:[1,0]
	v_pk_add_f32 v[64:65], v[64:65], 1.0 op_sel_hi:[1,0]
	v_pk_add_f32 v[66:67], v[66:67], 1.0 op_sel_hi:[1,0]
	v_rcp_f32_e32 v62, v62
	v_rcp_f32_e32 v60, v60
	v_rcp_f32_e32 v61, v61
	v_rcp_f32_e32 v63, v63
	v_rcp_f32_e32 v66, v66
	v_rcp_f32_e32 v64, v64
	v_rcp_f32_e32 v65, v65
	v_rcp_f32_e32 v67, v67
	v_pk_mul_f32 v[50:51], v[50:51], v[134:135] op_sel_hi:[1,0]
	v_pk_mul_f32 v[48:49], v[48:49], v[134:135] op_sel_hi:[1,0]
	v_pk_mul_f32 v[50:51], v[54:55], v[50:51]
	v_pk_mul_f32 v[48:49], v[52:53], v[48:49]
	v_mul_f32_e32 v132, 0x45800000, v135
	v_pk_mul_f32 v[52:53], v[50:51], v[60:61]
	v_pk_mul_f32 v[50:51], v[48:49], v[62:63]
	v_cndmask_b32_e64 v132, v135, v132, s[6:7]
	v_pk_mul_f32 v[58:59], v[58:59], v[64:65]
	v_pk_mul_f32 v[56:57], v[56:57], v[66:67]
	v_pk_mul_f32 v[46:47], v[46:47], v[132:133] op_sel_hi:[1,0]
	v_cvt_pk_bf16_f32 v48, v56, v57
	v_cvt_pk_bf16_f32 v49, v58, v59
	v_cvt_pk_bf16_f32 v50, v50, v51
	v_cvt_pk_bf16_f32 v51, v52, v53
	v_mad_i64_i32 v[52:53], s[4:5], v172, s35, v[112:113]
	v_lshl_add_u64 v[52:53], v[52:53], 0, v[114:115]
	v_pk_mul_f32 v[44:45], v[44:45], v[132:133] op_sel_hi:[1,0]
	v_pk_mul_f32 v[42:43], v[42:43], v[132:133] op_sel_hi:[1,0]
	v_pk_mul_f32 v[40:41], v[40:41], v[132:133] op_sel_hi:[1,0]
	v_pk_mul_f32 v[38:39], v[38:39], v[132:133] op_sel_hi:[1,0]
	v_pk_mul_f32 v[36:37], v[36:37], v[132:133] op_sel_hi:[1,0]
	global_store_dwordx4 v[52:53], v[48:51], off
	v_pk_mul_f32 v[40:41], v[44:45], v[40:41]
	v_pk_mul_f32 v[42:43], v[46:47], v[42:43]
	v_pk_mul_f32 v[48:49], v[46:47], s[44:45] op_sel_hi:[1,0]
	v_pk_mul_f32 v[50:51], v[44:45], s[44:45] op_sel_hi:[1,0]
	v_pk_mul_f32 v[44:45], v[38:39], s[44:45] op_sel_hi:[1,0]
	v_pk_mul_f32 v[46:47], v[36:37], s[44:45] op_sel_hi:[1,0]
	v_exp_f32_e32 v44, v44
	v_exp_f32_e32 v46, v46
	v_exp_f32_e32 v45, v45
	v_exp_f32_e32 v47, v47
	v_exp_f32_e32 v50, v50
	v_exp_f32_e32 v48, v48
	v_exp_f32_e32 v49, v49
	v_exp_f32_e32 v51, v51
	v_pk_add_f32 v[44:45], v[44:45], 1.0 op_sel_hi:[1,0]
	v_pk_add_f32 v[46:47], v[46:47], 1.0 op_sel_hi:[1,0]
	v_pk_add_f32 v[48:49], v[48:49], 1.0 op_sel_hi:[1,0]
	v_pk_add_f32 v[50:51], v[50:51], 1.0 op_sel_hi:[1,0]
	v_rcp_f32_e32 v46, v46
	v_rcp_f32_e32 v44, v44
	v_rcp_f32_e32 v45, v45
	v_rcp_f32_e32 v47, v47
	v_rcp_f32_e32 v50, v50
	v_rcp_f32_e32 v48, v48
	v_rcp_f32_e32 v49, v49
	v_rcp_f32_e32 v51, v51
	v_pk_mul_f32 v[34:35], v[34:35], v[132:133] op_sel_hi:[1,0]
	v_pk_mul_f32 v[32:33], v[32:33], v[132:133] op_sel_hi:[1,0]
	v_pk_mul_f32 v[34:35], v[38:39], v[34:35]
	v_pk_mul_f32 v[32:33], v[36:37], v[32:33]
	v_pk_mul_f32 v[36:37], v[34:35], v[44:45]
	v_pk_mul_f32 v[34:35], v[32:33], v[46:47]
	v_pk_mul_f32 v[42:43], v[42:43], v[48:49]
	v_pk_mul_f32 v[40:41], v[40:41], v[50:51]
	v_pk_mul_f32 v[30:31], v[30:31], v[130:131] op_sel_hi:[1,0]
	v_cvt_pk_bf16_f32 v32, v40, v41
	v_cvt_pk_bf16_f32 v33, v42, v43
	v_cvt_pk_bf16_f32 v34, v34, v35
	v_cvt_pk_bf16_f32 v35, v36, v37
	v_mad_i64_i32 v[36:37], s[4:5], v170, s35, v[112:113]
	v_lshl_add_u64 v[36:37], v[36:37], 0, v[114:115]
	v_pk_mul_f32 v[28:29], v[28:29], v[130:131] op_sel_hi:[1,0]
	v_pk_mul_f32 v[26:27], v[26:27], v[130:131] op_sel_hi:[1,0]
	v_pk_mul_f32 v[24:25], v[24:25], v[130:131] op_sel_hi:[1,0]
	v_pk_mul_f32 v[22:23], v[22:23], v[130:131] op_sel_hi:[1,0]
	v_pk_mul_f32 v[20:21], v[20:21], v[130:131] op_sel_hi:[1,0]
	global_store_dwordx4 v[36:37], v[32:35], off
	v_pk_mul_f32 v[24:25], v[28:29], v[24:25]
	v_pk_mul_f32 v[26:27], v[30:31], v[26:27]
	v_pk_mul_f32 v[32:33], v[30:31], s[44:45] op_sel_hi:[1,0]
	v_pk_mul_f32 v[34:35], v[28:29], s[44:45] op_sel_hi:[1,0]
	v_pk_mul_f32 v[28:29], v[22:23], s[44:45] op_sel_hi:[1,0]
	v_pk_mul_f32 v[30:31], v[20:21], s[44:45] op_sel_hi:[1,0]
	v_exp_f32_e32 v28, v28
	v_exp_f32_e32 v30, v30
	v_exp_f32_e32 v29, v29
	v_exp_f32_e32 v31, v31
	v_exp_f32_e32 v34, v34
	v_exp_f32_e32 v32, v32
	v_exp_f32_e32 v33, v33
	v_exp_f32_e32 v35, v35
	v_pk_add_f32 v[28:29], v[28:29], 1.0 op_sel_hi:[1,0]
	v_pk_add_f32 v[30:31], v[30:31], 1.0 op_sel_hi:[1,0]
	v_pk_add_f32 v[32:33], v[32:33], 1.0 op_sel_hi:[1,0]
	v_pk_add_f32 v[34:35], v[34:35], 1.0 op_sel_hi:[1,0]
	v_rcp_f32_e32 v30, v30
	v_rcp_f32_e32 v28, v28
	v_rcp_f32_e32 v29, v29
	v_rcp_f32_e32 v31, v31
	v_rcp_f32_e32 v34, v34
	v_rcp_f32_e32 v32, v32
	v_rcp_f32_e32 v33, v33
	v_rcp_f32_e32 v35, v35
	v_pk_mul_f32 v[18:19], v[18:19], v[130:131] op_sel_hi:[1,0]
	v_pk_mul_f32 v[16:17], v[16:17], v[130:131] op_sel_hi:[1,0]
	v_pk_mul_f32 v[18:19], v[22:23], v[18:19]
	v_pk_mul_f32 v[16:17], v[20:21], v[16:17]
	v_pk_mul_f32 v[20:21], v[18:19], v[28:29]
	v_pk_mul_f32 v[18:19], v[16:17], v[30:31]
	v_pk_mul_f32 v[26:27], v[26:27], v[32:33]
	v_pk_mul_f32 v[24:25], v[24:25], v[34:35]
	v_pk_mul_f32 v[14:15], v[14:15], v[128:129] op_sel_hi:[1,0]
	v_cvt_pk_bf16_f32 v16, v24, v25
	v_cvt_pk_bf16_f32 v17, v26, v27
	v_cvt_pk_bf16_f32 v18, v18, v19
	v_cvt_pk_bf16_f32 v19, v20, v21
	v_mad_i64_i32 v[20:21], s[4:5], v168, s35, v[112:113]
	v_lshl_add_u64 v[20:21], v[20:21], 0, v[114:115]
	v_pk_mul_f32 v[12:13], v[12:13], v[128:129] op_sel_hi:[1,0]
	v_pk_mul_f32 v[10:11], v[10:11], v[128:129] op_sel_hi:[1,0]
	v_pk_mul_f32 v[8:9], v[8:9], v[128:129] op_sel_hi:[1,0]
	v_pk_mul_f32 v[6:7], v[6:7], v[128:129] op_sel_hi:[1,0]
	v_pk_mul_f32 v[4:5], v[4:5], v[128:129] op_sel_hi:[1,0]
	global_store_dwordx4 v[20:21], v[16:19], off
	v_pk_mul_f32 v[8:9], v[12:13], v[8:9]
	v_pk_mul_f32 v[10:11], v[14:15], v[10:11]
	v_pk_mul_f32 v[16:17], v[14:15], s[44:45] op_sel_hi:[1,0]
	v_pk_mul_f32 v[18:19], v[12:13], s[44:45] op_sel_hi:[1,0]
	v_pk_mul_f32 v[12:13], v[6:7], s[44:45] op_sel_hi:[1,0]
	v_pk_mul_f32 v[14:15], v[4:5], s[44:45] op_sel_hi:[1,0]
	v_exp_f32_e32 v12, v12
	v_exp_f32_e32 v14, v14
	v_exp_f32_e32 v13, v13
	v_exp_f32_e32 v15, v15
	v_exp_f32_e32 v18, v18
	v_exp_f32_e32 v16, v16
	v_exp_f32_e32 v17, v17
	v_exp_f32_e32 v19, v19
	v_pk_add_f32 v[12:13], v[12:13], 1.0 op_sel_hi:[1,0]
	v_pk_add_f32 v[14:15], v[14:15], 1.0 op_sel_hi:[1,0]
	v_pk_add_f32 v[16:17], v[16:17], 1.0 op_sel_hi:[1,0]
	v_pk_add_f32 v[18:19], v[18:19], 1.0 op_sel_hi:[1,0]
	v_rcp_f32_e32 v14, v14
	v_rcp_f32_e32 v12, v12
	v_rcp_f32_e32 v13, v13
	v_rcp_f32_e32 v15, v15
	v_rcp_f32_e32 v18, v18
	v_rcp_f32_e32 v16, v16
	v_rcp_f32_e32 v17, v17
	v_rcp_f32_e32 v19, v19
	v_pk_mul_f32 v[2:3], v[2:3], v[128:129] op_sel_hi:[1,0]
	v_pk_mul_f32 v[0:1], v[0:1], v[128:129] op_sel_hi:[1,0]
	v_pk_mul_f32 v[2:3], v[6:7], v[2:3]
	v_pk_mul_f32 v[0:1], v[4:5], v[0:1]
	v_pk_mul_f32 v[4:5], v[2:3], v[12:13]
	v_pk_mul_f32 v[2:3], v[0:1], v[14:15]
	v_pk_mul_f32 v[10:11], v[10:11], v[16:17]
	v_pk_mul_f32 v[8:9], v[8:9], v[18:19]
	s_andn2_b64 vcc, exec, s[2:3]
	v_cvt_pk_bf16_f32 v0, v8, v9
	v_cvt_pk_bf16_f32 v1, v10, v11
	v_cvt_pk_bf16_f32 v2, v2, v3
	v_cvt_pk_bf16_f32 v3, v4, v5
	v_mad_i64_i32 v[4:5], s[4:5], v166, s35, v[112:113]
	v_lshl_add_u64 v[4:5], v[4:5], 0, v[114:115]
	s_mov_b32 s4, s16
	s_mov_b32 s5, s12
	s_mov_b64 s[6:7], s[18:19]
	global_store_dwordx4 v[4:5], v[0:3], off
	s_cbranch_vccnz .LBB0_1429
	s_waitcnt vmcnt(0)
	s_cmpk_gt_u32 s24, 0xff
	s_cbranch_scc1 .LBB0_1440
	s_barrier
